# S5 GEMMs in P2: the 40 per-block s_setprio flips removed (last remaining per-segment priority toggles)
# baseline (speedup 1.0000x reference)
; template <class Epi, class Sched, bool ALIGN_EPI, bool SP2>
; __device__ __forceinline__ void gemm_phase(LAS unsigned char* lds, const Gemm g, const Sched& S, const Epi& E, int tid_in) {
;     ...
;     if constexpr (SP2) {
;         PG8_STAGE(PG8_SB(0, 0), cB, voffB); PG8_STAGE(PG8_SB(0, 1), cB + hstepB, voffB); PG8_STAGE(PG8_SA(0, 0), cA, voffA); PG8_STAGE(PG8_SA(0, 1), cA + hstepA, voffA);
;         if (wr == 1) PG8_BAR;
;         PG8_WAIT_V(2); PG8_BAR;
;         PG8_STAGE(PG8_SB(1, 0), cB + kstep, voffB); PG8_STAGE(PG8_SA(1, 0), cA + kstep, voffA); PG8_STAGE(PG8_SB(1, 1), cB + hstepB + kstep, voffB);
;         PG8_WAIT_V(6); PG8_BAR;
;     } else {
;         PG8_STAGE(PG8_SB(0, 0), cB, voffB); PG8_STAGE(PG8_SA(0, 0), cA, voffA); PG8_STAGE(PG8_SB(0, 1), cB + hstepB, voffB); PG8_STAGE(PG8_SA(0, 1), cA + hstepA, voffA);
;         if (wr == 1) PG8_BAR;
;         PG8_WAIT_V(4); PG8_BAR;
;         PG8_STAGE(PG8_SB(1, 0), cB + kstep, voffB); PG8_STAGE(PG8_SA(1, 0), cA + kstep, voffA); PG8_STAGE(PG8_SB(1, 1), cB + hstepB + kstep, voffB);
;         PG8_WAIT_V(6); PG8_BAR;
;     }
;     for (;;) {
;         const bool has_next = S.next(ui + 1, nxt);
;         const unsigned nA = has_next ? (unsigned)nxt.pm * tstepA : cA, nB = has_next ? (unsigned)nxt.pn * tstepB : cB;
;         for (int t = 0; t < nt; t += 2) {
;             const bool last = (t == nt - 2);
;             const unsigned a1 = cA + (unsigned)(t + 1) * kstep;
;             const unsigned a2 = last ? nA : cA + (unsigned)(t + 2) * kstep, b2 = last ? nB : cB + (unsigned)(t + 2) * kstep;
;             const unsigned a3 = a2 + kstep, b3 = b2 + kstep;
;             if constexpr (Epi::MIDK) { if (t == g.kmid) E.midk(acc, wr, fr); }
;             if constexpr (SP2) {
;             PG8_LDB(B0, 0, 0); PG8_LDB(B1, 0, 1); PG8_SCHED; PG8_LDA(At, 0, 0); PG8_STAGE(PG8_SA(1, 1), a1 + hstepA, voffA);
;             PG8_WAIT_V(8); PG8_WAIT_L(0); PG8_BAR; PG8_MMA(0, 0, At, B0); PG8_MMA(0, 1, At, B1); PG8_BAR; PG8_SCHED;
;             PG8_LDA(At, 0, 1); PG8_STAGE(PG8_SB(0, 0), b2, voffB); PG8_STAGE(PG8_SB(0, 1), b2 + hstepB, voffB); PG8_STAGE(PG8_SA(0, 0), a2, voffA);
;             PG8_WAIT_V(8); PG8_WAIT_L(0); PG8_BAR; PG8_MMA(1, 0, At, B0); PG8_MMA(1, 1, At, B1); PG8_BAR; PG8_SCHED;
;             PG8_LDB(B0, 1, 0); PG8_LDB(B1, 1, 1); PG8_SCHED; PG8_LDA(At, 1, 0); PG8_STAGE(PG8_SA(0, 1), a2 + hstepA, voffA);
.LBB0_503:
	s_add_i32 s25, 0, 0x18000
	s_add_i32 s57, s25, s12
	s_mov_b32 m0, s57
	s_movk_i32 s72, 0x80
	s_add_i32 s67, s57, 0x2000
	s_waitcnt vmcnt(2)
	s_barrier
	buffer_load_dwordx4 v34, s[84:87], s72 offen lds
	s_mov_b32 m0, s67
	s_add_i32 s66, s31, 0x8000
	buffer_load_dwordx4 v36, s[84:87], s72 offen lds
	s_or_b32 s12, s13, 0x80
	s_mov_b32 s36, s46
	s_mov_b32 s38, s86
	s_mov_b32 s39, s87
	s_mov_b32 m0, s66
	s_add_i32 s68, s31, 0xa000
	buffer_load_dwordx4 v0, s[36:39], s12 offen lds
	s_mov_b32 m0, s68
	s_add_i32 s69, s31, 0x1c000
	buffer_load_dwordx4 v35, s[36:39], s12 offen lds
	s_mov_b32 m0, s69
	s_mov_b32 s73, 0x10080
	s_add_i32 s70, s31, 0x1e000
	buffer_load_dwordx4 v34, s[84:87], s73 offen lds
	s_mov_b32 m0, s70
	v_bfe_u32 v66, v2, 4, 2
	buffer_load_dwordx4 v36, s[84:87], s73 offen lds
	s_and_b32 s4, s4, 3
	v_and_b32_e32 v67, 15, v2
	v_lshlrev_b32_e32 v3, 4, v66
	v_lshlrev_b32_e32 v2, 2, v2
	v_lshl_or_b32 v3, v67, 6, v3
	v_and_b32_e32 v2, 32, v2
	s_lshl_b32 s15, s4, 12
	s_lshl_b32 s14, s5, 13
	v_bitop3_b32 v4, v3, s15, v2 bitop3:0xde
	v_bitop3_b32 v2, v3, s14, v2 bitop3:0xde
	v_add_u32_e32 v3, 0, v4
	v_add_u32_e32 v37, 0x10000, v3
	s_waitcnt vmcnt(6)
	s_barrier
	v_add_u32_e32 v112, 0, v2
	v_add_u32_e32 v113, s25, v4
	ds_read_b128 v[2:5], v37
	ds_read_b128 v[6:9], v37 offset:1024
	ds_read_b128 v[10:13], v37 offset:2048
	ds_read_b128 v[14:17], v37 offset:3072
	s_add_i32 s27, s13, 0x18080
	s_or_b32 s19, s13, 0x100
	s_or_b32 s16, s13, 0x180
	s_add_i32 s71, s31, 0xc000
	s_mov_b32 m0, s71
	s_add_i32 s14, s31, 0xe000
	ds_read_b128 v[18:21], v112
	ds_read_b128 v[22:25], v112 offset:1024
	ds_read_b128 v[26:29], v112 offset:2048
	s_waitcnt vmcnt(14)
	ds_read_b128 v[30:33], v112 offset:3072
	ds_read_b128 v[38:41], v112 offset:4096
	ds_read_b128 v[42:45], v112 offset:5120
	ds_read_b128 v[46:49], v112 offset:6144
	ds_read_b128 v[50:53], v112 offset:7168
	buffer_load_dwordx4 v0, s[36:39], s27 offen lds
	s_mov_b32 m0, s14
	s_nop 0
	buffer_load_dwordx4 v35, s[36:39], s27 offen lds
	s_waitcnt vmcnt(8)
	s_waitcnt lgkmcnt(0)
	s_barrier
	s_waitcnt lgkmcnt(7)
	v_mfma_f32_16x16x32_bf16 v[54:57], v[2:5], v[18:21], 0
	v_mfma_f32_16x16x32_bf16 v[18:21], v[10:13], v[18:21], 0
	s_waitcnt lgkmcnt(6)
	v_mfma_f32_16x16x32_bf16 v[54:57], v[6:9], v[22:25], v[54:57]
	v_mfma_f32_16x16x32_bf16 v[18:21], v[14:17], v[22:25], v[18:21]
	s_waitcnt lgkmcnt(5)
	v_mfma_f32_16x16x32_bf16 v[22:25], v[2:5], v[26:29], 0
	v_mfma_f32_16x16x32_bf16 v[26:29], v[10:13], v[26:29], 0
	s_waitcnt lgkmcnt(4)
	v_mfma_f32_16x16x32_bf16 v[22:25], v[6:9], v[30:33], v[22:25]
	v_mfma_f32_16x16x32_bf16 v[26:29], v[14:17], v[30:33], v[26:29]
	s_waitcnt lgkmcnt(3)
	v_mfma_f32_16x16x32_bf16 v[30:33], v[2:5], v[38:41], 0
	v_mfma_f32_16x16x32_bf16 v[38:41], v[10:13], v[38:41], 0
	s_waitcnt lgkmcnt(2)
	v_mfma_f32_16x16x32_bf16 v[30:33], v[6:9], v[42:45], v[30:33]
	v_mfma_f32_16x16x32_bf16 v[38:41], v[14:17], v[42:45], v[38:41]
	s_waitcnt lgkmcnt(1)
	v_mfma_f32_16x16x32_bf16 v[42:45], v[2:5], v[46:49], 0
	v_mfma_f32_16x16x32_bf16 v[46:49], v[10:13], v[46:49], 0
	s_waitcnt lgkmcnt(0)
	v_mfma_f32_16x16x32_bf16 v[42:45], v[6:9], v[50:53], v[42:45]
	v_mfma_f32_16x16x32_bf16 v[46:49], v[14:17], v[50:53], v[46:49]
	s_barrier
	s_mov_b32 m0, s34
	s_movk_i32 s15, 0x100
	ds_read_b128 v[50:53], v112 offset:16384
	ds_read_b128 v[58:61], v112 offset:17408
	ds_read_b128 v[62:65], v112 offset:18432
	ds_read_b128 v[68:71], v112 offset:19456
	ds_read_b128 v[72:75], v112 offset:20480
	ds_read_b128 v[76:79], v112 offset:21504
	ds_read_b128 v[80:83], v112 offset:22528
	ds_read_b128 v[84:87], v112 offset:23552
	buffer_load_dwordx4 v34, s[84:87], s15 offen lds
	s_mov_b32 m0, s50
	s_nop 0
	buffer_load_dwordx4 v36, s[84:87], s15 offen lds
	s_mov_b32 m0, s52
	s_mov_b32 s15, 0x10100
	buffer_load_dwordx4 v34, s[84:87], s15 offen lds
	s_mov_b32 m0, s56
	s_nop 0
	buffer_load_dwordx4 v36, s[84:87], s15 offen lds
	s_mov_b32 m0, s31
	s_nop 0
	buffer_load_dwordx4 v0, s[36:39], s19 offen lds
	s_mov_b32 m0, s65
	s_nop 0
	buffer_load_dwordx4 v35, s[36:39], s19 offen lds
	s_waitcnt vmcnt(8)
	s_waitcnt lgkmcnt(0)
	s_barrier
	s_waitcnt lgkmcnt(7)
	v_mfma_f32_16x16x32_bf16 v[88:91], v[2:5], v[50:53], 0
	v_mfma_f32_16x16x32_bf16 v[50:53], v[10:13], v[50:53], 0
	s_waitcnt lgkmcnt(6)
	v_mfma_f32_16x16x32_bf16 v[88:91], v[6:9], v[58:61], v[88:91]
	v_mfma_f32_16x16x32_bf16 v[50:53], v[14:17], v[58:61], v[50:53]
	s_waitcnt lgkmcnt(5)
	v_mfma_f32_16x16x32_bf16 v[58:61], v[2:5], v[62:65], 0
	v_mfma_f32_16x16x32_bf16 v[62:65], v[10:13], v[62:65], 0
	s_waitcnt lgkmcnt(4)
	v_mfma_f32_16x16x32_bf16 v[58:61], v[6:9], v[68:71], v[58:61]
	v_mfma_f32_16x16x32_bf16 v[62:65], v[14:17], v[68:71], v[62:65]
	s_waitcnt lgkmcnt(3)
	v_mfma_f32_16x16x32_bf16 v[68:71], v[2:5], v[72:75], 0
	s_waitcnt lgkmcnt(1)
	v_mfma_f32_16x16x32_bf16 v[2:5], v[2:5], v[80:83], 0
	v_mfma_f32_16x16x32_bf16 v[68:71], v[6:9], v[76:79], v[68:71]
	s_waitcnt lgkmcnt(0)
	v_mfma_f32_16x16x32_bf16 v[2:5], v[6:9], v[84:87], v[2:5]
	v_mfma_f32_16x16x32_bf16 v[6:9], v[10:13], v[80:83], 0
	v_mfma_f32_16x16x32_bf16 v[72:75], v[10:13], v[72:75], 0
	v_mfma_f32_16x16x32_bf16 v[6:9], v[14:17], v[84:87], v[6:9]
	v_mfma_f32_16x16x32_bf16 v[72:75], v[14:17], v[76:79], v[72:75]
	s_barrier
	ds_read_b128 v[10:13], v113
	ds_read_b128 v[14:17], v113 offset:1024
	ds_read_b128 v[76:79], v113 offset:2048
	ds_read_b128 v[80:83], v113 offset:3072
	s_add_i32 s29, s13, 0x18100
	s_mov_b32 m0, s11
	ds_read_b128 v[84:87], v112 offset:32768
	ds_read_b128 v[92:95], v112 offset:33792
	ds_read_b128 v[96:99], v112 offset:34816
	ds_read_b128 v[100:103], v112 offset:35840
	ds_read_b128 v[104:107], v112 offset:36864
	ds_read_b128 v[108:111], v112 offset:37888
	ds_read_b128 v[116:119], v112 offset:38912
	ds_read_b128 v[120:123], v112 offset:39936
	buffer_load_dwordx4 v0, s[36:39], s29 offen lds
	s_mov_b32 m0, s30
	s_nop 0
	buffer_load_dwordx4 v35, s[36:39], s29 offen lds
	s_waitcnt vmcnt(8)
	s_waitcnt lgkmcnt(0)
	s_barrier
; #define PG8_STAGE(bufoff, goff, voff) do { _Pragma("unroll") for (int _i = 0; _i < 2; ++_i) \
;         __builtin_amdgcn_raw_ptr_buffer_load_lds(R_##voff, (LAS void*)(lds + (bufoff) + ldsw + _i * 8192), 16, (int)(voff)[_i], (int)(goff), 0, 0); } while (0)
; #define PG8_WAIT_V(n) asm volatile("s_waitcnt vmcnt(" #n ")" ::: "memory")
; #define PG8_WAIT_L(n) asm volatile("s_waitcnt lgkmcnt(" #n ")" ::: "memory")
; #define PG8_BAR __builtin_amdgcn_s_barrier()
; #define PG8_SCHED __builtin_amdgcn_sched_barrier(0)
; template <class Epi, class Sched, bool ALIGN_EPI, bool SP2>
; __device__ __forceinline__ void gemm_phase(LAS unsigned char* lds, const Gemm g, const Sched& S, const Epi& E, int tid_in) {
;     ...
;             PG8_LDB(B0, 0, 0); PG8_LDB(B1, 0, 1); PG8_SCHED; PG8_LDA(At, 0, 0); PG8_STAGE(PG8_SA(1, 1), a1 + hstepA, voffA);
;             PG8_WAIT_V(8); PG8_WAIT_L(0); PG8_BAR; PG8_MMA(0, 0, At, B0); PG8_MMA(0, 1, At, B1); PG8_BAR; PG8_SCHED;
;             PG8_LDA(At, 0, 1); PG8_STAGE(PG8_SB(0, 0), b2, voffB); PG8_STAGE(PG8_SB(0, 1), b2 + hstepB, voffB); PG8_STAGE(PG8_SA(0, 0), a2, voffA);
;             PG8_WAIT_V(8); PG8_WAIT_L(0); PG8_BAR; PG8_MMA(1, 0, At, B0); PG8_MMA(1, 1, At, B1); PG8_BAR; PG8_SCHED;
;             PG8_LDB(B0, 1, 0); PG8_LDB(B1, 1, 1); PG8_SCHED; PG8_LDA(At, 1, 0); PG8_STAGE(PG8_SA(0, 1), a2 + hstepA, voffA);
;             PG8_WAIT_V(8); PG8_WAIT_L(0); PG8_BAR; PG8_MMA(0, 0, At, B0); PG8_MMA(0, 1, At, B1); PG8_BAR; PG8_SCHED;
;             PG8_LDA(At, 1, 1); PG8_STAGE(PG8_SB(1, 0), b3, voffB); PG8_STAGE(PG8_SB(1, 1), b3 + hstepB, voffB); PG8_STAGE(PG8_SA(1, 0), a3, voffA);
;             PG8_WAIT_V(8); PG8_WAIT_L(0); PG8_BAR; PG8_MMA(1, 0, At, B0); PG8_MMA(1, 1, At, B1); PG8_BAR; PG8_SCHED;
	s_waitcnt lgkmcnt(7)
	v_mfma_f32_16x16x32_bf16 v[54:57], v[10:13], v[84:87], v[54:57]
	v_mfma_f32_16x16x32_bf16 v[18:21], v[76:79], v[84:87], v[18:21]
	s_waitcnt lgkmcnt(5)
	v_mfma_f32_16x16x32_bf16 v[22:25], v[10:13], v[96:99], v[22:25]
	v_mfma_f32_16x16x32_bf16 v[26:29], v[76:79], v[96:99], v[26:29]
	s_waitcnt lgkmcnt(3)
	v_mfma_f32_16x16x32_bf16 v[30:33], v[10:13], v[104:107], v[30:33]
	v_mfma_f32_16x16x32_bf16 v[38:41], v[76:79], v[104:107], v[38:41]
	s_waitcnt lgkmcnt(1)
	v_mfma_f32_16x16x32_bf16 v[42:45], v[10:13], v[116:119], v[42:45]
	v_mfma_f32_16x16x32_bf16 v[46:49], v[76:79], v[116:119], v[46:49]
	v_mfma_f32_16x16x32_bf16 v[54:57], v[14:17], v[92:95], v[54:57]
	v_mfma_f32_16x16x32_bf16 v[18:21], v[80:83], v[92:95], v[18:21]
	v_mfma_f32_16x16x32_bf16 v[22:25], v[14:17], v[100:103], v[22:25]
	v_mfma_f32_16x16x32_bf16 v[26:29], v[80:83], v[100:103], v[26:29]
	v_mfma_f32_16x16x32_bf16 v[30:33], v[14:17], v[108:111], v[30:33]
	v_mfma_f32_16x16x32_bf16 v[38:41], v[80:83], v[108:111], v[38:41]
	s_waitcnt lgkmcnt(0)
	v_mfma_f32_16x16x32_bf16 v[42:45], v[14:17], v[120:123], v[42:45]
	v_mfma_f32_16x16x32_bf16 v[46:49], v[80:83], v[120:123], v[46:49]
	s_barrier
	s_mov_b32 m0, s57
	s_movk_i32 s15, 0x180
	ds_read_b128 v[84:87], v112 offset:49152
	ds_read_b128 v[92:95], v112 offset:50176
	ds_read_b128 v[96:99], v112 offset:51200
	ds_read_b128 v[100:103], v112 offset:52224
	ds_read_b128 v[104:107], v112 offset:53248
	ds_read_b128 v[108:111], v112 offset:54272
	ds_read_b128 v[116:119], v112 offset:55296
	ds_read_b128 v[120:123], v112 offset:56320
	buffer_load_dwordx4 v34, s[84:87], s15 offen lds
	s_mov_b32 m0, s67
	s_nop 0
	buffer_load_dwordx4 v36, s[84:87], s15 offen lds
	s_mov_b32 m0, s69
	s_mov_b32 s15, 0x10180
	buffer_load_dwordx4 v34, s[84:87], s15 offen lds
	s_mov_b32 m0, s70
	s_nop 0
	buffer_load_dwordx4 v36, s[84:87], s15 offen lds
	s_mov_b32 m0, s66
	s_nop 0
	buffer_load_dwordx4 v0, s[36:39], s16 offen lds
	s_mov_b32 m0, s68
	s_nop 0
	buffer_load_dwordx4 v35, s[36:39], s16 offen lds
	s_waitcnt vmcnt(8)
	s_waitcnt lgkmcnt(0)
	s_barrier
	s_waitcnt lgkmcnt(7)
	v_mfma_f32_16x16x32_bf16 v[50:53], v[76:79], v[84:87], v[50:53]
	s_waitcnt lgkmcnt(5)
	v_mfma_f32_16x16x32_bf16 v[58:61], v[10:13], v[96:99], v[58:61]
	v_mfma_f32_16x16x32_bf16 v[62:65], v[76:79], v[96:99], v[62:65]
	s_waitcnt lgkmcnt(1)
	v_mfma_f32_16x16x32_bf16 v[2:5], v[10:13], v[116:119], v[2:5]
	v_mfma_f32_16x16x32_bf16 v[6:9], v[76:79], v[116:119], v[6:9]
	v_mfma_f32_16x16x32_bf16 v[88:91], v[10:13], v[84:87], v[88:91]
	v_mfma_f32_16x16x32_bf16 v[50:53], v[80:83], v[92:95], v[50:53]
	v_mfma_f32_16x16x32_bf16 v[58:61], v[14:17], v[100:103], v[58:61]
	v_mfma_f32_16x16x32_bf16 v[62:65], v[80:83], v[100:103], v[62:65]
	v_mfma_f32_16x16x32_bf16 v[68:71], v[10:13], v[104:107], v[68:71]
	v_mfma_f32_16x16x32_bf16 v[72:75], v[76:79], v[104:107], v[72:75]
	s_waitcnt lgkmcnt(0)
	v_mfma_f32_16x16x32_bf16 v[2:5], v[14:17], v[120:123], v[2:5]
	v_mfma_f32_16x16x32_bf16 v[6:9], v[80:83], v[120:123], v[6:9]
	v_mfma_f32_16x16x32_bf16 v[88:91], v[14:17], v[92:95], v[88:91]
	v_mfma_f32_16x16x32_bf16 v[68:71], v[14:17], v[108:111], v[68:71]
	v_mfma_f32_16x16x32_bf16 v[72:75], v[80:83], v[108:111], v[72:75]
	s_barrier
	ds_read_b128 v[10:13], v37
	ds_read_b128 v[14:17], v37 offset:1024
	ds_read_b128 v[76:79], v37 offset:2048
	ds_read_b128 v[80:83], v37 offset:3072
	s_add_i32 s20, s13, 0x18180
	s_mov_b32 m0, s71
	ds_read_b128 v[84:87], v112
	ds_read_b128 v[92:95], v112 offset:1024
	ds_read_b128 v[96:99], v112 offset:2048
	ds_read_b128 v[100:103], v112 offset:3072
	ds_read_b128 v[104:107], v112 offset:4096
	ds_read_b128 v[108:111], v112 offset:5120
	ds_read_b128 v[116:119], v112 offset:6144
	ds_read_b128 v[120:123], v112 offset:7168
	buffer_load_dwordx4 v0, s[36:39], s20 offen lds
	s_mov_b32 m0, s14
	s_nop 0
	buffer_load_dwordx4 v35, s[36:39], s20 offen lds
	s_waitcnt vmcnt(8)
	s_waitcnt lgkmcnt(0)
	s_barrier
	s_waitcnt lgkmcnt(7)
	v_mfma_f32_16x16x32_bf16 v[54:57], v[10:13], v[84:87], v[54:57]
	v_mfma_f32_16x16x32_bf16 v[18:21], v[76:79], v[84:87], v[18:21]
	s_waitcnt lgkmcnt(5)
	v_mfma_f32_16x16x32_bf16 v[22:25], v[10:13], v[96:99], v[22:25]
	v_mfma_f32_16x16x32_bf16 v[26:29], v[76:79], v[96:99], v[26:29]
	s_waitcnt lgkmcnt(3)
	v_mfma_f32_16x16x32_bf16 v[30:33], v[10:13], v[104:107], v[30:33]
	v_mfma_f32_16x16x32_bf16 v[38:41], v[76:79], v[104:107], v[38:41]
	s_waitcnt lgkmcnt(1)
	v_mfma_f32_16x16x32_bf16 v[42:45], v[10:13], v[116:119], v[42:45]
	v_mfma_f32_16x16x32_bf16 v[46:49], v[76:79], v[116:119], v[46:49]
	v_mfma_f32_16x16x32_bf16 v[54:57], v[14:17], v[92:95], v[54:57]
	v_mfma_f32_16x16x32_bf16 v[18:21], v[80:83], v[92:95], v[18:21]
	v_mfma_f32_16x16x32_bf16 v[22:25], v[14:17], v[100:103], v[22:25]
	v_mfma_f32_16x16x32_bf16 v[26:29], v[80:83], v[100:103], v[26:29]
	v_mfma_f32_16x16x32_bf16 v[30:33], v[14:17], v[108:111], v[30:33]
	v_mfma_f32_16x16x32_bf16 v[38:41], v[80:83], v[108:111], v[38:41]
	s_waitcnt lgkmcnt(0)
	v_mfma_f32_16x16x32_bf16 v[42:45], v[14:17], v[120:123], v[42:45]
	v_mfma_f32_16x16x32_bf16 v[46:49], v[80:83], v[120:123], v[46:49]
	s_barrier
	s_mov_b32 m0, s34
	ds_read_b128 v[84:87], v112 offset:16384
	ds_read_b128 v[92:95], v112 offset:17408
	ds_read_b128 v[96:99], v112 offset:18432
	ds_read_b128 v[100:103], v112 offset:19456
	ds_read_b128 v[104:107], v112 offset:20480
	ds_read_b128 v[108:111], v112 offset:21504
	ds_read_b128 v[116:119], v112 offset:22528
	ds_read_b128 v[120:123], v112 offset:23552
	buffer_load_dwordx4 v34, s[84:87], 0 offen lds
	s_mov_b32 m0, s50
	s_mov_b32 s14, 0x10000
	buffer_load_dwordx4 v36, s[84:87], 0 offen lds
	s_mov_b32 m0, s52
	s_nop 0
	buffer_load_dwordx4 v34, s[84:87], s14 offen lds
	s_mov_b32 m0, s56
	s_nop 0
	buffer_load_dwordx4 v36, s[84:87], s14 offen lds
	s_mov_b32 m0, s31
	s_nop 0
	buffer_load_dwordx4 v0, s[36:39], s13 offen lds
	s_mov_b32 m0, s65
	s_nop 0
	buffer_load_dwordx4 v35, s[36:39], s13 offen lds
	s_waitcnt vmcnt(8)
	s_waitcnt lgkmcnt(0)
	s_barrier
; #define PG8_STAGE(bufoff, goff, voff) do { _Pragma("unroll") for (int _i = 0; _i < 2; ++_i) \
;         __builtin_amdgcn_raw_ptr_buffer_load_lds(R_##voff, (LAS void*)(lds + (bufoff) + ldsw + _i * 8192), 16, (int)(voff)[_i], (int)(goff), 0, 0); } while (0)
; #define PG8_WAIT_V(n) asm volatile("s_waitcnt vmcnt(" #n ")" ::: "memory")
; #define PG8_WAIT_L(n) asm volatile("s_waitcnt lgkmcnt(" #n ")" ::: "memory")
; #define PG8_BAR __builtin_amdgcn_s_barrier()
; #define PG8_SCHED __builtin_amdgcn_sched_barrier(0)
; template <class Epi, class Sched, bool ALIGN_EPI, bool SP2>
; __device__ __forceinline__ void gemm_phase(LAS unsigned char* lds, const Gemm g, const Sched& S, const Epi& E, int tid_in) {
;     ...
;             PG8_LDA(At, 0, 1); PG8_STAGE(PG8_SB(0, 0), b2, voffB); PG8_STAGE(PG8_SB(0, 1), b2 + hstepB, voffB); PG8_STAGE(PG8_SA(0, 0), a2, voffA);
;             PG8_WAIT_V(8); PG8_WAIT_L(0); PG8_BAR; PG8_MMA(1, 0, At, B0); PG8_MMA(1, 1, At, B1); PG8_BAR; PG8_SCHED;
;             PG8_LDB(B0, 1, 0); PG8_LDB(B1, 1, 1); PG8_SCHED; PG8_LDA(At, 1, 0); PG8_STAGE(PG8_SA(0, 1), a2 + hstepA, voffA);
;             PG8_WAIT_V(8); PG8_WAIT_L(0); PG8_BAR; PG8_MMA(0, 0, At, B0); PG8_MMA(0, 1, At, B1); PG8_BAR; PG8_SCHED;
;             PG8_LDA(At, 1, 1); PG8_STAGE(PG8_SB(1, 0), b3, voffB); PG8_STAGE(PG8_SB(1, 1), b3 + hstepB, voffB); PG8_STAGE(PG8_SA(1, 0), a3, voffA);
;             PG8_WAIT_V(8); PG8_WAIT_L(0); PG8_BAR; PG8_MMA(1, 0, At, B0); PG8_MMA(1, 1, At, B1); PG8_BAR; PG8_SCHED;
;     ...
;     PG8_WAIT_V(0);
;     if constexpr (!ALIGN_EPI) { if (wr == 0) PG8_BAR; }
;     PG8_BAR;
	s_waitcnt lgkmcnt(7)
	v_mfma_f32_16x16x32_bf16 v[50:53], v[76:79], v[84:87], v[50:53]
	s_waitcnt lgkmcnt(5)
	v_mfma_f32_16x16x32_bf16 v[58:61], v[10:13], v[96:99], v[58:61]
	v_mfma_f32_16x16x32_bf16 v[62:65], v[76:79], v[96:99], v[62:65]
	s_waitcnt lgkmcnt(1)
	v_mfma_f32_16x16x32_bf16 v[2:5], v[10:13], v[116:119], v[2:5]
	v_mfma_f32_16x16x32_bf16 v[88:91], v[10:13], v[84:87], v[88:91]
	v_mfma_f32_16x16x32_bf16 v[50:53], v[80:83], v[92:95], v[50:53]
	v_mfma_f32_16x16x32_bf16 v[58:61], v[14:17], v[100:103], v[58:61]
	v_mfma_f32_16x16x32_bf16 v[62:65], v[80:83], v[100:103], v[62:65]
	v_mfma_f32_16x16x32_bf16 v[68:71], v[10:13], v[104:107], v[68:71]
	v_mfma_f32_16x16x32_bf16 v[72:75], v[76:79], v[104:107], v[72:75]
	s_waitcnt lgkmcnt(0)
	v_mfma_f32_16x16x32_bf16 v[84:87], v[14:17], v[120:123], v[2:5]
	v_mfma_f32_16x16x32_bf16 v[2:5], v[76:79], v[116:119], v[6:9]
	v_mfma_f32_16x16x32_bf16 v[88:91], v[14:17], v[92:95], v[88:91]
	v_mfma_f32_16x16x32_bf16 v[68:71], v[14:17], v[108:111], v[68:71]
	v_mfma_f32_16x16x32_bf16 v[72:75], v[80:83], v[108:111], v[72:75]
	v_mfma_f32_16x16x32_bf16 v[76:79], v[80:83], v[120:123], v[2:5]
	s_barrier
	ds_read_b128 v[80:83], v113
	ds_read_b128 v[92:95], v113 offset:1024
	ds_read_b128 v[96:99], v113 offset:2048
	ds_read_b128 v[100:103], v113 offset:3072
	s_mov_b32 m0, s11
	ds_read_b128 v[6:9], v112 offset:32768
	ds_read_b128 v[10:13], v112 offset:33792
	ds_read_b128 v[14:17], v112 offset:34816
	ds_read_b128 v[104:107], v112 offset:35840
	ds_read_b128 v[108:111], v112 offset:36864
	ds_read_b128 v[116:119], v112 offset:37888
	ds_read_b128 v[120:123], v112 offset:38912
	ds_read_b128 v[124:127], v112 offset:39936
	buffer_load_dwordx4 v0, s[36:39], s10 offen lds
	s_mov_b32 m0, s30
	s_nop 0
	buffer_load_dwordx4 v35, s[36:39], s10 offen lds
	s_waitcnt vmcnt(8)
	s_waitcnt lgkmcnt(0)
	s_barrier
	s_waitcnt lgkmcnt(7)
	v_mfma_f32_16x16x32_bf16 v[2:5], v[80:83], v[6:9], v[54:57]
	v_mfma_f32_16x16x32_bf16 v[6:9], v[96:99], v[6:9], v[18:21]
	s_waitcnt lgkmcnt(6)
	v_mfma_f32_16x16x32_bf16 v[2:5], v[92:95], v[10:13], v[2:5]
	v_mfma_f32_16x16x32_bf16 v[6:9], v[100:103], v[10:13], v[6:9]
	s_waitcnt lgkmcnt(5)
	v_mfma_f32_16x16x32_bf16 v[10:13], v[80:83], v[14:17], v[22:25]
	v_mfma_f32_16x16x32_bf16 v[14:17], v[96:99], v[14:17], v[26:29]
	s_waitcnt lgkmcnt(3)
	v_mfma_f32_16x16x32_bf16 v[18:21], v[80:83], v[108:111], v[30:33]
	v_mfma_f32_16x16x32_bf16 v[22:25], v[96:99], v[108:111], v[38:41]
	s_waitcnt lgkmcnt(1)
	v_mfma_f32_16x16x32_bf16 v[26:29], v[80:83], v[120:123], v[42:45]
	v_mfma_f32_16x16x32_bf16 v[30:33], v[96:99], v[120:123], v[46:49]
	v_mfma_f32_16x16x32_bf16 v[10:13], v[92:95], v[104:107], v[10:13]
	v_mfma_f32_16x16x32_bf16 v[14:17], v[100:103], v[104:107], v[14:17]
	v_mfma_f32_16x16x32_bf16 v[18:21], v[92:95], v[116:119], v[18:21]
	v_mfma_f32_16x16x32_bf16 v[22:25], v[100:103], v[116:119], v[22:25]
	s_waitcnt lgkmcnt(0)
	v_mfma_f32_16x16x32_bf16 v[26:29], v[92:95], v[124:127], v[26:29]
	v_mfma_f32_16x16x32_bf16 v[30:33], v[100:103], v[124:127], v[30:33]
	s_barrier
	s_mov_b32 m0, s57
	ds_read_b128 v[38:41], v112 offset:49152
	ds_read_b128 v[42:45], v112 offset:50176
	ds_read_b128 v[46:49], v112 offset:51200
	ds_read_b128 v[54:57], v112 offset:52224
	ds_read_b128 v[104:107], v112 offset:53248
	ds_read_b128 v[108:111], v112 offset:54272
	ds_read_b128 v[116:119], v112 offset:55296
	ds_read_b128 v[120:123], v112 offset:56320
	buffer_load_dwordx4 v34, s[84:87], s72 offen lds
	s_mov_b32 m0, s67
	s_movk_i32 s11, 0x80
	buffer_load_dwordx4 v36, s[84:87], s72 offen lds
	s_mov_b32 m0, s69
	s_nop 0
	buffer_load_dwordx4 v34, s[84:87], s73 offen lds
	s_mov_b32 m0, s70
	s_nop 0
	buffer_load_dwordx4 v36, s[84:87], s73 offen lds
	s_mov_b32 m0, s66
	s_nop 0
	buffer_load_dwordx4 v0, s[36:39], s12 offen lds
	s_mov_b32 m0, s68
	s_nop 0
	buffer_load_dwordx4 v35, s[36:39], s12 offen lds
	s_waitcnt vmcnt(8)
	s_waitcnt lgkmcnt(0)
	s_barrier
	s_waitcnt lgkmcnt(7)
	v_mfma_f32_16x16x32_bf16 v[34:37], v[80:83], v[38:41], v[88:91]
	v_mfma_f32_16x16x32_bf16 v[38:41], v[96:99], v[38:41], v[50:53]
	s_waitcnt lgkmcnt(6)
	v_mfma_f32_16x16x32_bf16 v[34:37], v[92:95], v[42:45], v[34:37]
	v_mfma_f32_16x16x32_bf16 v[38:41], v[100:103], v[42:45], v[38:41]
	s_waitcnt lgkmcnt(5)
	v_mfma_f32_16x16x32_bf16 v[42:45], v[80:83], v[46:49], v[58:61]
	v_mfma_f32_16x16x32_bf16 v[46:49], v[96:99], v[46:49], v[62:65]
	s_waitcnt lgkmcnt(4)
	v_mfma_f32_16x16x32_bf16 v[42:45], v[92:95], v[54:57], v[42:45]
	v_mfma_f32_16x16x32_bf16 v[46:49], v[100:103], v[54:57], v[46:49]
	s_waitcnt lgkmcnt(3)
	v_mfma_f32_16x16x32_bf16 v[50:53], v[80:83], v[104:107], v[68:71]
	v_mfma_f32_16x16x32_bf16 v[54:57], v[96:99], v[104:107], v[72:75]
	s_waitcnt lgkmcnt(1)
	v_mfma_f32_16x16x32_bf16 v[58:61], v[80:83], v[116:119], v[84:87]
	v_mfma_f32_16x16x32_bf16 v[62:65], v[96:99], v[116:119], v[76:79]
	v_mfma_f32_16x16x32_bf16 v[50:53], v[92:95], v[108:111], v[50:53]
	v_mfma_f32_16x16x32_bf16 v[54:57], v[100:103], v[108:111], v[54:57]
	s_waitcnt lgkmcnt(0)
	v_mfma_f32_16x16x32_bf16 v[58:61], v[92:95], v[120:123], v[58:61]
	v_mfma_f32_16x16x32_bf16 v[62:65], v[100:103], v[120:123], v[62:65]
	s_barrier
	s_waitcnt vmcnt(0)
	s_cmpk_gt_u32 s3, 0xff
	s_cbranch_scc1 .LBB0_505
	s_barrier

; #define PG8_WAIT_V(n) asm volatile("s_waitcnt vmcnt(" #n ")" ::: "memory")
; template <class Epi, class Sched, bool ALIGN_EPI, bool SP2>
; __device__ __forceinline__ void gemm_phase(LAS unsigned char* lds, const Gemm g, const Sched& S, const Epi& E, int tid_in) {
;     ...
;     if constexpr (SP2) {
;         PG8_STAGE(PG8_SB(0, 0), cB, voffB); PG8_STAGE(PG8_SB(0, 1), cB + hstepB, voffB); PG8_STAGE(PG8_SA(0, 0), cA, voffA); PG8_STAGE(PG8_SA(0, 1), cA + hstepA, voffA);
;         if (wr == 1) PG8_BAR;
;         PG8_WAIT_V(2); PG8_BAR;
;         PG8_STAGE(PG8_SB(1, 0), cB + kstep, voffB); PG8_STAGE(PG8_SA(1, 0), cA + kstep, voffA); PG8_STAGE(PG8_SB(1, 1), cB + hstepB + kstep, voffB);
;         PG8_WAIT_V(6); PG8_BAR;
;     } else {
;         PG8_STAGE(PG8_SB(0, 0), cB, voffB); PG8_STAGE(PG8_SA(0, 0), cA, voffA); PG8_STAGE(PG8_SB(0, 1), cB + hstepB, voffB); PG8_STAGE(PG8_SA(0, 1), cA + hstepA, voffA);
;         if (wr == 1) PG8_BAR;
;         PG8_WAIT_V(4); PG8_BAR;
;         PG8_STAGE(PG8_SB(1, 0), cB + kstep, voffB); PG8_STAGE(PG8_SA(1, 0), cA + kstep, voffA); PG8_STAGE(PG8_SB(1, 1), cB + hstepB + kstep, voffB);
;         PG8_WAIT_V(6); PG8_BAR;
;     }
;     for (;;) {
;         const bool has_next = S.next(ui + 1, nxt);
;         const unsigned nA = has_next ? (unsigned)nxt.pm * tstepA : cA, nB = has_next ? (unsigned)nxt.pn * tstepB : cB;
;         for (int t = 0; t < nt; t += 2) {
;             const bool last = (t == nt - 2);
;             const unsigned a1 = cA + (unsigned)(t + 1) * kstep;
;             const unsigned a2 = last ? nA : cA + (unsigned)(t + 2) * kstep, b2 = last ? nB : cB + (unsigned)(t + 2) * kstep;
;             const unsigned a3 = a2 + kstep, b3 = b2 + kstep;
;             if constexpr (Epi::MIDK) { if (t == g.kmid) E.midk(acc, wr, fr); }
;             if constexpr (SP2) {
;             PG8_LDB(B0, 0, 0); PG8_LDB(B1, 0, 1); PG8_SCHED; PG8_LDA(At, 0, 0); PG8_STAGE(PG8_SA(1, 1), a1 + hstepA, voffA);
;             PG8_WAIT_V(8); PG8_WAIT_L(0); PG8_BAR; PG8_MMA(0, 0, At, B0); PG8_MMA(0, 1, At, B1); PG8_BAR; PG8_SCHED;
; __device__ __forceinline__ void p2_ssm(const Frame& F, ArgsP a, int l) {
;     ...
;         { pg8::Gemm g2{a2g, (const bf16_t*)(F.ws + WS_BT2) + (size_t)lg * 256 * A2LD, A2LD, A2LD, A2LD, -1}; pg8::OneUnit S{bp, 0};
;           EpiSsmOut E{a2g, a->in[I_D] + (size_t)l * DS + g * 16, (bf16_t*)(F.ws + WS_YG), F.ws + WS_YG8, g};
.LBB0_512:
	v_readlane_b32 s66, v255, 42
	v_readlane_b32 s67, v255, 43
	s_waitcnt lgkmcnt(0)
	s_add_u32 s11, s2, s66
	s_addc_u32 s34, s3, s67
	s_lshl_b32 s2, s17, 4
	s_ashr_i32 s3, s2, 31
	s_lshl_b64 s[66:67], s[2:3], 2
	s_add_u32 s66, s11, s66
	v_bfe_u32 v11, v5, 4, 2
	s_addc_u32 s67, s34, s67
	s_and_b32 s5, s5, 3
	v_and_b32_e32 v10, 15, v5
	v_lshlrev_b32_e32 v6, 4, v11
	v_lshlrev_b32_e32 v5, 2, v5
	s_add_i32 s50, s25, s14
	v_lshl_or_b32 v6, v10, 6, v6
	v_and_b32_e32 v5, 32, v5
	s_lshl_b32 s17, s5, 12
	s_mov_b32 m0, s50
	s_movk_i32 s74, 0x80
	s_add_i32 s52, s50, 0x2000
	s_lshl_b32 s11, s15, 6
	s_lshl_b32 s15, s15, 13
	v_bitop3_b32 v12, v6, s17, v5 bitop3:0xde
	s_waitcnt vmcnt(2)
	s_barrier
	buffer_load_dwordx4 v2, s[84:87], s74 offen lds
	s_mov_b32 m0, s52
	s_add_i32 s17, s56, 0x8000
	v_bitop3_b32 v5, v6, s15, v5 bitop3:0xde
	buffer_load_dwordx4 v4, s[84:87], s74 offen lds
	s_mov_b32 m0, s17
	s_add_i32 s34, s56, 0xa000
	s_add_i32 s15, 0, 0x1c000
	buffer_load_dwordx4 v0, s[36:39], s12 offen lds
	s_mov_b32 m0, s34
	s_add_i32 s57, s15, s14
	buffer_load_dwordx4 v3, s[36:39], s12 offen lds
	s_mov_b32 m0, s57
	s_movk_i32 s75, 0x6080
	s_add_i32 s65, s57, 0x2000
	buffer_load_dwordx4 v2, s[84:87], s75 offen lds
	s_mov_b32 m0, s65
	v_add_u32_e32 v6, 0, v12
	buffer_load_dwordx4 v4, s[84:87], s75 offen lds
	v_add_u32_e32 v9, 0x10000, v6
	s_waitcnt vmcnt(6)
	s_barrier
	v_add_u32_e32 v8, 0x14000, v6
	v_add_u32_e32 v7, s25, v12
	v_add_u32_e32 v6, s15, v12
	ds_read_b128 v[12:15], v9
	ds_read_b128 v[16:19], v9 offset:1024
	ds_read_b128 v[20:23], v9 offset:2048
	ds_read_b128 v[24:27], v9 offset:3072
	ds_read_b128 v[28:31], v8
	ds_read_b128 v[32:35], v8 offset:1024
	ds_read_b128 v[36:39], v8 offset:2048
	ds_read_b128 v[40:43], v8 offset:3072
	v_add_u32_e32 v5, 0, v5
	s_add_i32 s73, s56, 0xc000
	s_mov_b32 m0, s73
	s_add_i32 s25, s56, 0xe000
	ds_read_b128 v[44:47], v5
	ds_read_b128 v[48:51], v5 offset:1024
	ds_read_b128 v[52:55], v5 offset:2048
	ds_read_b128 v[56:59], v5 offset:3072
	ds_read_b128 v[60:63], v5 offset:4096
	ds_read_b128 v[64:67], v5 offset:5120
	ds_read_b128 v[68:71], v5 offset:6144
	ds_read_b128 v[72:75], v5 offset:7168
	buffer_load_dwordx4 v0, s[36:39], s27 offen lds
	s_mov_b32 m0, s25
	s_nop 0
	buffer_load_dwordx4 v3, s[36:39], s27 offen lds
	s_waitcnt vmcnt(8)
	s_waitcnt lgkmcnt(0)
	s_barrier
	s_waitcnt lgkmcnt(7)
	v_mfma_f32_16x16x32_bf16 v[76:79], v[12:15], v[44:47], 0
	v_mfma_f32_16x16x32_bf16 v[80:83], v[20:23], v[44:47], 0
	s_waitcnt lgkmcnt(5)
	v_mfma_f32_16x16x32_bf16 v[84:87], v[12:15], v[52:55], 0
	v_mfma_f32_16x16x32_bf16 v[88:91], v[20:23], v[52:55], 0
	s_waitcnt lgkmcnt(3)
	v_mfma_f32_16x16x32_bf16 v[92:95], v[12:15], v[60:63], 0
	v_mfma_f32_16x16x32_bf16 v[96:99], v[20:23], v[60:63], 0
	s_waitcnt lgkmcnt(1)
	v_mfma_f32_16x16x32_bf16 v[100:103], v[12:15], v[68:71], 0
	v_mfma_f32_16x16x32_bf16 v[104:107], v[20:23], v[68:71], 0
	v_mfma_f32_16x16x32_bf16 v[76:79], v[16:19], v[48:51], v[76:79]
	v_mfma_f32_16x16x32_bf16 v[80:83], v[24:27], v[48:51], v[80:83]
	v_mfma_f32_16x16x32_bf16 v[84:87], v[16:19], v[56:59], v[84:87]
	v_mfma_f32_16x16x32_bf16 v[88:91], v[24:27], v[56:59], v[88:91]
	v_mfma_f32_16x16x32_bf16 v[92:95], v[16:19], v[64:67], v[92:95]
	v_mfma_f32_16x16x32_bf16 v[96:99], v[24:27], v[64:67], v[96:99]
	s_waitcnt lgkmcnt(0)
	v_mfma_f32_16x16x32_bf16 v[100:103], v[16:19], v[72:75], v[100:103]
	v_mfma_f32_16x16x32_bf16 v[104:107], v[24:27], v[72:75], v[104:107]
	v_mfma_f32_16x16x32_bf16 v[108:111], v[28:31], v[44:47], 0
	v_mfma_f32_16x16x32_bf16 v[44:47], v[36:39], v[44:47], 0
	v_mfma_f32_16x16x32_bf16 v[108:111], v[32:35], v[48:51], v[108:111]
	v_mfma_f32_16x16x32_bf16 v[44:47], v[40:43], v[48:51], v[44:47]
	v_mfma_f32_16x16x32_bf16 v[48:51], v[28:31], v[52:55], 0
	v_mfma_f32_16x16x32_bf16 v[52:55], v[36:39], v[52:55], 0
	v_mfma_f32_16x16x32_bf16 v[48:51], v[32:35], v[56:59], v[48:51]
	v_mfma_f32_16x16x32_bf16 v[52:55], v[40:43], v[56:59], v[52:55]
	v_mfma_f32_16x16x32_bf16 v[56:59], v[28:31], v[60:63], 0
	v_mfma_f32_16x16x32_bf16 v[60:63], v[36:39], v[60:63], 0
	v_mfma_f32_16x16x32_bf16 v[56:59], v[32:35], v[64:67], v[56:59]
	v_mfma_f32_16x16x32_bf16 v[60:63], v[40:43], v[64:67], v[60:63]
	v_mfma_f32_16x16x32_bf16 v[64:67], v[28:31], v[68:71], 0
	v_mfma_f32_16x16x32_bf16 v[68:71], v[36:39], v[68:71], 0
	v_mfma_f32_16x16x32_bf16 v[64:67], v[32:35], v[72:75], v[64:67]
	v_mfma_f32_16x16x32_bf16 v[68:71], v[40:43], v[72:75], v[68:71]
	s_barrier
	s_mov_b32 m0, s68
	s_movk_i32 s14, 0x100
	ds_read_b128 v[72:75], v5 offset:16384
	ds_read_b128 v[116:119], v5 offset:17408
	ds_read_b128 v[120:123], v5 offset:18432
	ds_read_b128 v[124:127], v5 offset:19456
	ds_read_b128 v[128:131], v5 offset:20480
	ds_read_b128 v[132:135], v5 offset:21504
	ds_read_b128 v[136:139], v5 offset:22528
	ds_read_b128 v[140:143], v5 offset:23552
	buffer_load_dwordx4 v2, s[84:87], s14 offen lds
	s_mov_b32 m0, s69
	s_nop 0
	buffer_load_dwordx4 v4, s[84:87], s14 offen lds
	s_mov_b32 m0, s70
	s_movk_i32 s14, 0x6100
	buffer_load_dwordx4 v2, s[84:87], s14 offen lds
	s_mov_b32 m0, s71
	s_nop 0
	buffer_load_dwordx4 v4, s[84:87], s14 offen lds
	s_mov_b32 m0, s56
	s_nop 0
	buffer_load_dwordx4 v0, s[36:39], s19 offen lds
	s_mov_b32 m0, s72
	s_nop 0
	buffer_load_dwordx4 v3, s[36:39], s19 offen lds
	s_waitcnt vmcnt(8)
	s_waitcnt lgkmcnt(0)
	s_barrier
; #define PG8_STAGE(bufoff, goff, voff) do { _Pragma("unroll") for (int _i = 0; _i < 2; ++_i) \
;         __builtin_amdgcn_raw_ptr_buffer_load_lds(R_##voff, (LAS void*)(lds + (bufoff) + ldsw + _i * 8192), 16, (int)(voff)[_i], (int)(goff), 0, 0); } while (0)
; #define PG8_WAIT_V(n) asm volatile("s_waitcnt vmcnt(" #n ")" ::: "memory")
; #define PG8_WAIT_L(n) asm volatile("s_waitcnt lgkmcnt(" #n ")" ::: "memory")
; #define PG8_BAR __builtin_amdgcn_s_barrier()
; #define PG8_SCHED __builtin_amdgcn_sched_barrier(0)
; template <class Epi, class Sched, bool ALIGN_EPI, bool SP2>
; __device__ __forceinline__ void gemm_phase(LAS unsigned char* lds, const Gemm g, const Sched& S, const Epi& E, int tid_in) {
;     ...
;             PG8_LDB(B0, 0, 0); PG8_LDB(B1, 0, 1); PG8_SCHED; PG8_LDA(At, 0, 0); PG8_STAGE(PG8_SA(1, 1), a1 + hstepA, voffA);
;             PG8_WAIT_V(8); PG8_WAIT_L(0); PG8_BAR; PG8_MMA(0, 0, At, B0); PG8_MMA(0, 1, At, B1); PG8_BAR; PG8_SCHED;
;             PG8_LDA(At, 0, 1); PG8_STAGE(PG8_SB(0, 0), b2, voffB); PG8_STAGE(PG8_SB(0, 1), b2 + hstepB, voffB); PG8_STAGE(PG8_SA(0, 0), a2, voffA);
;             PG8_WAIT_V(8); PG8_WAIT_L(0); PG8_BAR; PG8_MMA(1, 0, At, B0); PG8_MMA(1, 1, At, B1); PG8_BAR; PG8_SCHED;
;             PG8_LDB(B0, 1, 0); PG8_LDB(B1, 1, 1); PG8_SCHED; PG8_LDA(At, 1, 0); PG8_STAGE(PG8_SA(0, 1), a2 + hstepA, voffA);
;             PG8_WAIT_V(8); PG8_WAIT_L(0); PG8_BAR; PG8_MMA(0, 0, At, B0); PG8_MMA(0, 1, At, B1); PG8_BAR; PG8_SCHED;
;             PG8_LDA(At, 1, 1); PG8_STAGE(PG8_SB(1, 0), b3, voffB); PG8_STAGE(PG8_SB(1, 1), b3 + hstepB, voffB); PG8_STAGE(PG8_SA(1, 0), a3, voffA);
;             PG8_WAIT_V(8); PG8_WAIT_L(0); PG8_BAR; PG8_MMA(1, 0, At, B0); PG8_MMA(1, 1, At, B1); PG8_BAR; PG8_SCHED;
	s_waitcnt lgkmcnt(7)
	v_mfma_f32_16x16x32_bf16 v[144:147], v[12:15], v[72:75], 0
	s_waitcnt lgkmcnt(5)
	v_mfma_f32_16x16x32_bf16 v[152:155], v[12:15], v[120:123], 0
	s_waitcnt lgkmcnt(3)
	v_mfma_f32_16x16x32_bf16 v[160:163], v[12:15], v[128:131], 0
	s_waitcnt lgkmcnt(1)
	v_mfma_f32_16x16x32_bf16 v[12:15], v[12:15], v[136:139], 0
	v_mfma_f32_16x16x32_bf16 v[144:147], v[16:19], v[116:119], v[144:147]
	v_mfma_f32_16x16x32_bf16 v[148:151], v[20:23], v[72:75], 0
	v_mfma_f32_16x16x32_bf16 v[152:155], v[16:19], v[124:127], v[152:155]
	v_mfma_f32_16x16x32_bf16 v[156:159], v[20:23], v[120:123], 0
	v_mfma_f32_16x16x32_bf16 v[160:163], v[16:19], v[132:135], v[160:163]
	v_mfma_f32_16x16x32_bf16 v[164:167], v[20:23], v[128:131], 0
	s_waitcnt lgkmcnt(0)
	v_mfma_f32_16x16x32_bf16 v[12:15], v[16:19], v[140:143], v[12:15]
	v_mfma_f32_16x16x32_bf16 v[16:19], v[20:23], v[136:139], 0
	v_mfma_f32_16x16x32_bf16 v[148:151], v[24:27], v[116:119], v[148:151]
	v_mfma_f32_16x16x32_bf16 v[156:159], v[24:27], v[124:127], v[156:159]
	v_mfma_f32_16x16x32_bf16 v[164:167], v[24:27], v[132:135], v[164:167]
	v_mfma_f32_16x16x32_bf16 v[16:19], v[24:27], v[140:143], v[16:19]
	v_mfma_f32_16x16x32_bf16 v[20:23], v[28:31], v[72:75], 0
	v_mfma_f32_16x16x32_bf16 v[24:27], v[36:39], v[72:75], 0
	v_mfma_f32_16x16x32_bf16 v[20:23], v[32:35], v[116:119], v[20:23]
	v_mfma_f32_16x16x32_bf16 v[24:27], v[40:43], v[116:119], v[24:27]
	v_mfma_f32_16x16x32_bf16 v[72:75], v[28:31], v[120:123], 0
	v_mfma_f32_16x16x32_bf16 v[116:119], v[36:39], v[120:123], 0
	v_mfma_f32_16x16x32_bf16 v[120:123], v[28:31], v[128:131], 0
	v_mfma_f32_16x16x32_bf16 v[28:31], v[28:31], v[136:139], 0
	v_mfma_f32_16x16x32_bf16 v[72:75], v[32:35], v[124:127], v[72:75]
	v_mfma_f32_16x16x32_bf16 v[116:119], v[40:43], v[124:127], v[116:119]
	v_mfma_f32_16x16x32_bf16 v[120:123], v[32:35], v[132:135], v[120:123]
	v_mfma_f32_16x16x32_bf16 v[124:127], v[36:39], v[128:131], 0
	v_mfma_f32_16x16x32_bf16 v[28:31], v[32:35], v[140:143], v[28:31]
	v_mfma_f32_16x16x32_bf16 v[32:35], v[36:39], v[136:139], 0
	v_mfma_f32_16x16x32_bf16 v[124:127], v[40:43], v[132:135], v[124:127]
	v_mfma_f32_16x16x32_bf16 v[32:35], v[40:43], v[140:143], v[32:35]
	s_barrier
	ds_read_b128 v[36:39], v7
	ds_read_b128 v[40:43], v7 offset:1024
	ds_read_b128 v[128:131], v7 offset:2048
	ds_read_b128 v[132:135], v7 offset:3072
	ds_read_b128 v[136:139], v6
	ds_read_b128 v[140:143], v6 offset:1024
	ds_read_b128 v[168:171], v6 offset:2048
	ds_read_b128 v[172:175], v6 offset:3072
	s_mov_b32 m0, s30
	ds_read_b128 v[176:179], v5 offset:32768
	ds_read_b128 v[180:183], v5 offset:33792
	ds_read_b128 v[184:187], v5 offset:34816
	ds_read_b128 v[188:191], v5 offset:35840
	ds_read_b128 v[192:195], v5 offset:36864
	ds_read_b128 v[196:199], v5 offset:37888
	ds_read_b128 v[200:203], v5 offset:38912
	ds_read_b128 v[204:207], v5 offset:39936
	buffer_load_dwordx4 v0, s[36:39], s29 offen lds
	s_mov_b32 m0, s31
	s_nop 0
	buffer_load_dwordx4 v3, s[36:39], s29 offen lds
	s_waitcnt vmcnt(8)
	s_waitcnt lgkmcnt(0)
	s_barrier
	s_waitcnt lgkmcnt(7)
	v_mfma_f32_16x16x32_bf16 v[76:79], v[36:39], v[176:179], v[76:79]
	v_mfma_f32_16x16x32_bf16 v[80:83], v[128:131], v[176:179], v[80:83]
	s_waitcnt lgkmcnt(5)
	v_mfma_f32_16x16x32_bf16 v[84:87], v[36:39], v[184:187], v[84:87]
	v_mfma_f32_16x16x32_bf16 v[88:91], v[128:131], v[184:187], v[88:91]
	s_waitcnt lgkmcnt(3)
	v_mfma_f32_16x16x32_bf16 v[92:95], v[36:39], v[192:195], v[92:95]
	v_mfma_f32_16x16x32_bf16 v[96:99], v[128:131], v[192:195], v[96:99]
	s_waitcnt lgkmcnt(1)
	v_mfma_f32_16x16x32_bf16 v[100:103], v[36:39], v[200:203], v[100:103]
	v_mfma_f32_16x16x32_bf16 v[104:107], v[128:131], v[200:203], v[104:107]
	v_mfma_f32_16x16x32_bf16 v[76:79], v[40:43], v[180:183], v[76:79]
	v_mfma_f32_16x16x32_bf16 v[80:83], v[132:135], v[180:183], v[80:83]
	v_mfma_f32_16x16x32_bf16 v[84:87], v[40:43], v[188:191], v[84:87]
	v_mfma_f32_16x16x32_bf16 v[88:91], v[132:135], v[188:191], v[88:91]
	v_mfma_f32_16x16x32_bf16 v[92:95], v[40:43], v[196:199], v[92:95]
	v_mfma_f32_16x16x32_bf16 v[96:99], v[132:135], v[196:199], v[96:99]
	s_waitcnt lgkmcnt(0)
	v_mfma_f32_16x16x32_bf16 v[100:103], v[40:43], v[204:207], v[100:103]
	v_mfma_f32_16x16x32_bf16 v[104:107], v[132:135], v[204:207], v[104:107]
	v_mfma_f32_16x16x32_bf16 v[108:111], v[136:139], v[176:179], v[108:111]
	v_mfma_f32_16x16x32_bf16 v[44:47], v[168:171], v[176:179], v[44:47]
	v_mfma_f32_16x16x32_bf16 v[48:51], v[136:139], v[184:187], v[48:51]
	v_mfma_f32_16x16x32_bf16 v[52:55], v[168:171], v[184:187], v[52:55]
	v_mfma_f32_16x16x32_bf16 v[56:59], v[136:139], v[192:195], v[56:59]
	v_mfma_f32_16x16x32_bf16 v[60:63], v[168:171], v[192:195], v[60:63]
	v_mfma_f32_16x16x32_bf16 v[64:67], v[136:139], v[200:203], v[64:67]
	v_mfma_f32_16x16x32_bf16 v[68:71], v[168:171], v[200:203], v[68:71]
	v_mfma_f32_16x16x32_bf16 v[108:111], v[140:143], v[180:183], v[108:111]
	v_mfma_f32_16x16x32_bf16 v[44:47], v[172:175], v[180:183], v[44:47]
	v_mfma_f32_16x16x32_bf16 v[48:51], v[140:143], v[188:191], v[48:51]
	v_mfma_f32_16x16x32_bf16 v[52:55], v[172:175], v[188:191], v[52:55]
	v_mfma_f32_16x16x32_bf16 v[56:59], v[140:143], v[196:199], v[56:59]
	v_mfma_f32_16x16x32_bf16 v[60:63], v[172:175], v[196:199], v[60:63]
	v_mfma_f32_16x16x32_bf16 v[64:67], v[140:143], v[204:207], v[64:67]
	v_mfma_f32_16x16x32_bf16 v[68:71], v[172:175], v[204:207], v[68:71]
	s_barrier
; #define PG8_STAGE(bufoff, goff, voff) do { _Pragma("unroll") for (int _i = 0; _i < 2; ++_i) \
;         __builtin_amdgcn_raw_ptr_buffer_load_lds(R_##voff, (LAS void*)(lds + (bufoff) + ldsw + _i * 8192), 16, (int)(voff)[_i], (int)(goff), 0, 0); } while (0)
; #define PG8_WAIT_V(n) asm volatile("s_waitcnt vmcnt(" #n ")" ::: "memory")
; #define PG8_WAIT_L(n) asm volatile("s_waitcnt lgkmcnt(" #n ")" ::: "memory")
; #define PG8_BAR __builtin_amdgcn_s_barrier()
; #define PG8_SCHED __builtin_amdgcn_sched_barrier(0)
; template <class Epi, class Sched, bool ALIGN_EPI, bool SP2>
; __device__ __forceinline__ void gemm_phase(LAS unsigned char* lds, const Gemm g, const Sched& S, const Epi& E, int tid_in) {
;     ...
;             PG8_LDB(B0, 0, 0); PG8_LDB(B1, 0, 1); PG8_SCHED; PG8_LDA(At, 0, 0); PG8_STAGE(PG8_SA(1, 1), a1 + hstepA, voffA);
;             PG8_WAIT_V(8); PG8_WAIT_L(0); PG8_BAR; PG8_MMA(0, 0, At, B0); PG8_MMA(0, 1, At, B1); PG8_BAR; PG8_SCHED;
;             PG8_LDA(At, 0, 1); PG8_STAGE(PG8_SB(0, 0), b2, voffB); PG8_STAGE(PG8_SB(0, 1), b2 + hstepB, voffB); PG8_STAGE(PG8_SA(0, 0), a2, voffA);
;             PG8_WAIT_V(8); PG8_WAIT_L(0); PG8_BAR; PG8_MMA(1, 0, At, B0); PG8_MMA(1, 1, At, B1); PG8_BAR; PG8_SCHED;
;             PG8_LDB(B0, 1, 0); PG8_LDB(B1, 1, 1); PG8_SCHED; PG8_LDA(At, 1, 0); PG8_STAGE(PG8_SA(0, 1), a2 + hstepA, voffA);
;             PG8_WAIT_V(8); PG8_WAIT_L(0); PG8_BAR; PG8_MMA(0, 0, At, B0); PG8_MMA(0, 1, At, B1); PG8_BAR; PG8_SCHED;
;             PG8_LDA(At, 1, 1); PG8_STAGE(PG8_SB(1, 0), b3, voffB); PG8_STAGE(PG8_SB(1, 1), b3 + hstepB, voffB); PG8_STAGE(PG8_SA(1, 0), a3, voffA);
;             PG8_WAIT_V(8); PG8_WAIT_L(0); PG8_BAR; PG8_MMA(1, 0, At, B0); PG8_MMA(1, 1, At, B1); PG8_BAR; PG8_SCHED;
	s_mov_b32 m0, s50
	s_movk_i32 s14, 0x180
	ds_read_b128 v[176:179], v5 offset:49152
	ds_read_b128 v[180:183], v5 offset:50176
	ds_read_b128 v[184:187], v5 offset:51200
	ds_read_b128 v[188:191], v5 offset:52224
	ds_read_b128 v[192:195], v5 offset:53248
	ds_read_b128 v[196:199], v5 offset:54272
	ds_read_b128 v[200:203], v5 offset:55296
	ds_read_b128 v[204:207], v5 offset:56320
	buffer_load_dwordx4 v2, s[84:87], s14 offen lds
	s_mov_b32 m0, s52
	s_nop 0
	buffer_load_dwordx4 v4, s[84:87], s14 offen lds
	s_mov_b32 m0, s57
	s_movk_i32 s14, 0x6180
	buffer_load_dwordx4 v2, s[84:87], s14 offen lds
	s_mov_b32 m0, s65
	s_nop 0
	buffer_load_dwordx4 v4, s[84:87], s14 offen lds
	s_mov_b32 m0, s17
	s_nop 0
	buffer_load_dwordx4 v0, s[36:39], s16 offen lds
	s_mov_b32 m0, s34
	s_nop 0
	buffer_load_dwordx4 v3, s[36:39], s16 offen lds
	s_waitcnt vmcnt(8)
	s_waitcnt lgkmcnt(0)
	s_barrier
	s_waitcnt lgkmcnt(7)
	v_mfma_f32_16x16x32_bf16 v[144:147], v[36:39], v[176:179], v[144:147]
	v_mfma_f32_16x16x32_bf16 v[148:151], v[128:131], v[176:179], v[148:151]
	s_waitcnt lgkmcnt(5)
	v_mfma_f32_16x16x32_bf16 v[152:155], v[36:39], v[184:187], v[152:155]
	v_mfma_f32_16x16x32_bf16 v[156:159], v[128:131], v[184:187], v[156:159]
	s_waitcnt lgkmcnt(3)
	v_mfma_f32_16x16x32_bf16 v[160:163], v[36:39], v[192:195], v[160:163]
	v_mfma_f32_16x16x32_bf16 v[164:167], v[128:131], v[192:195], v[164:167]
	s_waitcnt lgkmcnt(1)
	v_mfma_f32_16x16x32_bf16 v[12:15], v[36:39], v[200:203], v[12:15]
	v_mfma_f32_16x16x32_bf16 v[16:19], v[128:131], v[200:203], v[16:19]
	v_mfma_f32_16x16x32_bf16 v[144:147], v[40:43], v[180:183], v[144:147]
	v_mfma_f32_16x16x32_bf16 v[148:151], v[132:135], v[180:183], v[148:151]
	v_mfma_f32_16x16x32_bf16 v[152:155], v[40:43], v[188:191], v[152:155]
	v_mfma_f32_16x16x32_bf16 v[156:159], v[132:135], v[188:191], v[156:159]
	v_mfma_f32_16x16x32_bf16 v[160:163], v[40:43], v[196:199], v[160:163]
	v_mfma_f32_16x16x32_bf16 v[164:167], v[132:135], v[196:199], v[164:167]
	s_waitcnt lgkmcnt(0)
	v_mfma_f32_16x16x32_bf16 v[12:15], v[40:43], v[204:207], v[12:15]
	v_mfma_f32_16x16x32_bf16 v[16:19], v[132:135], v[204:207], v[16:19]
	v_mfma_f32_16x16x32_bf16 v[20:23], v[136:139], v[176:179], v[20:23]
	v_mfma_f32_16x16x32_bf16 v[24:27], v[168:171], v[176:179], v[24:27]
	v_mfma_f32_16x16x32_bf16 v[36:39], v[136:139], v[184:187], v[72:75]
	v_mfma_f32_16x16x32_bf16 v[40:43], v[168:171], v[184:187], v[116:119]
	v_mfma_f32_16x16x32_bf16 v[72:75], v[136:139], v[192:195], v[120:123]
	v_mfma_f32_16x16x32_bf16 v[116:119], v[168:171], v[192:195], v[124:127]
	v_mfma_f32_16x16x32_bf16 v[28:31], v[136:139], v[200:203], v[28:31]
	v_mfma_f32_16x16x32_bf16 v[32:35], v[168:171], v[200:203], v[32:35]
	v_mfma_f32_16x16x32_bf16 v[20:23], v[140:143], v[180:183], v[20:23]
	v_mfma_f32_16x16x32_bf16 v[24:27], v[172:175], v[180:183], v[24:27]
	v_mfma_f32_16x16x32_bf16 v[36:39], v[140:143], v[188:191], v[36:39]
	v_mfma_f32_16x16x32_bf16 v[40:43], v[172:175], v[188:191], v[40:43]
	v_mfma_f32_16x16x32_bf16 v[72:75], v[140:143], v[196:199], v[72:75]
	v_mfma_f32_16x16x32_bf16 v[116:119], v[172:175], v[196:199], v[116:119]
	v_mfma_f32_16x16x32_bf16 v[28:31], v[140:143], v[204:207], v[28:31]
	v_mfma_f32_16x16x32_bf16 v[32:35], v[172:175], v[204:207], v[32:35]
	s_barrier
	ds_read_b128 v[120:123], v9
	ds_read_b128 v[124:127], v9 offset:1024
	ds_read_b128 v[128:131], v9 offset:2048
	ds_read_b128 v[132:135], v9 offset:3072
	ds_read_b128 v[136:139], v8
	ds_read_b128 v[140:143], v8 offset:1024
	ds_read_b128 v[168:171], v8 offset:2048
	ds_read_b128 v[172:175], v8 offset:3072
	s_or_b32 s14, s13, 0x200
	s_or_b32 s15, s13, 0x280
	s_mov_b32 m0, s73
	ds_read_b128 v[176:179], v5
	ds_read_b128 v[180:183], v5 offset:1024
	ds_read_b128 v[184:187], v5 offset:2048
	ds_read_b128 v[188:191], v5 offset:3072
	ds_read_b128 v[192:195], v5 offset:4096
	ds_read_b128 v[196:199], v5 offset:5120
	ds_read_b128 v[200:203], v5 offset:6144
	ds_read_b128 v[204:207], v5 offset:7168
	buffer_load_dwordx4 v0, s[36:39], s20 offen lds
	s_mov_b32 m0, s25
	s_nop 0
	buffer_load_dwordx4 v3, s[36:39], s20 offen lds
	s_waitcnt vmcnt(8)
	s_waitcnt lgkmcnt(0)
	s_barrier
	s_waitcnt lgkmcnt(7)
	v_mfma_f32_16x16x32_bf16 v[76:79], v[120:123], v[176:179], v[76:79]
	v_mfma_f32_16x16x32_bf16 v[80:83], v[128:131], v[176:179], v[80:83]
	s_waitcnt lgkmcnt(5)
	v_mfma_f32_16x16x32_bf16 v[84:87], v[120:123], v[184:187], v[84:87]
	v_mfma_f32_16x16x32_bf16 v[88:91], v[128:131], v[184:187], v[88:91]
	s_waitcnt lgkmcnt(3)
	v_mfma_f32_16x16x32_bf16 v[92:95], v[120:123], v[192:195], v[92:95]
	v_mfma_f32_16x16x32_bf16 v[96:99], v[128:131], v[192:195], v[96:99]
	s_waitcnt lgkmcnt(1)
	v_mfma_f32_16x16x32_bf16 v[100:103], v[120:123], v[200:203], v[100:103]
	v_mfma_f32_16x16x32_bf16 v[104:107], v[128:131], v[200:203], v[104:107]
	v_mfma_f32_16x16x32_bf16 v[76:79], v[124:127], v[180:183], v[76:79]
	v_mfma_f32_16x16x32_bf16 v[80:83], v[132:135], v[180:183], v[80:83]
	v_mfma_f32_16x16x32_bf16 v[84:87], v[124:127], v[188:191], v[84:87]
	v_mfma_f32_16x16x32_bf16 v[88:91], v[132:135], v[188:191], v[88:91]
	v_mfma_f32_16x16x32_bf16 v[92:95], v[124:127], v[196:199], v[92:95]
	v_mfma_f32_16x16x32_bf16 v[96:99], v[132:135], v[196:199], v[96:99]
	s_waitcnt lgkmcnt(0)
	v_mfma_f32_16x16x32_bf16 v[100:103], v[124:127], v[204:207], v[100:103]
	v_mfma_f32_16x16x32_bf16 v[104:107], v[132:135], v[204:207], v[104:107]
	v_mfma_f32_16x16x32_bf16 v[108:111], v[136:139], v[176:179], v[108:111]
	v_mfma_f32_16x16x32_bf16 v[44:47], v[168:171], v[176:179], v[44:47]
	v_mfma_f32_16x16x32_bf16 v[48:51], v[136:139], v[184:187], v[48:51]
	v_mfma_f32_16x16x32_bf16 v[52:55], v[168:171], v[184:187], v[52:55]
	v_mfma_f32_16x16x32_bf16 v[56:59], v[136:139], v[192:195], v[56:59]
	v_mfma_f32_16x16x32_bf16 v[60:63], v[168:171], v[192:195], v[60:63]
	v_mfma_f32_16x16x32_bf16 v[64:67], v[136:139], v[200:203], v[64:67]
	v_mfma_f32_16x16x32_bf16 v[68:71], v[168:171], v[200:203], v[68:71]
	v_mfma_f32_16x16x32_bf16 v[108:111], v[140:143], v[180:183], v[108:111]
	v_mfma_f32_16x16x32_bf16 v[44:47], v[172:175], v[180:183], v[44:47]
	v_mfma_f32_16x16x32_bf16 v[48:51], v[140:143], v[188:191], v[48:51]
	v_mfma_f32_16x16x32_bf16 v[52:55], v[172:175], v[188:191], v[52:55]
	v_mfma_f32_16x16x32_bf16 v[56:59], v[140:143], v[196:199], v[56:59]
	v_mfma_f32_16x16x32_bf16 v[60:63], v[172:175], v[196:199], v[60:63]
	v_mfma_f32_16x16x32_bf16 v[64:67], v[140:143], v[204:207], v[64:67]
	v_mfma_f32_16x16x32_bf16 v[68:71], v[172:175], v[204:207], v[68:71]
	s_barrier
; #define PG8_STAGE(bufoff, goff, voff) do { _Pragma("unroll") for (int _i = 0; _i < 2; ++_i) \
;         __builtin_amdgcn_raw_ptr_buffer_load_lds(R_##voff, (LAS void*)(lds + (bufoff) + ldsw + _i * 8192), 16, (int)(voff)[_i], (int)(goff), 0, 0); } while (0)
; #define PG8_WAIT_V(n) asm volatile("s_waitcnt vmcnt(" #n ")" ::: "memory")
; #define PG8_WAIT_L(n) asm volatile("s_waitcnt lgkmcnt(" #n ")" ::: "memory")
; #define PG8_BAR __builtin_amdgcn_s_barrier()
; #define PG8_SCHED __builtin_amdgcn_sched_barrier(0)
; template <class Epi, class Sched, bool ALIGN_EPI, bool SP2>
; __device__ __forceinline__ void gemm_phase(LAS unsigned char* lds, const Gemm g, const Sched& S, const Epi& E, int tid_in) {
;     ...
;             PG8_LDB(B0, 0, 0); PG8_LDB(B1, 0, 1); PG8_SCHED; PG8_LDA(At, 0, 0); PG8_STAGE(PG8_SA(1, 1), a1 + hstepA, voffA);
;             PG8_WAIT_V(8); PG8_WAIT_L(0); PG8_BAR; PG8_MMA(0, 0, At, B0); PG8_MMA(0, 1, At, B1); PG8_BAR; PG8_SCHED;
;             PG8_LDA(At, 0, 1); PG8_STAGE(PG8_SB(0, 0), b2, voffB); PG8_STAGE(PG8_SB(0, 1), b2 + hstepB, voffB); PG8_STAGE(PG8_SA(0, 0), a2, voffA);
;             PG8_WAIT_V(8); PG8_WAIT_L(0); PG8_BAR; PG8_MMA(1, 0, At, B0); PG8_MMA(1, 1, At, B1); PG8_BAR; PG8_SCHED;
;             PG8_LDB(B0, 1, 0); PG8_LDB(B1, 1, 1); PG8_SCHED; PG8_LDA(At, 1, 0); PG8_STAGE(PG8_SA(0, 1), a2 + hstepA, voffA);
;             PG8_WAIT_V(8); PG8_WAIT_L(0); PG8_BAR; PG8_MMA(0, 0, At, B0); PG8_MMA(0, 1, At, B1); PG8_BAR; PG8_SCHED;
;             PG8_LDA(At, 1, 1); PG8_STAGE(PG8_SB(1, 0), b3, voffB); PG8_STAGE(PG8_SB(1, 1), b3 + hstepB, voffB); PG8_STAGE(PG8_SA(1, 0), a3, voffA);
;             PG8_WAIT_V(8); PG8_WAIT_L(0); PG8_BAR; PG8_MMA(1, 0, At, B0); PG8_MMA(1, 1, At, B1); PG8_BAR; PG8_SCHED;
	s_mov_b32 m0, s68
	s_movk_i32 s16, 0x200
	ds_read_b128 v[176:179], v5 offset:16384
	ds_read_b128 v[180:183], v5 offset:17408
	ds_read_b128 v[184:187], v5 offset:18432
	ds_read_b128 v[188:191], v5 offset:19456
	ds_read_b128 v[192:195], v5 offset:20480
	ds_read_b128 v[196:199], v5 offset:21504
	ds_read_b128 v[200:203], v5 offset:22528
	ds_read_b128 v[204:207], v5 offset:23552
	buffer_load_dwordx4 v2, s[84:87], s16 offen lds
	s_mov_b32 m0, s69
	s_nop 0
	buffer_load_dwordx4 v4, s[84:87], s16 offen lds
	s_mov_b32 m0, s70
	s_movk_i32 s16, 0x6200
	buffer_load_dwordx4 v2, s[84:87], s16 offen lds
	s_mov_b32 m0, s71
	s_nop 0
	buffer_load_dwordx4 v4, s[84:87], s16 offen lds
	s_mov_b32 m0, s56
	s_nop 0
	buffer_load_dwordx4 v0, s[36:39], s14 offen lds
	s_mov_b32 m0, s72
	s_nop 0
	buffer_load_dwordx4 v3, s[36:39], s14 offen lds
	s_waitcnt vmcnt(8)
	s_waitcnt lgkmcnt(0)
	s_barrier
	s_waitcnt lgkmcnt(7)
	v_mfma_f32_16x16x32_bf16 v[144:147], v[120:123], v[176:179], v[144:147]
	v_mfma_f32_16x16x32_bf16 v[148:151], v[128:131], v[176:179], v[148:151]
	s_waitcnt lgkmcnt(5)
	v_mfma_f32_16x16x32_bf16 v[152:155], v[120:123], v[184:187], v[152:155]
	v_mfma_f32_16x16x32_bf16 v[156:159], v[128:131], v[184:187], v[156:159]
	s_waitcnt lgkmcnt(3)
	v_mfma_f32_16x16x32_bf16 v[160:163], v[120:123], v[192:195], v[160:163]
	v_mfma_f32_16x16x32_bf16 v[164:167], v[128:131], v[192:195], v[164:167]
	s_waitcnt lgkmcnt(1)
	v_mfma_f32_16x16x32_bf16 v[12:15], v[120:123], v[200:203], v[12:15]
	v_mfma_f32_16x16x32_bf16 v[16:19], v[128:131], v[200:203], v[16:19]
	v_mfma_f32_16x16x32_bf16 v[144:147], v[124:127], v[180:183], v[144:147]
	v_mfma_f32_16x16x32_bf16 v[148:151], v[132:135], v[180:183], v[148:151]
	v_mfma_f32_16x16x32_bf16 v[152:155], v[124:127], v[188:191], v[152:155]
	v_mfma_f32_16x16x32_bf16 v[156:159], v[132:135], v[188:191], v[156:159]
	v_mfma_f32_16x16x32_bf16 v[160:163], v[124:127], v[196:199], v[160:163]
	v_mfma_f32_16x16x32_bf16 v[164:167], v[132:135], v[196:199], v[164:167]
	s_waitcnt lgkmcnt(0)
	v_mfma_f32_16x16x32_bf16 v[12:15], v[124:127], v[204:207], v[12:15]
	v_mfma_f32_16x16x32_bf16 v[16:19], v[132:135], v[204:207], v[16:19]
	v_mfma_f32_16x16x32_bf16 v[20:23], v[136:139], v[176:179], v[20:23]
	v_mfma_f32_16x16x32_bf16 v[24:27], v[168:171], v[176:179], v[24:27]
	v_mfma_f32_16x16x32_bf16 v[36:39], v[136:139], v[184:187], v[36:39]
	v_mfma_f32_16x16x32_bf16 v[40:43], v[168:171], v[184:187], v[40:43]
	v_mfma_f32_16x16x32_bf16 v[72:75], v[136:139], v[192:195], v[72:75]
	v_mfma_f32_16x16x32_bf16 v[116:119], v[168:171], v[192:195], v[116:119]
	v_mfma_f32_16x16x32_bf16 v[28:31], v[136:139], v[200:203], v[28:31]
	v_mfma_f32_16x16x32_bf16 v[32:35], v[168:171], v[200:203], v[32:35]
	v_mfma_f32_16x16x32_bf16 v[20:23], v[140:143], v[180:183], v[20:23]
	v_mfma_f32_16x16x32_bf16 v[24:27], v[172:175], v[180:183], v[24:27]
	v_mfma_f32_16x16x32_bf16 v[36:39], v[140:143], v[188:191], v[36:39]
	v_mfma_f32_16x16x32_bf16 v[40:43], v[172:175], v[188:191], v[40:43]
	v_mfma_f32_16x16x32_bf16 v[72:75], v[140:143], v[196:199], v[72:75]
	v_mfma_f32_16x16x32_bf16 v[116:119], v[172:175], v[196:199], v[116:119]
	v_mfma_f32_16x16x32_bf16 v[28:31], v[140:143], v[204:207], v[28:31]
	v_mfma_f32_16x16x32_bf16 v[32:35], v[172:175], v[204:207], v[32:35]
	s_barrier
	ds_read_b128 v[120:123], v7
	ds_read_b128 v[124:127], v7 offset:1024
	ds_read_b128 v[128:131], v7 offset:2048
	ds_read_b128 v[132:135], v7 offset:3072
	ds_read_b128 v[136:139], v6
	ds_read_b128 v[140:143], v6 offset:1024
	ds_read_b128 v[168:171], v6 offset:2048
	ds_read_b128 v[172:175], v6 offset:3072
	s_add_i32 s14, s13, 0x18200
	s_mov_b32 m0, s30
	ds_read_b128 v[176:179], v5 offset:32768
	ds_read_b128 v[180:183], v5 offset:33792
	ds_read_b128 v[184:187], v5 offset:34816
	ds_read_b128 v[188:191], v5 offset:35840
	ds_read_b128 v[192:195], v5 offset:36864
	ds_read_b128 v[196:199], v5 offset:37888
	ds_read_b128 v[200:203], v5 offset:38912
	ds_read_b128 v[204:207], v5 offset:39936
	buffer_load_dwordx4 v0, s[36:39], s14 offen lds
	s_mov_b32 m0, s31
	s_nop 0
	buffer_load_dwordx4 v3, s[36:39], s14 offen lds
	s_waitcnt vmcnt(8)
	s_waitcnt lgkmcnt(0)
	s_barrier
	s_waitcnt lgkmcnt(7)
	v_mfma_f32_16x16x32_bf16 v[76:79], v[120:123], v[176:179], v[76:79]
	v_mfma_f32_16x16x32_bf16 v[80:83], v[128:131], v[176:179], v[80:83]
	s_waitcnt lgkmcnt(5)
	v_mfma_f32_16x16x32_bf16 v[84:87], v[120:123], v[184:187], v[84:87]
	v_mfma_f32_16x16x32_bf16 v[88:91], v[128:131], v[184:187], v[88:91]
	s_waitcnt lgkmcnt(3)
	v_mfma_f32_16x16x32_bf16 v[92:95], v[120:123], v[192:195], v[92:95]
	v_mfma_f32_16x16x32_bf16 v[96:99], v[128:131], v[192:195], v[96:99]
	s_waitcnt lgkmcnt(1)
	v_mfma_f32_16x16x32_bf16 v[100:103], v[120:123], v[200:203], v[100:103]
	v_mfma_f32_16x16x32_bf16 v[104:107], v[128:131], v[200:203], v[104:107]
	v_mfma_f32_16x16x32_bf16 v[76:79], v[124:127], v[180:183], v[76:79]
	v_mfma_f32_16x16x32_bf16 v[80:83], v[132:135], v[180:183], v[80:83]
	v_mfma_f32_16x16x32_bf16 v[84:87], v[124:127], v[188:191], v[84:87]
	v_mfma_f32_16x16x32_bf16 v[88:91], v[132:135], v[188:191], v[88:91]
	v_mfma_f32_16x16x32_bf16 v[92:95], v[124:127], v[196:199], v[92:95]
	v_mfma_f32_16x16x32_bf16 v[96:99], v[132:135], v[196:199], v[96:99]
	s_waitcnt lgkmcnt(0)
	v_mfma_f32_16x16x32_bf16 v[100:103], v[124:127], v[204:207], v[100:103]
	v_mfma_f32_16x16x32_bf16 v[104:107], v[132:135], v[204:207], v[104:107]
	v_mfma_f32_16x16x32_bf16 v[108:111], v[136:139], v[176:179], v[108:111]
	v_mfma_f32_16x16x32_bf16 v[44:47], v[168:171], v[176:179], v[44:47]
	v_mfma_f32_16x16x32_bf16 v[48:51], v[136:139], v[184:187], v[48:51]
	v_mfma_f32_16x16x32_bf16 v[52:55], v[168:171], v[184:187], v[52:55]
	v_mfma_f32_16x16x32_bf16 v[56:59], v[136:139], v[192:195], v[56:59]
	v_mfma_f32_16x16x32_bf16 v[60:63], v[168:171], v[192:195], v[60:63]
	v_mfma_f32_16x16x32_bf16 v[64:67], v[136:139], v[200:203], v[64:67]
	v_mfma_f32_16x16x32_bf16 v[68:71], v[168:171], v[200:203], v[68:71]
	v_mfma_f32_16x16x32_bf16 v[108:111], v[140:143], v[180:183], v[108:111]
	v_mfma_f32_16x16x32_bf16 v[44:47], v[172:175], v[180:183], v[44:47]
	v_mfma_f32_16x16x32_bf16 v[48:51], v[140:143], v[188:191], v[48:51]
	v_mfma_f32_16x16x32_bf16 v[52:55], v[172:175], v[188:191], v[52:55]
	v_mfma_f32_16x16x32_bf16 v[56:59], v[140:143], v[196:199], v[56:59]
	v_mfma_f32_16x16x32_bf16 v[60:63], v[172:175], v[196:199], v[60:63]
	v_mfma_f32_16x16x32_bf16 v[64:67], v[140:143], v[204:207], v[64:67]
	v_mfma_f32_16x16x32_bf16 v[68:71], v[172:175], v[204:207], v[68:71]
	s_barrier
; #define PG8_STAGE(bufoff, goff, voff) do { _Pragma("unroll") for (int _i = 0; _i < 2; ++_i) \
;         __builtin_amdgcn_raw_ptr_buffer_load_lds(R_##voff, (LAS void*)(lds + (bufoff) + ldsw + _i * 8192), 16, (int)(voff)[_i], (int)(goff), 0, 0); } while (0)
; #define PG8_WAIT_V(n) asm volatile("s_waitcnt vmcnt(" #n ")" ::: "memory")
; #define PG8_WAIT_L(n) asm volatile("s_waitcnt lgkmcnt(" #n ")" ::: "memory")
; #define PG8_BAR __builtin_amdgcn_s_barrier()
; #define PG8_SCHED __builtin_amdgcn_sched_barrier(0)
; template <class Epi, class Sched, bool ALIGN_EPI, bool SP2>
; __device__ __forceinline__ void gemm_phase(LAS unsigned char* lds, const Gemm g, const Sched& S, const Epi& E, int tid_in) {
;     ...
;             PG8_LDB(B0, 0, 0); PG8_LDB(B1, 0, 1); PG8_SCHED; PG8_LDA(At, 0, 0); PG8_STAGE(PG8_SA(1, 1), a1 + hstepA, voffA);
;             PG8_WAIT_V(8); PG8_WAIT_L(0); PG8_BAR; PG8_MMA(0, 0, At, B0); PG8_MMA(0, 1, At, B1); PG8_BAR; PG8_SCHED;
;             PG8_LDA(At, 0, 1); PG8_STAGE(PG8_SB(0, 0), b2, voffB); PG8_STAGE(PG8_SB(0, 1), b2 + hstepB, voffB); PG8_STAGE(PG8_SA(0, 0), a2, voffA);
;             PG8_WAIT_V(8); PG8_WAIT_L(0); PG8_BAR; PG8_MMA(1, 0, At, B0); PG8_MMA(1, 1, At, B1); PG8_BAR; PG8_SCHED;
;             PG8_LDB(B0, 1, 0); PG8_LDB(B1, 1, 1); PG8_SCHED; PG8_LDA(At, 1, 0); PG8_STAGE(PG8_SA(0, 1), a2 + hstepA, voffA);
;             PG8_WAIT_V(8); PG8_WAIT_L(0); PG8_BAR; PG8_MMA(0, 0, At, B0); PG8_MMA(0, 1, At, B1); PG8_BAR; PG8_SCHED;
;             PG8_LDA(At, 1, 1); PG8_STAGE(PG8_SB(1, 0), b3, voffB); PG8_STAGE(PG8_SB(1, 1), b3 + hstepB, voffB); PG8_STAGE(PG8_SA(1, 0), a3, voffA);
;             PG8_WAIT_V(8); PG8_WAIT_L(0); PG8_BAR; PG8_MMA(1, 0, At, B0); PG8_MMA(1, 1, At, B1); PG8_BAR; PG8_SCHED;
	s_mov_b32 m0, s50
	s_movk_i32 s14, 0x280
	ds_read_b128 v[176:179], v5 offset:49152
	ds_read_b128 v[180:183], v5 offset:50176
	ds_read_b128 v[184:187], v5 offset:51200
	ds_read_b128 v[188:191], v5 offset:52224
	ds_read_b128 v[192:195], v5 offset:53248
	ds_read_b128 v[196:199], v5 offset:54272
	ds_read_b128 v[200:203], v5 offset:55296
	ds_read_b128 v[204:207], v5 offset:56320
	buffer_load_dwordx4 v2, s[84:87], s14 offen lds
	s_mov_b32 m0, s52
	s_nop 0
	buffer_load_dwordx4 v4, s[84:87], s14 offen lds
	s_mov_b32 m0, s57
	s_movk_i32 s14, 0x6280
	buffer_load_dwordx4 v2, s[84:87], s14 offen lds
	s_mov_b32 m0, s65
	s_nop 0
	buffer_load_dwordx4 v4, s[84:87], s14 offen lds
	s_mov_b32 m0, s17
	s_nop 0
	buffer_load_dwordx4 v0, s[36:39], s15 offen lds
	s_mov_b32 m0, s34
	s_nop 0
	buffer_load_dwordx4 v3, s[36:39], s15 offen lds
	s_waitcnt vmcnt(8)
	s_waitcnt lgkmcnt(0)
	s_barrier
	s_waitcnt lgkmcnt(7)
	v_mfma_f32_16x16x32_bf16 v[144:147], v[120:123], v[176:179], v[144:147]
	v_mfma_f32_16x16x32_bf16 v[148:151], v[128:131], v[176:179], v[148:151]
	s_waitcnt lgkmcnt(5)
	v_mfma_f32_16x16x32_bf16 v[152:155], v[120:123], v[184:187], v[152:155]
	v_mfma_f32_16x16x32_bf16 v[156:159], v[128:131], v[184:187], v[156:159]
	s_waitcnt lgkmcnt(3)
	v_mfma_f32_16x16x32_bf16 v[160:163], v[120:123], v[192:195], v[160:163]
	v_mfma_f32_16x16x32_bf16 v[164:167], v[128:131], v[192:195], v[164:167]
	s_waitcnt lgkmcnt(1)
	v_mfma_f32_16x16x32_bf16 v[12:15], v[120:123], v[200:203], v[12:15]
	v_mfma_f32_16x16x32_bf16 v[16:19], v[128:131], v[200:203], v[16:19]
	v_mfma_f32_16x16x32_bf16 v[144:147], v[124:127], v[180:183], v[144:147]
	v_mfma_f32_16x16x32_bf16 v[148:151], v[132:135], v[180:183], v[148:151]
	v_mfma_f32_16x16x32_bf16 v[152:155], v[124:127], v[188:191], v[152:155]
	v_mfma_f32_16x16x32_bf16 v[156:159], v[132:135], v[188:191], v[156:159]
	v_mfma_f32_16x16x32_bf16 v[160:163], v[124:127], v[196:199], v[160:163]
	v_mfma_f32_16x16x32_bf16 v[164:167], v[132:135], v[196:199], v[164:167]
	s_waitcnt lgkmcnt(0)
	v_mfma_f32_16x16x32_bf16 v[12:15], v[124:127], v[204:207], v[12:15]
	v_mfma_f32_16x16x32_bf16 v[16:19], v[132:135], v[204:207], v[16:19]
	v_mfma_f32_16x16x32_bf16 v[20:23], v[136:139], v[176:179], v[20:23]
	v_mfma_f32_16x16x32_bf16 v[24:27], v[168:171], v[176:179], v[24:27]
	v_mfma_f32_16x16x32_bf16 v[36:39], v[136:139], v[184:187], v[36:39]
	v_mfma_f32_16x16x32_bf16 v[40:43], v[168:171], v[184:187], v[40:43]
	v_mfma_f32_16x16x32_bf16 v[72:75], v[136:139], v[192:195], v[72:75]
	v_mfma_f32_16x16x32_bf16 v[116:119], v[168:171], v[192:195], v[116:119]
	v_mfma_f32_16x16x32_bf16 v[28:31], v[136:139], v[200:203], v[28:31]
	v_mfma_f32_16x16x32_bf16 v[32:35], v[168:171], v[200:203], v[32:35]
	v_mfma_f32_16x16x32_bf16 v[20:23], v[140:143], v[180:183], v[20:23]
	v_mfma_f32_16x16x32_bf16 v[24:27], v[172:175], v[180:183], v[24:27]
	v_mfma_f32_16x16x32_bf16 v[36:39], v[140:143], v[188:191], v[36:39]
	v_mfma_f32_16x16x32_bf16 v[40:43], v[172:175], v[188:191], v[40:43]
	v_mfma_f32_16x16x32_bf16 v[72:75], v[140:143], v[196:199], v[72:75]
	v_mfma_f32_16x16x32_bf16 v[116:119], v[172:175], v[196:199], v[116:119]
	v_mfma_f32_16x16x32_bf16 v[28:31], v[140:143], v[204:207], v[28:31]
	v_mfma_f32_16x16x32_bf16 v[32:35], v[172:175], v[204:207], v[32:35]
	s_barrier
	ds_read_b128 v[120:123], v9
	ds_read_b128 v[124:127], v9 offset:1024
	ds_read_b128 v[128:131], v9 offset:2048
	ds_read_b128 v[132:135], v9 offset:3072
	ds_read_b128 v[136:139], v8
	ds_read_b128 v[140:143], v8 offset:1024
	ds_read_b128 v[168:171], v8 offset:2048
	ds_read_b128 v[172:175], v8 offset:3072
	s_add_i32 s14, s13, 0x18280
	s_mov_b32 m0, s73
	ds_read_b128 v[176:179], v5
	ds_read_b128 v[180:183], v5 offset:1024
	ds_read_b128 v[184:187], v5 offset:2048
	ds_read_b128 v[188:191], v5 offset:3072
	ds_read_b128 v[192:195], v5 offset:4096
	ds_read_b128 v[196:199], v5 offset:5120
	ds_read_b128 v[200:203], v5 offset:6144
	ds_read_b128 v[204:207], v5 offset:7168
	buffer_load_dwordx4 v0, s[36:39], s14 offen lds
	s_mov_b32 m0, s25
	s_nop 0
	buffer_load_dwordx4 v3, s[36:39], s14 offen lds
	s_waitcnt vmcnt(8)
	s_waitcnt lgkmcnt(0)
	s_barrier
	s_waitcnt lgkmcnt(7)
	v_mfma_f32_16x16x32_bf16 v[76:79], v[120:123], v[176:179], v[76:79]
	v_mfma_f32_16x16x32_bf16 v[80:83], v[128:131], v[176:179], v[80:83]
	s_waitcnt lgkmcnt(5)
	v_mfma_f32_16x16x32_bf16 v[84:87], v[120:123], v[184:187], v[84:87]
	v_mfma_f32_16x16x32_bf16 v[88:91], v[128:131], v[184:187], v[88:91]
	s_waitcnt lgkmcnt(3)
	v_mfma_f32_16x16x32_bf16 v[92:95], v[120:123], v[192:195], v[92:95]
	v_mfma_f32_16x16x32_bf16 v[96:99], v[128:131], v[192:195], v[96:99]
	s_waitcnt lgkmcnt(1)
	v_mfma_f32_16x16x32_bf16 v[100:103], v[120:123], v[200:203], v[100:103]
	v_mfma_f32_16x16x32_bf16 v[104:107], v[128:131], v[200:203], v[104:107]
	v_mfma_f32_16x16x32_bf16 v[76:79], v[124:127], v[180:183], v[76:79]
	v_mfma_f32_16x16x32_bf16 v[80:83], v[132:135], v[180:183], v[80:83]
	v_mfma_f32_16x16x32_bf16 v[84:87], v[124:127], v[188:191], v[84:87]
	v_mfma_f32_16x16x32_bf16 v[88:91], v[132:135], v[188:191], v[88:91]
	v_mfma_f32_16x16x32_bf16 v[92:95], v[124:127], v[196:199], v[92:95]
	v_mfma_f32_16x16x32_bf16 v[96:99], v[132:135], v[196:199], v[96:99]
	s_waitcnt lgkmcnt(0)
	v_mfma_f32_16x16x32_bf16 v[100:103], v[124:127], v[204:207], v[100:103]
	v_mfma_f32_16x16x32_bf16 v[104:107], v[132:135], v[204:207], v[104:107]
	v_mfma_f32_16x16x32_bf16 v[108:111], v[136:139], v[176:179], v[108:111]
	v_mfma_f32_16x16x32_bf16 v[44:47], v[168:171], v[176:179], v[44:47]
	v_mfma_f32_16x16x32_bf16 v[48:51], v[136:139], v[184:187], v[48:51]
	v_mfma_f32_16x16x32_bf16 v[52:55], v[168:171], v[184:187], v[52:55]
	v_mfma_f32_16x16x32_bf16 v[56:59], v[136:139], v[192:195], v[56:59]
	v_mfma_f32_16x16x32_bf16 v[60:63], v[168:171], v[192:195], v[60:63]
	v_mfma_f32_16x16x32_bf16 v[64:67], v[136:139], v[200:203], v[64:67]
	v_mfma_f32_16x16x32_bf16 v[68:71], v[168:171], v[200:203], v[68:71]
	v_mfma_f32_16x16x32_bf16 v[108:111], v[140:143], v[180:183], v[108:111]
	v_mfma_f32_16x16x32_bf16 v[44:47], v[172:175], v[180:183], v[44:47]
	v_mfma_f32_16x16x32_bf16 v[48:51], v[140:143], v[188:191], v[48:51]
	v_mfma_f32_16x16x32_bf16 v[52:55], v[172:175], v[188:191], v[52:55]
	v_mfma_f32_16x16x32_bf16 v[56:59], v[140:143], v[196:199], v[56:59]
	v_mfma_f32_16x16x32_bf16 v[60:63], v[172:175], v[196:199], v[60:63]
	v_mfma_f32_16x16x32_bf16 v[64:67], v[140:143], v[204:207], v[64:67]
	v_mfma_f32_16x16x32_bf16 v[68:71], v[172:175], v[204:207], v[68:71]
	s_barrier
; #define PG8_STAGE(bufoff, goff, voff) do { _Pragma("unroll") for (int _i = 0; _i < 2; ++_i) \
;         __builtin_amdgcn_raw_ptr_buffer_load_lds(R_##voff, (LAS void*)(lds + (bufoff) + ldsw + _i * 8192), 16, (int)(voff)[_i], (int)(goff), 0, 0); } while (0)
; #define PG8_WAIT_V(n) asm volatile("s_waitcnt vmcnt(" #n ")" ::: "memory")
; #define PG8_WAIT_L(n) asm volatile("s_waitcnt lgkmcnt(" #n ")" ::: "memory")
; #define PG8_BAR __builtin_amdgcn_s_barrier()
; #define PG8_SCHED __builtin_amdgcn_sched_barrier(0)
; template <class Epi, class Sched, bool ALIGN_EPI, bool SP2>
; __device__ __forceinline__ void gemm_phase(LAS unsigned char* lds, const Gemm g, const Sched& S, const Epi& E, int tid_in) {
;     ...
;             PG8_LDB(B0, 0, 0); PG8_LDB(B1, 0, 1); PG8_SCHED; PG8_LDA(At, 0, 0); PG8_STAGE(PG8_SA(1, 1), a1 + hstepA, voffA);
;             PG8_WAIT_V(8); PG8_WAIT_L(0); PG8_BAR; PG8_MMA(0, 0, At, B0); PG8_MMA(0, 1, At, B1); PG8_BAR; PG8_SCHED;
;             PG8_LDA(At, 0, 1); PG8_STAGE(PG8_SB(0, 0), b2, voffB); PG8_STAGE(PG8_SB(0, 1), b2 + hstepB, voffB); PG8_STAGE(PG8_SA(0, 0), a2, voffA);
;             PG8_WAIT_V(8); PG8_WAIT_L(0); PG8_BAR; PG8_MMA(1, 0, At, B0); PG8_MMA(1, 1, At, B1); PG8_BAR; PG8_SCHED;
;             PG8_LDB(B0, 1, 0); PG8_LDB(B1, 1, 1); PG8_SCHED; PG8_LDA(At, 1, 0); PG8_STAGE(PG8_SA(0, 1), a2 + hstepA, voffA);
;             PG8_WAIT_V(8); PG8_WAIT_L(0); PG8_BAR; PG8_MMA(0, 0, At, B0); PG8_MMA(0, 1, At, B1); PG8_BAR; PG8_SCHED;
;             PG8_LDA(At, 1, 1); PG8_STAGE(PG8_SB(1, 0), b3, voffB); PG8_STAGE(PG8_SB(1, 1), b3 + hstepB, voffB); PG8_STAGE(PG8_SA(1, 0), a3, voffA);
;             PG8_WAIT_V(8); PG8_WAIT_L(0); PG8_BAR; PG8_MMA(1, 0, At, B0); PG8_MMA(1, 1, At, B1); PG8_BAR; PG8_SCHED;
	s_mov_b32 m0, s68
	ds_read_b128 v[176:179], v5 offset:16384
	ds_read_b128 v[180:183], v5 offset:17408
	ds_read_b128 v[184:187], v5 offset:18432
	ds_read_b128 v[188:191], v5 offset:19456
	ds_read_b128 v[192:195], v5 offset:20480
	ds_read_b128 v[196:199], v5 offset:21504
	ds_read_b128 v[200:203], v5 offset:22528
	ds_read_b128 v[204:207], v5 offset:23552
	buffer_load_dwordx4 v2, s[84:87], 0 offen lds
	s_mov_b32 m0, s69
	s_movk_i32 s14, 0x6000
	buffer_load_dwordx4 v4, s[84:87], 0 offen lds
	s_mov_b32 m0, s70
	s_nop 0
	buffer_load_dwordx4 v2, s[84:87], s14 offen lds
	s_mov_b32 m0, s71
	s_nop 0
	buffer_load_dwordx4 v4, s[84:87], s14 offen lds
	s_mov_b32 m0, s56
	s_nop 0
	buffer_load_dwordx4 v0, s[36:39], s13 offen lds
	s_mov_b32 m0, s72
	s_nop 0
	buffer_load_dwordx4 v3, s[36:39], s13 offen lds
	s_waitcnt vmcnt(8)
	s_waitcnt lgkmcnt(0)
	s_barrier
	s_waitcnt lgkmcnt(7)
	v_mfma_f32_16x16x32_bf16 v[144:147], v[120:123], v[176:179], v[144:147]
	s_waitcnt lgkmcnt(6)
	v_mfma_f32_16x16x32_bf16 v[208:211], v[124:127], v[180:183], v[144:147]
	v_mfma_f32_16x16x32_bf16 v[144:147], v[128:131], v[176:179], v[148:151]
	v_mfma_f32_16x16x32_bf16 v[148:151], v[132:135], v[180:183], v[144:147]
	s_waitcnt lgkmcnt(5)
	v_mfma_f32_16x16x32_bf16 v[144:147], v[120:123], v[184:187], v[152:155]
	s_waitcnt lgkmcnt(4)
	v_mfma_f32_16x16x32_bf16 v[220:223], v[124:127], v[188:191], v[144:147]
	v_mfma_f32_16x16x32_bf16 v[144:147], v[128:131], v[184:187], v[156:159]
	v_mfma_f32_16x16x32_bf16 v[224:227], v[132:135], v[188:191], v[144:147]
	s_waitcnt lgkmcnt(3)
	v_mfma_f32_16x16x32_bf16 v[144:147], v[120:123], v[192:195], v[160:163]
	s_waitcnt lgkmcnt(2)
	v_mfma_f32_16x16x32_bf16 v[160:163], v[124:127], v[196:199], v[144:147]
	v_mfma_f32_16x16x32_bf16 v[144:147], v[128:131], v[192:195], v[164:167]
	s_waitcnt lgkmcnt(1)
	v_mfma_f32_16x16x32_bf16 v[12:15], v[120:123], v[200:203], v[12:15]
	v_mfma_f32_16x16x32_bf16 v[16:19], v[128:131], v[200:203], v[16:19]
	v_mfma_f32_16x16x32_bf16 v[228:231], v[132:135], v[196:199], v[144:147]
	s_waitcnt lgkmcnt(0)
	v_mfma_f32_16x16x32_bf16 v[12:15], v[124:127], v[204:207], v[12:15]
	v_mfma_f32_16x16x32_bf16 v[16:19], v[132:135], v[204:207], v[16:19]
	v_mfma_f32_16x16x32_bf16 v[20:23], v[136:139], v[176:179], v[20:23]
	v_mfma_f32_16x16x32_bf16 v[124:127], v[140:143], v[180:183], v[20:23]
	v_mfma_f32_16x16x32_bf16 v[20:23], v[168:171], v[176:179], v[24:27]
	v_mfma_f32_16x16x32_bf16 v[238:241], v[172:175], v[180:183], v[20:23]
	v_mfma_f32_16x16x32_bf16 v[20:23], v[136:139], v[184:187], v[36:39]
	v_mfma_f32_16x16x32_bf16 v[36:39], v[140:143], v[188:191], v[20:23]
	v_mfma_f32_16x16x32_bf16 v[20:23], v[168:171], v[184:187], v[40:43]
	v_mfma_f32_16x16x32_bf16 v[184:187], v[172:175], v[188:191], v[20:23]
	v_mfma_f32_16x16x32_bf16 v[20:23], v[136:139], v[192:195], v[72:75]
	v_mfma_f32_16x16x32_bf16 v[188:191], v[140:143], v[196:199], v[20:23]
	v_mfma_f32_16x16x32_bf16 v[20:23], v[168:171], v[192:195], v[116:119]
	v_mfma_f32_16x16x32_bf16 v[192:195], v[172:175], v[196:199], v[20:23]
	v_mfma_f32_16x16x32_bf16 v[20:23], v[136:139], v[200:203], v[28:31]
	v_mfma_f32_16x16x32_bf16 v[26:29], v[140:143], v[204:207], v[20:23]
	v_mfma_f32_16x16x32_bf16 v[20:23], v[168:171], v[200:203], v[32:35]
	v_mfma_f32_16x16x32_bf16 v[30:33], v[172:175], v[204:207], v[20:23]
	s_barrier
	s_nop 4
	ds_read_b128 v[20:23], v7
	ds_read_b128 v[136:139], v7 offset:1024
	ds_read_b128 v[172:175], v7 offset:2048
	ds_read_b128 v[196:199], v7 offset:3072
	ds_read_b128 v[200:203], v6
	ds_read_b128 v[204:207], v6 offset:1024
	ds_read_b128 v[242:245], v6 offset:2048
	ds_read_b128 v[246:249], v6 offset:3072
	s_mov_b32 m0, s30
	ds_read_b128 v[6:9], v5 offset:32768
	ds_read_b128 v[40:43], v5 offset:33792
	ds_read_b128 v[72:75], v5 offset:34816
	ds_read_b128 v[128:131], v5 offset:35840
	ds_read_b128 v[250:253], v5 offset:36864
	ds_read_b128 v[212:215], v5 offset:37888
	ds_read_b128 v[216:219], v5 offset:38912
	ds_read_b128 v[234:237], v5 offset:39936
	buffer_load_dwordx4 v0, s[36:39], s10 offen lds
	s_mov_b32 m0, s31
	s_nop 0
	buffer_load_dwordx4 v3, s[36:39], s10 offen lds
	s_waitcnt vmcnt(8)
	s_waitcnt lgkmcnt(0)
	s_barrier
	s_waitcnt lgkmcnt(5)
	v_mfma_f32_16x16x32_bf16 v[84:87], v[20:23], v[72:75], v[84:87]
	s_waitcnt lgkmcnt(4)
	v_mfma_f32_16x16x32_bf16 v[168:171], v[136:139], v[128:131], v[84:87]
	v_mfma_f32_16x16x32_bf16 v[84:87], v[172:175], v[72:75], v[88:91]
	v_mfma_f32_16x16x32_bf16 v[164:167], v[196:199], v[128:131], v[84:87]
	s_waitcnt lgkmcnt(3)
	v_mfma_f32_16x16x32_bf16 v[84:87], v[20:23], v[250:253], v[92:95]
	s_waitcnt lgkmcnt(2)
	v_mfma_f32_16x16x32_bf16 v[144:147], v[136:139], v[212:215], v[84:87]
	v_mfma_f32_16x16x32_bf16 v[84:87], v[172:175], v[250:253], v[96:99]
	v_mfma_f32_16x16x32_bf16 v[140:143], v[196:199], v[212:215], v[84:87]
	s_waitcnt lgkmcnt(1)
	v_mfma_f32_16x16x32_bf16 v[84:87], v[20:23], v[216:219], v[100:103]
	v_mfma_f32_16x16x32_bf16 v[76:79], v[20:23], v[6:9], v[76:79]
	v_mfma_f32_16x16x32_bf16 v[80:83], v[172:175], v[6:9], v[80:83]
	s_waitcnt lgkmcnt(0)
	v_mfma_f32_16x16x32_bf16 v[120:123], v[136:139], v[234:237], v[84:87]
	v_mfma_f32_16x16x32_bf16 v[84:87], v[172:175], v[216:219], v[104:107]
	v_mfma_f32_16x16x32_bf16 v[76:79], v[136:139], v[40:43], v[76:79]
	v_mfma_f32_16x16x32_bf16 v[80:83], v[196:199], v[40:43], v[80:83]
	v_mfma_f32_16x16x32_bf16 v[116:119], v[196:199], v[234:237], v[84:87]
	v_mfma_f32_16x16x32_bf16 v[84:87], v[200:203], v[6:9], v[108:111]
	v_mfma_f32_16x16x32_bf16 v[6:9], v[242:245], v[6:9], v[44:47]
	v_mfma_f32_16x16x32_bf16 v[176:179], v[246:249], v[40:43], v[6:9]
	v_mfma_f32_16x16x32_bf16 v[6:9], v[200:203], v[72:75], v[48:51]
	v_mfma_f32_16x16x32_bf16 v[156:159], v[204:207], v[128:131], v[6:9]
	v_mfma_f32_16x16x32_bf16 v[6:9], v[242:245], v[72:75], v[52:55]
	v_mfma_f32_16x16x32_bf16 v[152:155], v[246:249], v[128:131], v[6:9]
	v_mfma_f32_16x16x32_bf16 v[6:9], v[200:203], v[250:253], v[56:59]
	v_mfma_f32_16x16x32_bf16 v[132:135], v[204:207], v[212:215], v[6:9]
	v_mfma_f32_16x16x32_bf16 v[6:9], v[242:245], v[250:253], v[60:63]
	v_mfma_f32_16x16x32_bf16 v[128:131], v[246:249], v[212:215], v[6:9]
	v_mfma_f32_16x16x32_bf16 v[6:9], v[200:203], v[216:219], v[64:67]
	v_mfma_f32_16x16x32_bf16 v[106:109], v[204:207], v[234:237], v[6:9]
	v_mfma_f32_16x16x32_bf16 v[6:9], v[242:245], v[216:219], v[68:71]
	v_mfma_f32_16x16x32_bf16 v[180:183], v[204:207], v[40:43], v[84:87]
	v_mfma_f32_16x16x32_bf16 v[102:105], v[246:249], v[234:237], v[6:9]
	s_barrier
; #define PG8_STAGE(bufoff, goff, voff) do { _Pragma("unroll") for (int _i = 0; _i < 2; ++_i) \
;         __builtin_amdgcn_raw_ptr_buffer_load_lds(R_##voff, (LAS void*)(lds + (bufoff) + ldsw + _i * 8192), 16, (int)(voff)[_i], (int)(goff), 0, 0); } while (0)
; #define PG8_WAIT_V(n) asm volatile("s_waitcnt vmcnt(" #n ")" ::: "memory")
; template <class Epi, class Sched, bool ALIGN_EPI, bool SP2>
; __device__ __forceinline__ void gemm_phase(LAS unsigned char* lds, const Gemm g, const Sched& S, const Epi& E, int tid_in) {
;     ...
;             PG8_LDA(At, 1, 1); PG8_STAGE(PG8_SB(1, 0), b3, voffB); PG8_STAGE(PG8_SB(1, 1), b3 + hstepB, voffB); PG8_STAGE(PG8_SA(1, 0), a3, voffA);
;             PG8_WAIT_V(8); PG8_WAIT_L(0); PG8_BAR; PG8_MMA(1, 0, At, B0); PG8_MMA(1, 1, At, B1); PG8_BAR; PG8_SCHED;
;     __device__ __forceinline__ void operator()(const Acc& acc, const Unit& u, int wr, int wc, int fr, int fq) const {
;         asm volatile("" : "+v"(fr), "+v"(fq));
;         const int h0 = 8 * (fq & 1), row0 = u.pm * 256 + wr * 64 + fr, colb = wc * 64 + 8 * fq;
;         const f32x4 d0 = *(const f32x4*)(dsk + h0), d1 = *(const f32x4*)(dsk + h0 + 4);
;         u32x4 urow[8][2];
; #pragma unroll
;         for (int idx = 0; idx < 8; ++idx) { const size_t ro = (size_t)(row0 + (idx >> 2) * 128 + (idx & 3) * 16) * A2LD + colb; urow[idx][0] = *(const u32x4*)(a2g + ro); urow[idx][1] = *(const u32x4*)(a2g + ro + 32); }
;         asm volatile("" ::: "memory");
; #pragma unroll
;         for (int idx = 0; idx < 8; ++idx) { const int ai = idx >> 2, m = idx & 3, row = row0 + ai * 128 + m * 16;
; #pragma unroll
;             for (int bj = 0; bj < 2; ++bj) { const int col = bj * 32 + colb, tl = col >> 4;
;                 const u32x4 uu = urow[idx][bj];
;                 const f32x4 a = acc[ai][bj][m][0], b = acc[ai][bj][m][1];
;                 f32x2 y0 = (f32x2){a[0], a[1]} + (f32x2){d0[0], d0[1]} * (f32x2){bf2f(uu.x & 0xffffu), bf2f(uu.x >> 16)}, y1 = (f32x2){a[2], a[3]} + (f32x2){d0[2], d0[3]} * (f32x2){bf2f(uu.y & 0xffffu), bf2f(uu.y >> 16)};
;                 f32x2 y2 = (f32x2){b[0], b[1]} + (f32x2){d1[0], d1[1]} * (f32x2){bf2f(uu.z & 0xffffu), bf2f(uu.z >> 16)}, y3 = (f32x2){b[2], b[3]} + (f32x2){d1[2], d1[3]} * (f32x2){bf2f(uu.w & 0xffffu), bf2f(uu.w >> 16)};
;                 y0 = gelu_tanh2(y0); y1 = gelu_tanh2(y1); y2 = gelu_tanh2(y2); y3 = gelu_tanh2(y3);
	s_mov_b32 m0, s50
	s_nop 2
	ds_read_b128 v[6:9], v5 offset:49152
	ds_read_b128 v[50:53], v5 offset:50176
	ds_read_b128 v[54:57], v5 offset:51200
	ds_read_b128 v[58:61], v5 offset:52224
	ds_read_b128 v[98:101], v5 offset:53248
	ds_read_b128 v[110:113], v5 offset:54272
	ds_read_b128 v[212:215], v5 offset:55296
	ds_read_b128 v[216:219], v5 offset:56320
	buffer_load_dwordx4 v2, s[84:87], s74 offen lds
	s_mov_b32 m0, s52
	s_nop 0
	buffer_load_dwordx4 v4, s[84:87], s74 offen lds
	s_mov_b32 m0, s57
	s_nop 0
	buffer_load_dwordx4 v2, s[84:87], s75 offen lds
	s_mov_b32 m0, s65
	s_nop 0
	buffer_load_dwordx4 v4, s[84:87], s75 offen lds
	s_mov_b32 m0, s17
	s_nop 0
	buffer_load_dwordx4 v0, s[36:39], s12 offen lds
	s_mov_b32 m0, s34
	s_nop 0
	buffer_load_dwordx4 v3, s[36:39], s12 offen lds
	s_waitcnt vmcnt(8)
	s_waitcnt lgkmcnt(0)
	s_barrier
	s_waitcnt lgkmcnt(7)
	v_mfma_f32_16x16x32_bf16 v[2:5], v[20:23], v[6:9], v[208:211]
	s_waitcnt lgkmcnt(6)
	v_mfma_f32_16x16x32_bf16 v[94:97], v[136:139], v[50:53], v[2:5]
	v_mfma_f32_16x16x32_bf16 v[2:5], v[172:175], v[6:9], v[148:151]
	v_mfma_f32_16x16x32_bf16 v[90:93], v[196:199], v[50:53], v[2:5]
	s_waitcnt lgkmcnt(5)
	v_mfma_f32_16x16x32_bf16 v[2:5], v[20:23], v[54:57], v[220:223]
	s_waitcnt lgkmcnt(4)
	v_mfma_f32_16x16x32_bf16 v[70:73], v[136:139], v[58:61], v[2:5]
	v_mfma_f32_16x16x32_bf16 v[2:5], v[172:175], v[54:57], v[224:227]
	v_mfma_f32_16x16x32_bf16 v[66:69], v[196:199], v[58:61], v[2:5]
	s_waitcnt lgkmcnt(3)
	v_mfma_f32_16x16x32_bf16 v[2:5], v[20:23], v[98:101], v[160:163]
	s_waitcnt lgkmcnt(2)
	v_mfma_f32_16x16x32_bf16 v[46:49], v[136:139], v[110:113], v[2:5]
	v_mfma_f32_16x16x32_bf16 v[2:5], v[172:175], v[98:101], v[228:231]
	v_mfma_f32_16x16x32_bf16 v[42:45], v[196:199], v[110:113], v[2:5]
	s_waitcnt lgkmcnt(1)
	v_mfma_f32_16x16x32_bf16 v[2:5], v[20:23], v[212:215], v[12:15]
	s_waitcnt lgkmcnt(0)
	v_mfma_f32_16x16x32_bf16 v[22:25], v[136:139], v[216:219], v[2:5]
	v_mfma_f32_16x16x32_bf16 v[2:5], v[172:175], v[212:215], v[16:19]
	v_mfma_f32_16x16x32_bf16 v[18:21], v[196:199], v[216:219], v[2:5]
	v_mfma_f32_16x16x32_bf16 v[2:5], v[200:203], v[6:9], v[124:127]
	v_mfma_f32_16x16x32_bf16 v[86:89], v[204:207], v[50:53], v[2:5]
	v_mfma_f32_16x16x32_bf16 v[2:5], v[242:245], v[6:9], v[238:241]
	v_mfma_f32_16x16x32_bf16 v[208:211], v[246:249], v[50:53], v[2:5]
	v_mfma_f32_16x16x32_bf16 v[2:5], v[200:203], v[54:57], v[36:39]
	v_mfma_f32_16x16x32_bf16 v[62:65], v[204:207], v[58:61], v[2:5]
	v_mfma_f32_16x16x32_bf16 v[2:5], v[242:245], v[54:57], v[184:187]
	v_mfma_f32_16x16x32_bf16 v[58:61], v[246:249], v[58:61], v[2:5]
	v_mfma_f32_16x16x32_bf16 v[2:5], v[200:203], v[98:101], v[188:191]
	v_mfma_f32_16x16x32_bf16 v[38:41], v[204:207], v[110:113], v[2:5]
	v_mfma_f32_16x16x32_bf16 v[2:5], v[242:245], v[98:101], v[192:195]
	v_mfma_f32_16x16x32_bf16 v[34:37], v[246:249], v[110:113], v[2:5]
	v_mfma_f32_16x16x32_bf16 v[2:5], v[200:203], v[212:215], v[26:29]
	v_mfma_f32_16x16x32_bf16 v[6:9], v[204:207], v[216:219], v[2:5]
	v_mfma_f32_16x16x32_bf16 v[2:5], v[242:245], v[212:215], v[30:33]
	v_mfma_f32_16x16x32_bf16 v[2:5], v[246:249], v[216:219], v[2:5]
	s_barrier
	s_lshl_b32 s7, s7, 8
	v_lshlrev_b32_e32 v0, 3, v11
	v_lshl_add_u32 v192, s5, 6, v0
	s_add_i32 s11, s11, s7
	v_ashrrev_i32_e32 v193, 31, v192
	v_add_u32_e32 v30, s11, v10
	v_lshl_add_u64 v[26:27], v[192:193], 1, s[46:47]
	s_movk_i32 s5, 0x300
	v_mad_i64_i32 v[28:29], s[10:11], v30, s5, v[26:27]
	v_and_b32_e32 v0, 8, v0
	global_load_dwordx4 v[202:205], v[28:29], off
	v_lshlrev_b32_e32 v10, 2, v0
	global_load_dwordx4 v[14:17], v10, s[66:67]
	s_nop 0
	global_load_dwordx4 v[10:13], v10, s[66:67] offset:16
	s_mov_b32 s10, 0xc0135761
	v_add_u32_e32 v31, 16, v30
	v_add_u32_e32 v32, 32, v30
	v_add_u32_e32 v50, 48, v30
	v_add_u32_e32 v52, 0x80, v30
	v_add_u32_e32 v54, 0x90, v30
	v_add_u32_e32 v56, 0xa0, v30
	v_add_u32_e32 v57, 0xb0, v30
	v_mov_b64_e32 v[188:189], s[10:11]
	v_lshlrev_b32_e32 v193, 4, v30
	v_mad_i64_i32 v[30:31], s[10:11], v31, s5, v[26:27]
	v_mad_i64_i32 v[32:33], s[10:11], v32, s5, v[26:27]
	v_mad_i64_i32 v[50:51], s[10:11], v50, s5, v[26:27]
	v_mad_i64_i32 v[52:53], s[10:11], v52, s5, v[26:27]
	v_mad_i64_i32 v[54:55], s[10:11], v54, s5, v[26:27]
	v_mad_i64_i32 v[74:75], s[10:11], v56, s5, v[26:27]
	v_mad_i64_i32 v[26:27], s[10:11], v57, s5, v[26:27]
	global_load_dwordx4 v[212:215], v[28:29], off offset:64
	global_load_dwordx4 v[184:187], v[30:31], off
	global_load_dwordx4 v[172:175], v[30:31], off offset:64
	global_load_dwordx4 v[160:163], v[32:33], off
	global_load_dwordx4 v[148:151], v[32:33], off offset:64
	global_load_dwordx4 v[136:139], v[50:51], off
	global_load_dwordx4 v[124:127], v[50:51], off offset:64
	global_load_dwordx4 v[110:113], v[52:53], off
	global_load_dwordx4 v[98:101], v[52:53], off offset:64
	global_load_dwordx4 v[198:201], v[54:55], off
	global_load_dwordx4 v[194:197], v[54:55], off offset:64
	s_nop 0
	global_load_dwordx4 v[54:57], v[74:75], off
	global_load_dwordx4 v[50:53], v[74:75], off offset:64
	global_load_dwordx4 v[30:33], v[26:27], off
	s_nop 0
	global_load_dwordx4 v[26:29], v[26:27], off offset:64
	s_mov_b32 s10, 0x3dd2d3e7
	v_ashrrev_i32_e32 v115, 4, v192
	v_readlane_b32 s14, v255, 52
	v_readlane_b32 s15, v255, 53
	s_lshl_b64 s[36:37], s[2:3], 1
	s_mov_b32 s12, 0x41800000
	s_cmpk_gt_u32 s4, 0xff
	s_waitcnt vmcnt(17)
	v_lshlrev_b32_e32 v74, 16, v202
	v_and_b32_e32 v75, 0xffff0000, v202
	v_lshlrev_b32_e32 v84, 16, v203
	v_and_b32_e32 v85, 0xffff0000, v203
	v_lshlrev_b32_e32 v190, 16, v204
	v_and_b32_e32 v191, 0xffff0000, v204
	s_waitcnt vmcnt(16)
	v_pk_fma_f32 v[74:75], v[14:15], v[74:75], v[76:77]
	v_pk_fma_f32 v[76:77], v[16:17], v[84:85], v[78:79]
	s_waitcnt vmcnt(15)
; __device__ __forceinline__ unsigned cvt_pk_bf16(float lo, float hi) { unsigned r; asm volatile("v_cvt_pk_bf16_f32 %0, %1, %2" : "=v"(r) : "v"(lo), "v"(hi)); return r; }
;     __device__ __forceinline__ void operator()(const Acc& acc, const Unit& u, int wr, int wc, int fr, int fq) const {
;     ...
;         for (int idx = 0; idx < 8; ++idx) { const int ai = idx >> 2, m = idx & 3, row = row0 + ai * 128 + m * 16;
; #pragma unroll
;             for (int bj = 0; bj < 2; ++bj) { const int col = bj * 32 + colb, tl = col >> 4;
;                 const u32x4 uu = urow[idx][bj];
;                 const f32x4 a = acc[ai][bj][m][0], b = acc[ai][bj][m][1];
;                 f32x2 y0 = (f32x2){a[0], a[1]} + (f32x2){d0[0], d0[1]} * (f32x2){bf2f(uu.x & 0xffffu), bf2f(uu.x >> 16)}, y1 = (f32x2){a[2], a[3]} + (f32x2){d0[2], d0[3]} * (f32x2){bf2f(uu.y & 0xffffu), bf2f(uu.y >> 16)};
;                 f32x2 y2 = (f32x2){b[0], b[1]} + (f32x2){d1[0], d1[1]} * (f32x2){bf2f(uu.z & 0xffffu), bf2f(uu.z >> 16)}, y3 = (f32x2){b[2], b[3]} + (f32x2){d1[2], d1[3]} * (f32x2){bf2f(uu.w & 0xffffu), bf2f(uu.w >> 16)};
;                 y0 = gelu_tanh2(y0); y1 = gelu_tanh2(y1); y2 = gelu_tanh2(y2); y3 = gelu_tanh2(y3);
;                 u32x4 w; w.x = cvt_pk_bf16(y0.x, y0.y); w.y = cvt_pk_bf16(y1.x, y1.y); w.z = cvt_pk_bf16(y2.x, y2.y); w.w = cvt_pk_bf16(y3.x, y3.y);
;                 *(u32x4*)(yg + (size_t)(row * 16 + tl) * DS + g * 16 + h0) = w;
;                 y0 = y0 * F8_SY; y1 = y1 * F8_SY; y2 = y2 * F8_SY; y3 = y3 * F8_SY;
;                 u32x2 w8; w8.x = pk4_fp8(y0.x, y0.y, y1.x, y1.y); w8.y = pk4_fp8(y2.x, y2.y, y3.x, y3.y);
;                 *(u32x2*)(yg8 + (size_t)(row * 16 + tl) * DS + g * 16 + h0) = w8; }
	v_pk_fma_f32 v[78:79], v[10:11], v[190:191], v[80:81]
	v_lshlrev_b32_e32 v202, 16, v205
	v_and_b32_e32 v203, 0xffff0000, v205
	v_pk_mul_f32 v[190:191], v[78:79], v[78:79]
	v_pk_fma_f32 v[80:81], v[12:13], v[202:203], v[82:83]
	v_pk_fma_f32 v[190:191], v[190:191], s[10:11], v[188:189] op_sel_hi:[1,0,0] neg_lo:[1,0,0] neg_hi:[1,0,0]
	v_pk_mul_f32 v[202:203], v[80:81], v[80:81]
	v_pk_mul_f32 v[190:191], v[78:79], v[190:191]
	v_pk_fma_f32 v[202:203], v[202:203], s[10:11], v[188:189] op_sel_hi:[1,0,0] neg_lo:[1,0,0] neg_hi:[1,0,0]
	v_exp_f32_e32 v190, v190
	v_exp_f32_e32 v191, v191
	v_pk_mul_f32 v[202:203], v[80:81], v[202:203]
	v_pk_mul_f32 v[82:83], v[74:75], v[74:75]
	v_pk_mul_f32 v[84:85], v[76:77], v[76:77]
	v_exp_f32_e32 v202, v202
	v_exp_f32_e32 v203, v203
	v_pk_fma_f32 v[82:83], v[82:83], s[10:11], v[188:189] op_sel_hi:[1,0,0] neg_lo:[1,0,0] neg_hi:[1,0,0]
	v_pk_fma_f32 v[84:85], v[84:85], s[10:11], v[188:189] op_sel_hi:[1,0,0] neg_lo:[1,0,0] neg_hi:[1,0,0]
	v_pk_mul_f32 v[82:83], v[74:75], v[82:83]
	v_pk_mul_f32 v[84:85], v[76:77], v[84:85]
	v_pk_add_f32 v[190:191], v[190:191], 1.0 op_sel_hi:[1,0]
	v_exp_f32_e32 v82, v82
	v_exp_f32_e32 v83, v83
	v_exp_f32_e32 v84, v84
	v_exp_f32_e32 v85, v85
	v_rcp_f32_e32 v190, v190
	v_rcp_f32_e32 v191, v191
	v_pk_add_f32 v[202:203], v[202:203], 1.0 op_sel_hi:[1,0]
	v_pk_add_f32 v[82:83], v[82:83], 1.0 op_sel_hi:[1,0]
	v_rcp_f32_e32 v202, v202
	v_rcp_f32_e32 v203, v203
	v_pk_add_f32 v[84:85], v[84:85], 1.0 op_sel_hi:[1,0]
	v_pk_mul_f32 v[78:79], v[78:79], v[190:191]
	v_add_u32_e32 v190, v115, v193
	v_rcp_f32_e32 v82, v82
	v_rcp_f32_e32 v83, v83
	v_rcp_f32_e32 v84, v84
	v_rcp_f32_e32 v85, v85
	v_ashrrev_i32_e32 v191, 31, v190
	v_pk_mul_f32 v[80:81], v[80:81], v[202:203]
	v_lshlrev_b64 v[202:203], 11, v[190:191]
	v_lshlrev_b64 v[190:191], 12, v[190:191]
	v_lshl_add_u64 v[190:191], s[14:15], 0, v[190:191]
	v_lshl_add_u64 v[204:205], v[190:191], 0, s[36:37]
	v_lshlrev_b32_e32 v190, 1, v0
	v_mov_b32_e32 v191, v1
	v_pk_mul_f32 v[82:83], v[74:75], v[82:83]
	v_pk_mul_f32 v[84:85], v[76:77], v[84:85]
	v_cvt_pk_bf16_f32 v74, v82, v83
	v_lshl_add_u64 v[204:205], v[204:205], 0, v[190:191]
	v_cvt_pk_bf16_f32 v75, v84, v85
	v_cvt_pk_bf16_f32 v76, v78, v79
	v_cvt_pk_bf16_f32 v77, v80, v81
	global_store_dwordx4 v[204:205], v[74:77], off
	s_nop 1
	v_pk_mul_f32 v[74:75], v[82:83], s[12:13] op_sel_hi:[1,0]
	v_pk_mul_f32 v[76:77], v[78:79], s[12:13] op_sel_hi:[1,0]
	v_mov_b32_e32 v78, v1
	v_mov_b32_e32 v79, v1
	v_cvt_pk_fp8_f32 v78, v74, v75
	v_cvt_pk_fp8_f32 v79, v76, v77
	v_pk_mul_f32 v[74:75], v[84:85], s[12:13] op_sel_hi:[1,0]
	v_pk_mul_f32 v[76:77], v[80:81], s[12:13] op_sel_hi:[1,0]
	v_cvt_pk_fp8_f32 v78, v74, v75 op_sel:[0,0,1]
	v_cvt_pk_fp8_f32 v79, v76, v77 op_sel:[0,0,1]
	v_lshl_add_u64 v[74:75], s[60:61], 0, v[202:203]
	v_lshl_add_u64 v[74:75], v[74:75], 0, s[2:3]
	v_lshl_add_u64 v[74:75], v[74:75], 0, v[0:1]
	global_store_dwordx2 v[74:75], v[78:79], off
	s_waitcnt vmcnt(16)
	v_lshlrev_b32_e32 v78, 16, v214
	v_and_b32_e32 v79, 0xffff0000, v214
	v_pk_fma_f32 v[78:79], v[10:11], v[78:79], v[176:177]
	v_lshlrev_b32_e32 v80, 16, v215
	v_and_b32_e32 v81, 0xffff0000, v215
	v_pk_mul_f32 v[176:177], v[78:79], v[78:79]
	v_pk_fma_f32 v[80:81], v[12:13], v[80:81], v[178:179]
	v_pk_fma_f32 v[176:177], v[176:177], s[10:11], v[188:189] op_sel_hi:[1,0,0] neg_lo:[1,0,0] neg_hi:[1,0,0]
	v_add_u32_e32 v74, 32, v192
	v_pk_mul_f32 v[176:177], v[78:79], v[176:177]
	v_pk_mul_f32 v[178:179], v[80:81], v[80:81]
	v_ashrrev_i32_e32 v192, 4, v74
	v_lshlrev_b32_e32 v74, 16, v212
	v_and_b32_e32 v75, 0xffff0000, v212
	v_lshlrev_b32_e32 v76, 16, v213
	v_and_b32_e32 v77, 0xffff0000, v213
	v_exp_f32_e32 v176, v176
	v_exp_f32_e32 v177, v177
	v_pk_fma_f32 v[178:179], v[178:179], s[10:11], v[188:189] op_sel_hi:[1,0,0] neg_lo:[1,0,0] neg_hi:[1,0,0]
	v_pk_fma_f32 v[74:75], v[14:15], v[74:75], v[180:181]
	v_pk_fma_f32 v[76:77], v[16:17], v[76:77], v[182:183]
	v_pk_mul_f32 v[178:179], v[80:81], v[178:179]
	v_pk_mul_f32 v[82:83], v[74:75], v[74:75]
	v_pk_mul_f32 v[84:85], v[76:77], v[76:77]
	v_exp_f32_e32 v178, v178
	v_exp_f32_e32 v179, v179
	v_pk_fma_f32 v[82:83], v[82:83], s[10:11], v[188:189] op_sel_hi:[1,0,0] neg_lo:[1,0,0] neg_hi:[1,0,0]
	v_pk_fma_f32 v[84:85], v[84:85], s[10:11], v[188:189] op_sel_hi:[1,0,0] neg_lo:[1,0,0] neg_hi:[1,0,0]
	v_pk_mul_f32 v[82:83], v[74:75], v[82:83]
	v_pk_mul_f32 v[84:85], v[76:77], v[84:85]
	v_pk_add_f32 v[176:177], v[176:177], 1.0 op_sel_hi:[1,0]
	v_exp_f32_e32 v82, v82
	v_exp_f32_e32 v83, v83
	v_exp_f32_e32 v84, v84
	v_exp_f32_e32 v85, v85
	v_rcp_f32_e32 v176, v176
	v_rcp_f32_e32 v177, v177
	v_pk_add_f32 v[178:179], v[178:179], 1.0 op_sel_hi:[1,0]
	v_pk_add_f32 v[82:83], v[82:83], 1.0 op_sel_hi:[1,0]
	v_rcp_f32_e32 v178, v178
	v_rcp_f32_e32 v179, v179
	v_pk_add_f32 v[84:85], v[84:85], 1.0 op_sel_hi:[1,0]
	v_pk_mul_f32 v[78:79], v[78:79], v[176:177]
	v_add_u32_e32 v176, v192, v193
	v_rcp_f32_e32 v82, v82
	v_rcp_f32_e32 v83, v83
	v_rcp_f32_e32 v84, v84
	v_rcp_f32_e32 v85, v85
	v_ashrrev_i32_e32 v177, 31, v176
	v_pk_mul_f32 v[80:81], v[80:81], v[178:179]
	v_lshlrev_b64 v[178:179], 11, v[176:177]
	v_lshlrev_b64 v[176:177], 12, v[176:177]
	v_lshl_add_u64 v[176:177], s[14:15], 0, v[176:177]
	v_lshl_add_u64 v[176:177], v[176:177], 0, s[36:37]
	v_pk_mul_f32 v[82:83], v[74:75], v[82:83]
	v_pk_mul_f32 v[84:85], v[76:77], v[84:85]
	v_cvt_pk_bf16_f32 v74, v82, v83
	v_lshl_add_u64 v[176:177], v[176:177], 0, v[190:191]
	v_cvt_pk_bf16_f32 v75, v84, v85
	v_cvt_pk_bf16_f32 v76, v78, v79
	v_cvt_pk_bf16_f32 v77, v80, v81
	global_store_dwordx4 v[176:177], v[74:77], off
	v_add_u32_e32 v176, 0x100, v193
	s_nop 0
	v_pk_mul_f32 v[74:75], v[82:83], s[12:13] op_sel_hi:[1,0]
	v_pk_mul_f32 v[76:77], v[78:79], s[12:13] op_sel_hi:[1,0]
	v_mov_b32_e32 v78, v1
	v_mov_b32_e32 v79, v1
	v_cvt_pk_fp8_f32 v78, v74, v75
	v_cvt_pk_fp8_f32 v79, v76, v77
	v_pk_mul_f32 v[74:75], v[84:85], s[12:13] op_sel_hi:[1,0]
	v_pk_mul_f32 v[76:77], v[80:81], s[12:13] op_sel_hi:[1,0]
	v_cvt_pk_fp8_f32 v78, v74, v75 op_sel:[0,0,1]
	v_cvt_pk_fp8_f32 v79, v76, v77 op_sel:[0,0,1]
	v_lshl_add_u64 v[74:75], s[60:61], 0, v[178:179]
	v_lshl_add_u64 v[74:75], v[74:75], 0, s[2:3]
	v_lshl_add_u64 v[74:75], v[74:75], 0, v[0:1]
	global_store_dwordx2 v[74:75], v[78:79], off
	s_waitcnt vmcnt(17)
; __device__ __forceinline__ unsigned cvt_pk_bf16(float lo, float hi) { unsigned r; asm volatile("v_cvt_pk_bf16_f32 %0, %1, %2" : "=v"(r) : "v"(lo), "v"(hi)); return r; }
;     __device__ __forceinline__ void operator()(const Acc& acc, const Unit& u, int wr, int wc, int fr, int fq) const {
;     ...
;         for (int idx = 0; idx < 8; ++idx) { const int ai = idx >> 2, m = idx & 3, row = row0 + ai * 128 + m * 16;
; #pragma unroll
;             for (int bj = 0; bj < 2; ++bj) { const int col = bj * 32 + colb, tl = col >> 4;
;                 const u32x4 uu = urow[idx][bj];
;                 const f32x4 a = acc[ai][bj][m][0], b = acc[ai][bj][m][1];
;                 f32x2 y0 = (f32x2){a[0], a[1]} + (f32x2){d0[0], d0[1]} * (f32x2){bf2f(uu.x & 0xffffu), bf2f(uu.x >> 16)}, y1 = (f32x2){a[2], a[3]} + (f32x2){d0[2], d0[3]} * (f32x2){bf2f(uu.y & 0xffffu), bf2f(uu.y >> 16)};
;                 f32x2 y2 = (f32x2){b[0], b[1]} + (f32x2){d1[0], d1[1]} * (f32x2){bf2f(uu.z & 0xffffu), bf2f(uu.z >> 16)}, y3 = (f32x2){b[2], b[3]} + (f32x2){d1[2], d1[3]} * (f32x2){bf2f(uu.w & 0xffffu), bf2f(uu.w >> 16)};
;                 y0 = gelu_tanh2(y0); y1 = gelu_tanh2(y1); y2 = gelu_tanh2(y2); y3 = gelu_tanh2(y3);
;                 u32x4 w; w.x = cvt_pk_bf16(y0.x, y0.y); w.y = cvt_pk_bf16(y1.x, y1.y); w.z = cvt_pk_bf16(y2.x, y2.y); w.w = cvt_pk_bf16(y3.x, y3.y);
;                 *(u32x4*)(yg + (size_t)(row * 16 + tl) * DS + g * 16 + h0) = w;
;                 y0 = y0 * F8_SY; y1 = y1 * F8_SY; y2 = y2 * F8_SY; y3 = y3 * F8_SY;
;                 u32x2 w8; w8.x = pk4_fp8(y0.x, y0.y, y1.x, y1.y); w8.y = pk4_fp8(y2.x, y2.y, y3.x, y3.y);
;                 *(u32x2*)(yg8 + (size_t)(row * 16 + tl) * DS + g * 16 + h0) = w8; }
	v_lshlrev_b32_e32 v78, 16, v186
	v_and_b32_e32 v79, 0xffff0000, v186
	v_pk_fma_f32 v[78:79], v[10:11], v[78:79], v[164:165]
	v_lshlrev_b32_e32 v80, 16, v187
	v_and_b32_e32 v81, 0xffff0000, v187
	v_pk_mul_f32 v[164:165], v[78:79], v[78:79]
	v_pk_fma_f32 v[80:81], v[12:13], v[80:81], v[166:167]
	v_pk_fma_f32 v[164:165], v[164:165], s[10:11], v[188:189] op_sel_hi:[1,0,0] neg_lo:[1,0,0] neg_hi:[1,0,0]
	v_pk_mul_f32 v[166:167], v[80:81], v[80:81]
	v_pk_mul_f32 v[164:165], v[78:79], v[164:165]
	v_lshlrev_b32_e32 v74, 16, v184
	v_and_b32_e32 v75, 0xffff0000, v184
	v_lshlrev_b32_e32 v76, 16, v185
	v_and_b32_e32 v77, 0xffff0000, v185
	v_exp_f32_e32 v164, v164
	v_exp_f32_e32 v165, v165
	v_pk_fma_f32 v[166:167], v[166:167], s[10:11], v[188:189] op_sel_hi:[1,0,0] neg_lo:[1,0,0] neg_hi:[1,0,0]
	v_pk_fma_f32 v[74:75], v[14:15], v[74:75], v[168:169]
	v_pk_fma_f32 v[76:77], v[16:17], v[76:77], v[170:171]
	v_pk_mul_f32 v[166:167], v[80:81], v[166:167]
	v_pk_mul_f32 v[82:83], v[74:75], v[74:75]
	v_pk_mul_f32 v[84:85], v[76:77], v[76:77]
	v_exp_f32_e32 v166, v166
	v_exp_f32_e32 v167, v167
	v_pk_fma_f32 v[82:83], v[82:83], s[10:11], v[188:189] op_sel_hi:[1,0,0] neg_lo:[1,0,0] neg_hi:[1,0,0]
	v_pk_fma_f32 v[84:85], v[84:85], s[10:11], v[188:189] op_sel_hi:[1,0,0] neg_lo:[1,0,0] neg_hi:[1,0,0]
	v_pk_mul_f32 v[82:83], v[74:75], v[82:83]
	v_pk_mul_f32 v[84:85], v[76:77], v[84:85]
	v_pk_add_f32 v[164:165], v[164:165], 1.0 op_sel_hi:[1,0]
	v_exp_f32_e32 v82, v82
	v_exp_f32_e32 v83, v83
	v_exp_f32_e32 v84, v84
	v_exp_f32_e32 v85, v85
	v_rcp_f32_e32 v164, v164
	v_rcp_f32_e32 v165, v165
	v_pk_add_f32 v[166:167], v[166:167], 1.0 op_sel_hi:[1,0]
	v_pk_add_f32 v[82:83], v[82:83], 1.0 op_sel_hi:[1,0]
	v_rcp_f32_e32 v166, v166
	v_rcp_f32_e32 v167, v167
	v_pk_add_f32 v[84:85], v[84:85], 1.0 op_sel_hi:[1,0]
	v_pk_mul_f32 v[78:79], v[78:79], v[164:165]
	v_add_u32_e32 v164, v176, v115
	v_rcp_f32_e32 v82, v82
	v_rcp_f32_e32 v83, v83
	v_rcp_f32_e32 v84, v84
	v_rcp_f32_e32 v85, v85
	v_ashrrev_i32_e32 v165, 31, v164
	v_pk_mul_f32 v[80:81], v[80:81], v[166:167]
	v_lshlrev_b64 v[166:167], 11, v[164:165]
	v_lshlrev_b64 v[164:165], 12, v[164:165]
	v_lshl_add_u64 v[164:165], s[14:15], 0, v[164:165]
	v_lshl_add_u64 v[164:165], v[164:165], 0, s[36:37]
	v_pk_mul_f32 v[82:83], v[74:75], v[82:83]
	v_pk_mul_f32 v[84:85], v[76:77], v[84:85]
	v_cvt_pk_bf16_f32 v74, v82, v83
	v_lshl_add_u64 v[164:165], v[164:165], 0, v[190:191]
	v_cvt_pk_bf16_f32 v75, v84, v85
	v_cvt_pk_bf16_f32 v76, v78, v79
	v_cvt_pk_bf16_f32 v77, v80, v81
	global_store_dwordx4 v[164:165], v[74:77], off
	s_nop 1
	v_pk_mul_f32 v[74:75], v[82:83], s[12:13] op_sel_hi:[1,0]
	v_pk_mul_f32 v[76:77], v[78:79], s[12:13] op_sel_hi:[1,0]
	v_mov_b32_e32 v78, v1
	v_mov_b32_e32 v79, v1
	v_cvt_pk_fp8_f32 v78, v74, v75
	v_cvt_pk_fp8_f32 v79, v76, v77
	v_pk_mul_f32 v[74:75], v[84:85], s[12:13] op_sel_hi:[1,0]
	v_pk_mul_f32 v[76:77], v[80:81], s[12:13] op_sel_hi:[1,0]
	v_cvt_pk_fp8_f32 v78, v74, v75 op_sel:[0,0,1]
	v_cvt_pk_fp8_f32 v79, v76, v77 op_sel:[0,0,1]
	v_lshl_add_u64 v[74:75], s[60:61], 0, v[166:167]
	v_lshl_add_u64 v[74:75], v[74:75], 0, s[2:3]
	v_lshl_add_u64 v[74:75], v[74:75], 0, v[0:1]
	global_store_dwordx2 v[74:75], v[78:79], off
	s_waitcnt vmcnt(18)
	v_lshlrev_b32_e32 v78, 16, v174
	v_and_b32_e32 v79, 0xffff0000, v174
	v_pk_fma_f32 v[78:79], v[10:11], v[78:79], v[152:153]
	v_lshlrev_b32_e32 v80, 16, v175
	v_and_b32_e32 v81, 0xffff0000, v175
	v_pk_mul_f32 v[152:153], v[78:79], v[78:79]
	v_pk_fma_f32 v[80:81], v[12:13], v[80:81], v[154:155]
	v_pk_fma_f32 v[152:153], v[152:153], s[10:11], v[188:189] op_sel_hi:[1,0,0] neg_lo:[1,0,0] neg_hi:[1,0,0]
	v_pk_mul_f32 v[154:155], v[80:81], v[80:81]
	v_pk_mul_f32 v[152:153], v[78:79], v[152:153]
	v_lshlrev_b32_e32 v74, 16, v172
	v_and_b32_e32 v75, 0xffff0000, v172
	v_lshlrev_b32_e32 v76, 16, v173
	v_and_b32_e32 v77, 0xffff0000, v173
	v_exp_f32_e32 v152, v152
	v_exp_f32_e32 v153, v153
	v_pk_fma_f32 v[154:155], v[154:155], s[10:11], v[188:189] op_sel_hi:[1,0,0] neg_lo:[1,0,0] neg_hi:[1,0,0]
	v_pk_fma_f32 v[74:75], v[14:15], v[74:75], v[156:157]
	v_pk_fma_f32 v[76:77], v[16:17], v[76:77], v[158:159]
	v_pk_mul_f32 v[154:155], v[80:81], v[154:155]
	v_pk_mul_f32 v[82:83], v[74:75], v[74:75]
	v_pk_mul_f32 v[84:85], v[76:77], v[76:77]
	v_exp_f32_e32 v154, v154
	v_exp_f32_e32 v155, v155
	v_pk_fma_f32 v[82:83], v[82:83], s[10:11], v[188:189] op_sel_hi:[1,0,0] neg_lo:[1,0,0] neg_hi:[1,0,0]
	v_pk_fma_f32 v[84:85], v[84:85], s[10:11], v[188:189] op_sel_hi:[1,0,0] neg_lo:[1,0,0] neg_hi:[1,0,0]
	v_pk_mul_f32 v[82:83], v[74:75], v[82:83]
	v_pk_mul_f32 v[84:85], v[76:77], v[84:85]
	v_pk_add_f32 v[152:153], v[152:153], 1.0 op_sel_hi:[1,0]
	v_exp_f32_e32 v82, v82
	v_exp_f32_e32 v83, v83
	v_exp_f32_e32 v84, v84
	v_exp_f32_e32 v85, v85
	v_rcp_f32_e32 v152, v152
	v_rcp_f32_e32 v153, v153
	v_pk_add_f32 v[154:155], v[154:155], 1.0 op_sel_hi:[1,0]
	v_pk_add_f32 v[82:83], v[82:83], 1.0 op_sel_hi:[1,0]
	v_rcp_f32_e32 v154, v154
	v_rcp_f32_e32 v155, v155
	v_pk_add_f32 v[84:85], v[84:85], 1.0 op_sel_hi:[1,0]
	v_pk_mul_f32 v[78:79], v[78:79], v[152:153]
	v_add_u32_e32 v152, v192, v176
	v_rcp_f32_e32 v82, v82
	v_rcp_f32_e32 v83, v83
	v_rcp_f32_e32 v84, v84
	v_rcp_f32_e32 v85, v85
	v_ashrrev_i32_e32 v153, 31, v152
	v_pk_mul_f32 v[80:81], v[80:81], v[154:155]
	v_lshlrev_b64 v[154:155], 11, v[152:153]
	v_lshlrev_b64 v[152:153], 12, v[152:153]
	v_lshl_add_u64 v[152:153], s[14:15], 0, v[152:153]
	v_lshl_add_u64 v[152:153], v[152:153], 0, s[36:37]
	v_pk_mul_f32 v[82:83], v[74:75], v[82:83]
	v_pk_mul_f32 v[84:85], v[76:77], v[84:85]
	v_cvt_pk_bf16_f32 v74, v82, v83
	v_lshl_add_u64 v[152:153], v[152:153], 0, v[190:191]
	v_cvt_pk_bf16_f32 v75, v84, v85
	v_cvt_pk_bf16_f32 v76, v78, v79
	v_cvt_pk_bf16_f32 v77, v80, v81
	global_store_dwordx4 v[152:153], v[74:77], off
	v_add_u32_e32 v152, 0x200, v193
	s_nop 0
	v_pk_mul_f32 v[74:75], v[82:83], s[12:13] op_sel_hi:[1,0]
	v_pk_mul_f32 v[76:77], v[78:79], s[12:13] op_sel_hi:[1,0]
	v_mov_b32_e32 v78, v1
	v_mov_b32_e32 v79, v1
	v_cvt_pk_fp8_f32 v78, v74, v75
	v_cvt_pk_fp8_f32 v79, v76, v77
	v_pk_mul_f32 v[74:75], v[84:85], s[12:13] op_sel_hi:[1,0]
	v_pk_mul_f32 v[76:77], v[80:81], s[12:13] op_sel_hi:[1,0]
	v_cvt_pk_fp8_f32 v78, v74, v75 op_sel:[0,0,1]
	v_cvt_pk_fp8_f32 v79, v76, v77 op_sel:[0,0,1]
	v_lshl_add_u64 v[74:75], s[60:61], 0, v[154:155]
	v_lshl_add_u64 v[74:75], v[74:75], 0, s[2:3]
	v_lshl_add_u64 v[74:75], v[74:75], 0, v[0:1]
	global_store_dwordx2 v[74:75], v[78:79], off
	s_waitcnt vmcnt(19)
; __device__ __forceinline__ unsigned cvt_pk_bf16(float lo, float hi) { unsigned r; asm volatile("v_cvt_pk_bf16_f32 %0, %1, %2" : "=v"(r) : "v"(lo), "v"(hi)); return r; }
;     __device__ __forceinline__ void operator()(const Acc& acc, const Unit& u, int wr, int wc, int fr, int fq) const {
;     ...
;         for (int idx = 0; idx < 8; ++idx) { const int ai = idx >> 2, m = idx & 3, row = row0 + ai * 128 + m * 16;
; #pragma unroll
;             for (int bj = 0; bj < 2; ++bj) { const int col = bj * 32 + colb, tl = col >> 4;
;                 const u32x4 uu = urow[idx][bj];
;                 const f32x4 a = acc[ai][bj][m][0], b = acc[ai][bj][m][1];
;                 f32x2 y0 = (f32x2){a[0], a[1]} + (f32x2){d0[0], d0[1]} * (f32x2){bf2f(uu.x & 0xffffu), bf2f(uu.x >> 16)}, y1 = (f32x2){a[2], a[3]} + (f32x2){d0[2], d0[3]} * (f32x2){bf2f(uu.y & 0xffffu), bf2f(uu.y >> 16)};
;                 f32x2 y2 = (f32x2){b[0], b[1]} + (f32x2){d1[0], d1[1]} * (f32x2){bf2f(uu.z & 0xffffu), bf2f(uu.z >> 16)}, y3 = (f32x2){b[2], b[3]} + (f32x2){d1[2], d1[3]} * (f32x2){bf2f(uu.w & 0xffffu), bf2f(uu.w >> 16)};
;                 y0 = gelu_tanh2(y0); y1 = gelu_tanh2(y1); y2 = gelu_tanh2(y2); y3 = gelu_tanh2(y3);
;                 u32x4 w; w.x = cvt_pk_bf16(y0.x, y0.y); w.y = cvt_pk_bf16(y1.x, y1.y); w.z = cvt_pk_bf16(y2.x, y2.y); w.w = cvt_pk_bf16(y3.x, y3.y);
;                 *(u32x4*)(yg + (size_t)(row * 16 + tl) * DS + g * 16 + h0) = w;
;                 y0 = y0 * F8_SY; y1 = y1 * F8_SY; y2 = y2 * F8_SY; y3 = y3 * F8_SY;
;                 u32x2 w8; w8.x = pk4_fp8(y0.x, y0.y, y1.x, y1.y); w8.y = pk4_fp8(y2.x, y2.y, y3.x, y3.y);
;                 *(u32x2*)(yg8 + (size_t)(row * 16 + tl) * DS + g * 16 + h0) = w8; }
	v_lshlrev_b32_e32 v78, 16, v162
	v_and_b32_e32 v79, 0xffff0000, v162
	v_pk_fma_f32 v[78:79], v[10:11], v[78:79], v[140:141]
	v_lshlrev_b32_e32 v80, 16, v163
	v_and_b32_e32 v81, 0xffff0000, v163
	v_pk_mul_f32 v[140:141], v[78:79], v[78:79]
	v_pk_fma_f32 v[80:81], v[12:13], v[80:81], v[142:143]
	v_pk_fma_f32 v[140:141], v[140:141], s[10:11], v[188:189] op_sel_hi:[1,0,0] neg_lo:[1,0,0] neg_hi:[1,0,0]
	v_pk_mul_f32 v[142:143], v[80:81], v[80:81]
	v_pk_mul_f32 v[140:141], v[78:79], v[140:141]
	v_lshlrev_b32_e32 v74, 16, v160
	v_and_b32_e32 v75, 0xffff0000, v160
	v_lshlrev_b32_e32 v76, 16, v161
	v_and_b32_e32 v77, 0xffff0000, v161
	v_exp_f32_e32 v140, v140
	v_exp_f32_e32 v141, v141
	v_pk_fma_f32 v[142:143], v[142:143], s[10:11], v[188:189] op_sel_hi:[1,0,0] neg_lo:[1,0,0] neg_hi:[1,0,0]
	v_pk_fma_f32 v[74:75], v[14:15], v[74:75], v[144:145]
	v_pk_fma_f32 v[76:77], v[16:17], v[76:77], v[146:147]
	v_pk_mul_f32 v[142:143], v[80:81], v[142:143]
	v_pk_mul_f32 v[82:83], v[74:75], v[74:75]
	v_pk_mul_f32 v[84:85], v[76:77], v[76:77]
	v_exp_f32_e32 v142, v142
	v_exp_f32_e32 v143, v143
	v_pk_fma_f32 v[82:83], v[82:83], s[10:11], v[188:189] op_sel_hi:[1,0,0] neg_lo:[1,0,0] neg_hi:[1,0,0]
	v_pk_fma_f32 v[84:85], v[84:85], s[10:11], v[188:189] op_sel_hi:[1,0,0] neg_lo:[1,0,0] neg_hi:[1,0,0]
	v_pk_mul_f32 v[82:83], v[74:75], v[82:83]
	v_pk_mul_f32 v[84:85], v[76:77], v[84:85]
	v_pk_add_f32 v[140:141], v[140:141], 1.0 op_sel_hi:[1,0]
	v_exp_f32_e32 v82, v82
	v_exp_f32_e32 v83, v83
	v_exp_f32_e32 v84, v84
	v_exp_f32_e32 v85, v85
	v_rcp_f32_e32 v140, v140
	v_rcp_f32_e32 v141, v141
	v_pk_add_f32 v[142:143], v[142:143], 1.0 op_sel_hi:[1,0]
	v_pk_add_f32 v[82:83], v[82:83], 1.0 op_sel_hi:[1,0]
	v_rcp_f32_e32 v142, v142
	v_rcp_f32_e32 v143, v143
	v_pk_add_f32 v[84:85], v[84:85], 1.0 op_sel_hi:[1,0]
	v_pk_mul_f32 v[78:79], v[78:79], v[140:141]
	v_add_u32_e32 v140, v152, v115
	v_rcp_f32_e32 v82, v82
	v_rcp_f32_e32 v83, v83
	v_rcp_f32_e32 v84, v84
	v_rcp_f32_e32 v85, v85
	v_ashrrev_i32_e32 v141, 31, v140
	v_pk_mul_f32 v[80:81], v[80:81], v[142:143]
	v_lshlrev_b64 v[142:143], 11, v[140:141]
	v_lshlrev_b64 v[140:141], 12, v[140:141]
	v_lshl_add_u64 v[140:141], s[14:15], 0, v[140:141]
	v_lshl_add_u64 v[140:141], v[140:141], 0, s[36:37]
	v_pk_mul_f32 v[82:83], v[74:75], v[82:83]
	v_pk_mul_f32 v[84:85], v[76:77], v[84:85]
	v_cvt_pk_bf16_f32 v74, v82, v83
	v_lshl_add_u64 v[140:141], v[140:141], 0, v[190:191]
	v_cvt_pk_bf16_f32 v75, v84, v85
	v_cvt_pk_bf16_f32 v76, v78, v79
	v_cvt_pk_bf16_f32 v77, v80, v81
	global_store_dwordx4 v[140:141], v[74:77], off
	s_nop 1
	v_pk_mul_f32 v[74:75], v[82:83], s[12:13] op_sel_hi:[1,0]
	v_pk_mul_f32 v[76:77], v[78:79], s[12:13] op_sel_hi:[1,0]
	v_mov_b32_e32 v78, v1
	v_mov_b32_e32 v79, v1
	v_cvt_pk_fp8_f32 v78, v74, v75
	v_cvt_pk_fp8_f32 v79, v76, v77
	v_pk_mul_f32 v[74:75], v[84:85], s[12:13] op_sel_hi:[1,0]
	v_pk_mul_f32 v[76:77], v[80:81], s[12:13] op_sel_hi:[1,0]
	v_cvt_pk_fp8_f32 v78, v74, v75 op_sel:[0,0,1]
	v_cvt_pk_fp8_f32 v79, v76, v77 op_sel:[0,0,1]
	v_lshl_add_u64 v[74:75], s[60:61], 0, v[142:143]
	v_lshl_add_u64 v[74:75], v[74:75], 0, s[2:3]
	v_lshl_add_u64 v[74:75], v[74:75], 0, v[0:1]
	global_store_dwordx2 v[74:75], v[78:79], off
	s_waitcnt vmcnt(20)
	v_lshlrev_b32_e32 v78, 16, v150
	v_and_b32_e32 v79, 0xffff0000, v150
	v_pk_fma_f32 v[78:79], v[10:11], v[78:79], v[128:129]
	v_lshlrev_b32_e32 v80, 16, v151
	v_and_b32_e32 v81, 0xffff0000, v151
	v_pk_mul_f32 v[128:129], v[78:79], v[78:79]
	v_pk_fma_f32 v[80:81], v[12:13], v[80:81], v[130:131]
	v_pk_fma_f32 v[128:129], v[128:129], s[10:11], v[188:189] op_sel_hi:[1,0,0] neg_lo:[1,0,0] neg_hi:[1,0,0]
	v_pk_mul_f32 v[130:131], v[80:81], v[80:81]
	v_pk_mul_f32 v[128:129], v[78:79], v[128:129]
	v_lshlrev_b32_e32 v74, 16, v148
	v_and_b32_e32 v75, 0xffff0000, v148
	v_lshlrev_b32_e32 v76, 16, v149
	v_and_b32_e32 v77, 0xffff0000, v149
	v_exp_f32_e32 v128, v128
	v_exp_f32_e32 v129, v129
	v_pk_fma_f32 v[130:131], v[130:131], s[10:11], v[188:189] op_sel_hi:[1,0,0] neg_lo:[1,0,0] neg_hi:[1,0,0]
	v_pk_fma_f32 v[74:75], v[14:15], v[74:75], v[132:133]
	v_pk_fma_f32 v[76:77], v[16:17], v[76:77], v[134:135]
	v_pk_mul_f32 v[130:131], v[80:81], v[130:131]
	v_pk_mul_f32 v[82:83], v[74:75], v[74:75]
	v_pk_mul_f32 v[84:85], v[76:77], v[76:77]
	v_exp_f32_e32 v130, v130
	v_exp_f32_e32 v131, v131
	v_pk_fma_f32 v[82:83], v[82:83], s[10:11], v[188:189] op_sel_hi:[1,0,0] neg_lo:[1,0,0] neg_hi:[1,0,0]
	v_pk_fma_f32 v[84:85], v[84:85], s[10:11], v[188:189] op_sel_hi:[1,0,0] neg_lo:[1,0,0] neg_hi:[1,0,0]
	v_pk_mul_f32 v[82:83], v[74:75], v[82:83]
	v_pk_mul_f32 v[84:85], v[76:77], v[84:85]
	v_pk_add_f32 v[128:129], v[128:129], 1.0 op_sel_hi:[1,0]
	v_exp_f32_e32 v82, v82
	v_exp_f32_e32 v83, v83
	v_exp_f32_e32 v84, v84
	v_exp_f32_e32 v85, v85
	v_rcp_f32_e32 v128, v128
	v_rcp_f32_e32 v129, v129
	v_pk_add_f32 v[130:131], v[130:131], 1.0 op_sel_hi:[1,0]
	v_pk_add_f32 v[82:83], v[82:83], 1.0 op_sel_hi:[1,0]
	v_rcp_f32_e32 v130, v130
	v_rcp_f32_e32 v131, v131
	v_pk_add_f32 v[84:85], v[84:85], 1.0 op_sel_hi:[1,0]
	v_pk_mul_f32 v[78:79], v[78:79], v[128:129]
	v_add_u32_e32 v128, v192, v152
	v_rcp_f32_e32 v82, v82
	v_rcp_f32_e32 v83, v83
	v_rcp_f32_e32 v84, v84
	v_rcp_f32_e32 v85, v85
	v_ashrrev_i32_e32 v129, 31, v128
	v_pk_mul_f32 v[80:81], v[80:81], v[130:131]
	v_lshlrev_b64 v[130:131], 11, v[128:129]
	v_lshlrev_b64 v[128:129], 12, v[128:129]
	v_lshl_add_u64 v[128:129], s[14:15], 0, v[128:129]
	v_lshl_add_u64 v[128:129], v[128:129], 0, s[36:37]
	v_pk_mul_f32 v[82:83], v[74:75], v[82:83]
	v_pk_mul_f32 v[84:85], v[76:77], v[84:85]
	v_cvt_pk_bf16_f32 v74, v82, v83
	v_lshl_add_u64 v[128:129], v[128:129], 0, v[190:191]
	v_cvt_pk_bf16_f32 v75, v84, v85
	v_cvt_pk_bf16_f32 v76, v78, v79
	v_cvt_pk_bf16_f32 v77, v80, v81
	global_store_dwordx4 v[128:129], v[74:77], off
	v_add_u32_e32 v128, 0x300, v193
	s_nop 0
	v_pk_mul_f32 v[74:75], v[82:83], s[12:13] op_sel_hi:[1,0]
	v_pk_mul_f32 v[76:77], v[78:79], s[12:13] op_sel_hi:[1,0]
	v_mov_b32_e32 v78, v1
	v_mov_b32_e32 v79, v1
	v_cvt_pk_fp8_f32 v78, v74, v75
	v_cvt_pk_fp8_f32 v79, v76, v77
	v_pk_mul_f32 v[74:75], v[84:85], s[12:13] op_sel_hi:[1,0]
	v_pk_mul_f32 v[76:77], v[80:81], s[12:13] op_sel_hi:[1,0]
	v_cvt_pk_fp8_f32 v78, v74, v75 op_sel:[0,0,1]
	v_cvt_pk_fp8_f32 v79, v76, v77 op_sel:[0,0,1]
	v_lshl_add_u64 v[74:75], s[60:61], 0, v[130:131]
	v_lshl_add_u64 v[74:75], v[74:75], 0, s[2:3]
	v_lshl_add_u64 v[74:75], v[74:75], 0, v[0:1]
	global_store_dwordx2 v[74:75], v[78:79], off
	s_waitcnt vmcnt(21)
; __device__ __forceinline__ unsigned cvt_pk_bf16(float lo, float hi) { unsigned r; asm volatile("v_cvt_pk_bf16_f32 %0, %1, %2" : "=v"(r) : "v"(lo), "v"(hi)); return r; }
;     __device__ __forceinline__ void operator()(const Acc& acc, const Unit& u, int wr, int wc, int fr, int fq) const {
;     ...
;         for (int idx = 0; idx < 8; ++idx) { const int ai = idx >> 2, m = idx & 3, row = row0 + ai * 128 + m * 16;
; #pragma unroll
;             for (int bj = 0; bj < 2; ++bj) { const int col = bj * 32 + colb, tl = col >> 4;
;                 const u32x4 uu = urow[idx][bj];
;                 const f32x4 a = acc[ai][bj][m][0], b = acc[ai][bj][m][1];
;                 f32x2 y0 = (f32x2){a[0], a[1]} + (f32x2){d0[0], d0[1]} * (f32x2){bf2f(uu.x & 0xffffu), bf2f(uu.x >> 16)}, y1 = (f32x2){a[2], a[3]} + (f32x2){d0[2], d0[3]} * (f32x2){bf2f(uu.y & 0xffffu), bf2f(uu.y >> 16)};
;                 f32x2 y2 = (f32x2){b[0], b[1]} + (f32x2){d1[0], d1[1]} * (f32x2){bf2f(uu.z & 0xffffu), bf2f(uu.z >> 16)}, y3 = (f32x2){b[2], b[3]} + (f32x2){d1[2], d1[3]} * (f32x2){bf2f(uu.w & 0xffffu), bf2f(uu.w >> 16)};
;                 y0 = gelu_tanh2(y0); y1 = gelu_tanh2(y1); y2 = gelu_tanh2(y2); y3 = gelu_tanh2(y3);
;                 u32x4 w; w.x = cvt_pk_bf16(y0.x, y0.y); w.y = cvt_pk_bf16(y1.x, y1.y); w.z = cvt_pk_bf16(y2.x, y2.y); w.w = cvt_pk_bf16(y3.x, y3.y);
;                 *(u32x4*)(yg + (size_t)(row * 16 + tl) * DS + g * 16 + h0) = w;
;                 y0 = y0 * F8_SY; y1 = y1 * F8_SY; y2 = y2 * F8_SY; y3 = y3 * F8_SY;
;                 u32x2 w8; w8.x = pk4_fp8(y0.x, y0.y, y1.x, y1.y); w8.y = pk4_fp8(y2.x, y2.y, y3.x, y3.y);
;                 *(u32x2*)(yg8 + (size_t)(row * 16 + tl) * DS + g * 16 + h0) = w8; }
	v_lshlrev_b32_e32 v78, 16, v138
	v_and_b32_e32 v79, 0xffff0000, v138
	v_pk_fma_f32 v[78:79], v[10:11], v[78:79], v[116:117]
	v_lshlrev_b32_e32 v80, 16, v139
	v_and_b32_e32 v81, 0xffff0000, v139
	v_pk_mul_f32 v[116:117], v[78:79], v[78:79]
	v_pk_fma_f32 v[80:81], v[12:13], v[80:81], v[118:119]
	v_pk_fma_f32 v[116:117], v[116:117], s[10:11], v[188:189] op_sel_hi:[1,0,0] neg_lo:[1,0,0] neg_hi:[1,0,0]
	v_pk_mul_f32 v[118:119], v[80:81], v[80:81]
	v_pk_mul_f32 v[116:117], v[78:79], v[116:117]
	v_lshlrev_b32_e32 v74, 16, v136
	v_and_b32_e32 v75, 0xffff0000, v136
	v_lshlrev_b32_e32 v76, 16, v137
	v_and_b32_e32 v77, 0xffff0000, v137
	v_exp_f32_e32 v116, v116
	v_exp_f32_e32 v117, v117
	v_pk_fma_f32 v[118:119], v[118:119], s[10:11], v[188:189] op_sel_hi:[1,0,0] neg_lo:[1,0,0] neg_hi:[1,0,0]
	v_pk_fma_f32 v[74:75], v[14:15], v[74:75], v[120:121]
	v_pk_fma_f32 v[76:77], v[16:17], v[76:77], v[122:123]
	v_pk_mul_f32 v[118:119], v[80:81], v[118:119]
	v_pk_mul_f32 v[82:83], v[74:75], v[74:75]
	v_pk_mul_f32 v[84:85], v[76:77], v[76:77]
	v_exp_f32_e32 v118, v118
	v_exp_f32_e32 v119, v119
	v_pk_fma_f32 v[82:83], v[82:83], s[10:11], v[188:189] op_sel_hi:[1,0,0] neg_lo:[1,0,0] neg_hi:[1,0,0]
	v_pk_fma_f32 v[84:85], v[84:85], s[10:11], v[188:189] op_sel_hi:[1,0,0] neg_lo:[1,0,0] neg_hi:[1,0,0]
	v_pk_mul_f32 v[82:83], v[74:75], v[82:83]
	v_pk_mul_f32 v[84:85], v[76:77], v[84:85]
	v_pk_add_f32 v[116:117], v[116:117], 1.0 op_sel_hi:[1,0]
	v_exp_f32_e32 v82, v82
	v_exp_f32_e32 v83, v83
	v_exp_f32_e32 v84, v84
	v_exp_f32_e32 v85, v85
	v_rcp_f32_e32 v116, v116
	v_rcp_f32_e32 v117, v117
	v_pk_add_f32 v[118:119], v[118:119], 1.0 op_sel_hi:[1,0]
	v_pk_add_f32 v[82:83], v[82:83], 1.0 op_sel_hi:[1,0]
	v_rcp_f32_e32 v118, v118
	v_rcp_f32_e32 v119, v119
	v_pk_add_f32 v[84:85], v[84:85], 1.0 op_sel_hi:[1,0]
	v_pk_mul_f32 v[78:79], v[78:79], v[116:117]
	v_add_u32_e32 v116, v128, v115
	v_rcp_f32_e32 v82, v82
	v_rcp_f32_e32 v83, v83
	v_rcp_f32_e32 v84, v84
	v_rcp_f32_e32 v85, v85
	v_ashrrev_i32_e32 v117, 31, v116
	v_pk_mul_f32 v[80:81], v[80:81], v[118:119]
	v_lshlrev_b64 v[118:119], 11, v[116:117]
	v_lshlrev_b64 v[116:117], 12, v[116:117]
	v_lshl_add_u64 v[116:117], s[14:15], 0, v[116:117]
	v_lshl_add_u64 v[116:117], v[116:117], 0, s[36:37]
	v_pk_mul_f32 v[82:83], v[74:75], v[82:83]
	v_pk_mul_f32 v[84:85], v[76:77], v[84:85]
	v_cvt_pk_bf16_f32 v74, v82, v83
	v_lshl_add_u64 v[116:117], v[116:117], 0, v[190:191]
	v_cvt_pk_bf16_f32 v75, v84, v85
	v_cvt_pk_bf16_f32 v76, v78, v79
	v_cvt_pk_bf16_f32 v77, v80, v81
	global_store_dwordx4 v[116:117], v[74:77], off
	s_nop 1
	v_pk_mul_f32 v[74:75], v[82:83], s[12:13] op_sel_hi:[1,0]
	v_pk_mul_f32 v[76:77], v[78:79], s[12:13] op_sel_hi:[1,0]
	v_mov_b32_e32 v78, v1
	v_mov_b32_e32 v79, v1
	v_cvt_pk_fp8_f32 v78, v74, v75
	v_cvt_pk_fp8_f32 v79, v76, v77
	v_pk_mul_f32 v[74:75], v[84:85], s[12:13] op_sel_hi:[1,0]
	v_pk_mul_f32 v[76:77], v[80:81], s[12:13] op_sel_hi:[1,0]
	v_cvt_pk_fp8_f32 v78, v74, v75 op_sel:[0,0,1]
	v_cvt_pk_fp8_f32 v79, v76, v77 op_sel:[0,0,1]
	v_lshl_add_u64 v[74:75], s[60:61], 0, v[118:119]
	v_lshl_add_u64 v[74:75], v[74:75], 0, s[2:3]
	v_lshl_add_u64 v[74:75], v[74:75], 0, v[0:1]
	global_store_dwordx2 v[74:75], v[78:79], off
	s_waitcnt vmcnt(22)
	v_lshlrev_b32_e32 v78, 16, v126
	v_and_b32_e32 v79, 0xffff0000, v126
	v_pk_fma_f32 v[78:79], v[10:11], v[78:79], v[102:103]
	v_lshlrev_b32_e32 v80, 16, v127
	v_and_b32_e32 v81, 0xffff0000, v127
	v_pk_mul_f32 v[102:103], v[78:79], v[78:79]
	v_pk_fma_f32 v[80:81], v[12:13], v[80:81], v[104:105]
	v_pk_fma_f32 v[102:103], v[102:103], s[10:11], v[188:189] op_sel_hi:[1,0,0] neg_lo:[1,0,0] neg_hi:[1,0,0]
	v_pk_mul_f32 v[104:105], v[80:81], v[80:81]
	v_pk_mul_f32 v[102:103], v[78:79], v[102:103]
	v_lshlrev_b32_e32 v74, 16, v124
	v_and_b32_e32 v75, 0xffff0000, v124
	v_lshlrev_b32_e32 v76, 16, v125
	v_and_b32_e32 v77, 0xffff0000, v125
	v_exp_f32_e32 v102, v102
	v_exp_f32_e32 v103, v103
	v_pk_fma_f32 v[104:105], v[104:105], s[10:11], v[188:189] op_sel_hi:[1,0,0] neg_lo:[1,0,0] neg_hi:[1,0,0]
	v_pk_fma_f32 v[74:75], v[14:15], v[74:75], v[106:107]
	v_pk_fma_f32 v[76:77], v[16:17], v[76:77], v[108:109]
	v_pk_mul_f32 v[104:105], v[80:81], v[104:105]
	v_pk_mul_f32 v[82:83], v[74:75], v[74:75]
	v_pk_mul_f32 v[84:85], v[76:77], v[76:77]
	v_exp_f32_e32 v104, v104
	v_exp_f32_e32 v105, v105
	v_pk_fma_f32 v[82:83], v[82:83], s[10:11], v[188:189] op_sel_hi:[1,0,0] neg_lo:[1,0,0] neg_hi:[1,0,0]
	v_pk_fma_f32 v[84:85], v[84:85], s[10:11], v[188:189] op_sel_hi:[1,0,0] neg_lo:[1,0,0] neg_hi:[1,0,0]
	v_pk_mul_f32 v[82:83], v[74:75], v[82:83]
	v_pk_mul_f32 v[84:85], v[76:77], v[84:85]
	v_pk_add_f32 v[102:103], v[102:103], 1.0 op_sel_hi:[1,0]
	v_exp_f32_e32 v82, v82
	v_exp_f32_e32 v83, v83
	v_exp_f32_e32 v84, v84
	v_exp_f32_e32 v85, v85
	v_rcp_f32_e32 v102, v102
	v_rcp_f32_e32 v103, v103
	v_pk_add_f32 v[104:105], v[104:105], 1.0 op_sel_hi:[1,0]
	v_pk_add_f32 v[82:83], v[82:83], 1.0 op_sel_hi:[1,0]
	v_rcp_f32_e32 v104, v104
	v_rcp_f32_e32 v105, v105
	v_pk_add_f32 v[84:85], v[84:85], 1.0 op_sel_hi:[1,0]
	v_pk_mul_f32 v[78:79], v[78:79], v[102:103]
	v_add_u32_e32 v102, v192, v128
	v_rcp_f32_e32 v82, v82
	v_rcp_f32_e32 v83, v83
	v_rcp_f32_e32 v84, v84
	v_rcp_f32_e32 v85, v85
	v_ashrrev_i32_e32 v103, 31, v102
	v_pk_mul_f32 v[80:81], v[80:81], v[104:105]
	v_lshlrev_b64 v[104:105], 11, v[102:103]
	v_lshlrev_b64 v[102:103], 12, v[102:103]
	v_lshl_add_u64 v[102:103], s[14:15], 0, v[102:103]
	v_lshl_add_u64 v[102:103], v[102:103], 0, s[36:37]
	v_pk_mul_f32 v[82:83], v[74:75], v[82:83]
	v_pk_mul_f32 v[84:85], v[76:77], v[84:85]
	v_cvt_pk_bf16_f32 v74, v82, v83
	v_lshl_add_u64 v[102:103], v[102:103], 0, v[190:191]
	v_cvt_pk_bf16_f32 v75, v84, v85
	v_cvt_pk_bf16_f32 v76, v78, v79
	v_cvt_pk_bf16_f32 v77, v80, v81
	global_store_dwordx4 v[102:103], v[74:77], off
	v_add_u32_e32 v102, 0x800, v193
	s_nop 0
	v_pk_mul_f32 v[74:75], v[82:83], s[12:13] op_sel_hi:[1,0]
	v_pk_mul_f32 v[76:77], v[78:79], s[12:13] op_sel_hi:[1,0]
	v_mov_b32_e32 v78, v1
	v_mov_b32_e32 v79, v1
	v_cvt_pk_fp8_f32 v78, v74, v75
	v_cvt_pk_fp8_f32 v79, v76, v77
	v_pk_mul_f32 v[74:75], v[84:85], s[12:13] op_sel_hi:[1,0]
	v_pk_mul_f32 v[76:77], v[80:81], s[12:13] op_sel_hi:[1,0]
	v_cvt_pk_fp8_f32 v78, v74, v75 op_sel:[0,0,1]
	v_cvt_pk_fp8_f32 v79, v76, v77 op_sel:[0,0,1]
	v_lshl_add_u64 v[74:75], s[60:61], 0, v[104:105]
	v_lshl_add_u64 v[74:75], v[74:75], 0, s[2:3]
	v_lshl_add_u64 v[74:75], v[74:75], 0, v[0:1]
	global_store_dwordx2 v[74:75], v[78:79], off
	s_waitcnt vmcnt(23)
; __device__ __forceinline__ unsigned cvt_pk_bf16(float lo, float hi) { unsigned r; asm volatile("v_cvt_pk_bf16_f32 %0, %1, %2" : "=v"(r) : "v"(lo), "v"(hi)); return r; }
;     __device__ __forceinline__ void operator()(const Acc& acc, const Unit& u, int wr, int wc, int fr, int fq) const {
;     ...
;         for (int idx = 0; idx < 8; ++idx) { const int ai = idx >> 2, m = idx & 3, row = row0 + ai * 128 + m * 16;
; #pragma unroll
;             for (int bj = 0; bj < 2; ++bj) { const int col = bj * 32 + colb, tl = col >> 4;
;                 const u32x4 uu = urow[idx][bj];
;                 const f32x4 a = acc[ai][bj][m][0], b = acc[ai][bj][m][1];
;                 f32x2 y0 = (f32x2){a[0], a[1]} + (f32x2){d0[0], d0[1]} * (f32x2){bf2f(uu.x & 0xffffu), bf2f(uu.x >> 16)}, y1 = (f32x2){a[2], a[3]} + (f32x2){d0[2], d0[3]} * (f32x2){bf2f(uu.y & 0xffffu), bf2f(uu.y >> 16)};
;                 f32x2 y2 = (f32x2){b[0], b[1]} + (f32x2){d1[0], d1[1]} * (f32x2){bf2f(uu.z & 0xffffu), bf2f(uu.z >> 16)}, y3 = (f32x2){b[2], b[3]} + (f32x2){d1[2], d1[3]} * (f32x2){bf2f(uu.w & 0xffffu), bf2f(uu.w >> 16)};
;                 y0 = gelu_tanh2(y0); y1 = gelu_tanh2(y1); y2 = gelu_tanh2(y2); y3 = gelu_tanh2(y3);
;                 u32x4 w; w.x = cvt_pk_bf16(y0.x, y0.y); w.y = cvt_pk_bf16(y1.x, y1.y); w.z = cvt_pk_bf16(y2.x, y2.y); w.w = cvt_pk_bf16(y3.x, y3.y);
;                 *(u32x4*)(yg + (size_t)(row * 16 + tl) * DS + g * 16 + h0) = w;
;                 y0 = y0 * F8_SY; y1 = y1 * F8_SY; y2 = y2 * F8_SY; y3 = y3 * F8_SY;
;                 u32x2 w8; w8.x = pk4_fp8(y0.x, y0.y, y1.x, y1.y); w8.y = pk4_fp8(y2.x, y2.y, y3.x, y3.y);
;                 *(u32x2*)(yg8 + (size_t)(row * 16 + tl) * DS + g * 16 + h0) = w8; }
	v_lshlrev_b32_e32 v78, 16, v112
	v_and_b32_e32 v79, 0xffff0000, v112
	v_pk_fma_f32 v[78:79], v[10:11], v[78:79], v[90:91]
	v_lshlrev_b32_e32 v80, 16, v113
	v_and_b32_e32 v81, 0xffff0000, v113
	v_pk_mul_f32 v[90:91], v[78:79], v[78:79]
	v_pk_fma_f32 v[80:81], v[12:13], v[80:81], v[92:93]
	v_pk_fma_f32 v[90:91], v[90:91], s[10:11], v[188:189] op_sel_hi:[1,0,0] neg_lo:[1,0,0] neg_hi:[1,0,0]
	v_pk_mul_f32 v[92:93], v[80:81], v[80:81]
	v_pk_mul_f32 v[90:91], v[78:79], v[90:91]
	v_lshlrev_b32_e32 v74, 16, v110
	v_and_b32_e32 v75, 0xffff0000, v110
	v_lshlrev_b32_e32 v76, 16, v111
	v_and_b32_e32 v77, 0xffff0000, v111
	v_exp_f32_e32 v90, v90
	v_exp_f32_e32 v91, v91
	v_pk_fma_f32 v[92:93], v[92:93], s[10:11], v[188:189] op_sel_hi:[1,0,0] neg_lo:[1,0,0] neg_hi:[1,0,0]
	v_pk_fma_f32 v[74:75], v[14:15], v[74:75], v[94:95]
	v_pk_fma_f32 v[76:77], v[16:17], v[76:77], v[96:97]
	v_pk_mul_f32 v[92:93], v[80:81], v[92:93]
	v_pk_mul_f32 v[82:83], v[74:75], v[74:75]
	v_pk_mul_f32 v[84:85], v[76:77], v[76:77]
	v_exp_f32_e32 v92, v92
	v_exp_f32_e32 v93, v93
	v_pk_fma_f32 v[82:83], v[82:83], s[10:11], v[188:189] op_sel_hi:[1,0,0] neg_lo:[1,0,0] neg_hi:[1,0,0]
	v_pk_fma_f32 v[84:85], v[84:85], s[10:11], v[188:189] op_sel_hi:[1,0,0] neg_lo:[1,0,0] neg_hi:[1,0,0]
	v_pk_mul_f32 v[82:83], v[74:75], v[82:83]
	v_pk_mul_f32 v[84:85], v[76:77], v[84:85]
	v_pk_add_f32 v[90:91], v[90:91], 1.0 op_sel_hi:[1,0]
	v_exp_f32_e32 v82, v82
	v_exp_f32_e32 v83, v83
	v_exp_f32_e32 v84, v84
	v_exp_f32_e32 v85, v85
	v_rcp_f32_e32 v90, v90
	v_rcp_f32_e32 v91, v91
	v_pk_add_f32 v[92:93], v[92:93], 1.0 op_sel_hi:[1,0]
	v_pk_add_f32 v[82:83], v[82:83], 1.0 op_sel_hi:[1,0]
	v_rcp_f32_e32 v92, v92
	v_rcp_f32_e32 v93, v93
	v_pk_add_f32 v[84:85], v[84:85], 1.0 op_sel_hi:[1,0]
	v_pk_mul_f32 v[78:79], v[78:79], v[90:91]
	v_add_u32_e32 v90, v102, v115
	v_rcp_f32_e32 v82, v82
	v_rcp_f32_e32 v83, v83
	v_rcp_f32_e32 v84, v84
	v_rcp_f32_e32 v85, v85
	v_ashrrev_i32_e32 v91, 31, v90
	v_pk_mul_f32 v[80:81], v[80:81], v[92:93]
	v_lshlrev_b64 v[92:93], 11, v[90:91]
	v_lshlrev_b64 v[90:91], 12, v[90:91]
	v_lshl_add_u64 v[90:91], s[14:15], 0, v[90:91]
	v_lshl_add_u64 v[90:91], v[90:91], 0, s[36:37]
	v_pk_mul_f32 v[82:83], v[74:75], v[82:83]
	v_pk_mul_f32 v[84:85], v[76:77], v[84:85]
	v_cvt_pk_bf16_f32 v74, v82, v83
	v_lshl_add_u64 v[90:91], v[90:91], 0, v[190:191]
	v_cvt_pk_bf16_f32 v75, v84, v85
	v_cvt_pk_bf16_f32 v76, v78, v79
	v_cvt_pk_bf16_f32 v77, v80, v81
	global_store_dwordx4 v[90:91], v[74:77], off
	s_nop 1
	v_pk_mul_f32 v[74:75], v[82:83], s[12:13] op_sel_hi:[1,0]
	v_pk_mul_f32 v[76:77], v[78:79], s[12:13] op_sel_hi:[1,0]
	v_mov_b32_e32 v78, v1
	v_mov_b32_e32 v79, v1
	v_cvt_pk_fp8_f32 v78, v74, v75
	v_cvt_pk_fp8_f32 v79, v76, v77
	v_pk_mul_f32 v[74:75], v[84:85], s[12:13] op_sel_hi:[1,0]
	v_pk_mul_f32 v[76:77], v[80:81], s[12:13] op_sel_hi:[1,0]
	v_cvt_pk_fp8_f32 v78, v74, v75 op_sel:[0,0,1]
	v_cvt_pk_fp8_f32 v79, v76, v77 op_sel:[0,0,1]
	v_lshl_add_u64 v[74:75], s[60:61], 0, v[92:93]
	v_lshl_add_u64 v[74:75], v[74:75], 0, s[2:3]
	v_lshl_add_u64 v[74:75], v[74:75], 0, v[0:1]
	global_store_dwordx2 v[74:75], v[78:79], off
	s_waitcnt vmcnt(24)
	v_lshlrev_b32_e32 v78, 16, v100
	v_and_b32_e32 v79, 0xffff0000, v100
	v_lshlrev_b32_e32 v74, 16, v98
	v_and_b32_e32 v75, 0xffff0000, v98
	v_pk_fma_f32 v[78:79], v[10:11], v[78:79], v[208:209]
	v_pk_fma_f32 v[74:75], v[14:15], v[74:75], v[86:87]
	v_lshlrev_b32_e32 v80, 16, v101
	v_and_b32_e32 v81, 0xffff0000, v101
	v_pk_mul_f32 v[86:87], v[78:79], v[78:79]
	v_lshlrev_b32_e32 v76, 16, v99
	v_and_b32_e32 v77, 0xffff0000, v99
	v_pk_fma_f32 v[80:81], v[12:13], v[80:81], v[210:211]
	v_pk_fma_f32 v[86:87], v[86:87], s[10:11], v[188:189] op_sel_hi:[1,0,0] neg_lo:[1,0,0] neg_hi:[1,0,0]
	v_pk_fma_f32 v[76:77], v[16:17], v[76:77], v[88:89]
	v_pk_mul_f32 v[86:87], v[78:79], v[86:87]
	v_pk_mul_f32 v[88:89], v[80:81], v[80:81]
	v_exp_f32_e32 v86, v86
	v_exp_f32_e32 v87, v87
	v_pk_fma_f32 v[88:89], v[88:89], s[10:11], v[188:189] op_sel_hi:[1,0,0] neg_lo:[1,0,0] neg_hi:[1,0,0]
	v_pk_mul_f32 v[82:83], v[74:75], v[74:75]
	v_pk_mul_f32 v[88:89], v[80:81], v[88:89]
	v_pk_mul_f32 v[84:85], v[76:77], v[76:77]
	v_exp_f32_e32 v88, v88
	v_exp_f32_e32 v89, v89
	v_pk_fma_f32 v[82:83], v[82:83], s[10:11], v[188:189] op_sel_hi:[1,0,0] neg_lo:[1,0,0] neg_hi:[1,0,0]
	v_pk_fma_f32 v[84:85], v[84:85], s[10:11], v[188:189] op_sel_hi:[1,0,0] neg_lo:[1,0,0] neg_hi:[1,0,0]
	v_pk_mul_f32 v[82:83], v[74:75], v[82:83]
	v_pk_mul_f32 v[84:85], v[76:77], v[84:85]
	v_pk_add_f32 v[86:87], v[86:87], 1.0 op_sel_hi:[1,0]
	v_exp_f32_e32 v82, v82
	v_exp_f32_e32 v83, v83
	v_exp_f32_e32 v84, v84
	v_exp_f32_e32 v85, v85
	v_rcp_f32_e32 v86, v86
	v_rcp_f32_e32 v87, v87
	v_pk_add_f32 v[88:89], v[88:89], 1.0 op_sel_hi:[1,0]
	v_pk_add_f32 v[82:83], v[82:83], 1.0 op_sel_hi:[1,0]
	v_rcp_f32_e32 v88, v88
	v_rcp_f32_e32 v89, v89
	v_pk_add_f32 v[84:85], v[84:85], 1.0 op_sel_hi:[1,0]
	v_pk_mul_f32 v[78:79], v[78:79], v[86:87]
	v_add_u32_e32 v86, v192, v102
	v_rcp_f32_e32 v82, v82
	v_rcp_f32_e32 v83, v83
	v_rcp_f32_e32 v84, v84
	v_rcp_f32_e32 v85, v85
	v_ashrrev_i32_e32 v87, 31, v86
	v_pk_mul_f32 v[80:81], v[80:81], v[88:89]
	v_lshlrev_b64 v[88:89], 11, v[86:87]
	v_lshlrev_b64 v[86:87], 12, v[86:87]
	v_lshl_add_u64 v[86:87], s[14:15], 0, v[86:87]
	v_lshl_add_u64 v[86:87], v[86:87], 0, s[36:37]
	v_pk_mul_f32 v[82:83], v[74:75], v[82:83]
	v_pk_mul_f32 v[84:85], v[76:77], v[84:85]
	v_cvt_pk_bf16_f32 v74, v82, v83
	v_lshl_add_u64 v[86:87], v[86:87], 0, v[190:191]
	v_cvt_pk_bf16_f32 v75, v84, v85
	v_cvt_pk_bf16_f32 v76, v78, v79
	v_cvt_pk_bf16_f32 v77, v80, v81
	global_store_dwordx4 v[86:87], v[74:77], off
	s_nop 1
	v_pk_mul_f32 v[74:75], v[82:83], s[12:13] op_sel_hi:[1,0]
	v_pk_mul_f32 v[76:77], v[78:79], s[12:13] op_sel_hi:[1,0]
	v_mov_b32_e32 v78, v1
	v_mov_b32_e32 v79, v1
	v_cvt_pk_fp8_f32 v78, v74, v75
	v_cvt_pk_fp8_f32 v79, v76, v77
	v_pk_mul_f32 v[74:75], v[84:85], s[12:13] op_sel_hi:[1,0]
	v_pk_mul_f32 v[76:77], v[80:81], s[12:13] op_sel_hi:[1,0]
	v_cvt_pk_fp8_f32 v78, v74, v75 op_sel:[0,0,1]
	v_cvt_pk_fp8_f32 v79, v76, v77 op_sel:[0,0,1]
	v_lshl_add_u64 v[74:75], s[60:61], 0, v[88:89]
	v_lshl_add_u64 v[74:75], v[74:75], 0, s[2:3]
	v_lshl_add_u64 v[74:75], v[74:75], 0, v[0:1]
	global_store_dwordx2 v[74:75], v[78:79], off
	s_waitcnt vmcnt(25)
; __device__ __forceinline__ unsigned cvt_pk_bf16(float lo, float hi) { unsigned r; asm volatile("v_cvt_pk_bf16_f32 %0, %1, %2" : "=v"(r) : "v"(lo), "v"(hi)); return r; }
;     __device__ __forceinline__ void operator()(const Acc& acc, const Unit& u, int wr, int wc, int fr, int fq) const {
;     ...
;         for (int idx = 0; idx < 8; ++idx) { const int ai = idx >> 2, m = idx & 3, row = row0 + ai * 128 + m * 16;
; #pragma unroll
;             for (int bj = 0; bj < 2; ++bj) { const int col = bj * 32 + colb, tl = col >> 4;
;                 const u32x4 uu = urow[idx][bj];
;                 const f32x4 a = acc[ai][bj][m][0], b = acc[ai][bj][m][1];
;                 f32x2 y0 = (f32x2){a[0], a[1]} + (f32x2){d0[0], d0[1]} * (f32x2){bf2f(uu.x & 0xffffu), bf2f(uu.x >> 16)}, y1 = (f32x2){a[2], a[3]} + (f32x2){d0[2], d0[3]} * (f32x2){bf2f(uu.y & 0xffffu), bf2f(uu.y >> 16)};
;                 f32x2 y2 = (f32x2){b[0], b[1]} + (f32x2){d1[0], d1[1]} * (f32x2){bf2f(uu.z & 0xffffu), bf2f(uu.z >> 16)}, y3 = (f32x2){b[2], b[3]} + (f32x2){d1[2], d1[3]} * (f32x2){bf2f(uu.w & 0xffffu), bf2f(uu.w >> 16)};
;                 y0 = gelu_tanh2(y0); y1 = gelu_tanh2(y1); y2 = gelu_tanh2(y2); y3 = gelu_tanh2(y3);
;                 u32x4 w; w.x = cvt_pk_bf16(y0.x, y0.y); w.y = cvt_pk_bf16(y1.x, y1.y); w.z = cvt_pk_bf16(y2.x, y2.y); w.w = cvt_pk_bf16(y3.x, y3.y);
;                 *(u32x4*)(yg + (size_t)(row * 16 + tl) * DS + g * 16 + h0) = w;
;                 y0 = y0 * F8_SY; y1 = y1 * F8_SY; y2 = y2 * F8_SY; y3 = y3 * F8_SY;
;                 u32x2 w8; w8.x = pk4_fp8(y0.x, y0.y, y1.x, y1.y); w8.y = pk4_fp8(y2.x, y2.y, y3.x, y3.y);
;                 *(u32x2*)(yg8 + (size_t)(row * 16 + tl) * DS + g * 16 + h0) = w8; }
	v_lshlrev_b32_e32 v74, 16, v198
	v_and_b32_e32 v75, 0xffff0000, v198
	v_pk_fma_f32 v[70:71], v[14:15], v[74:75], v[70:71]
	v_lshlrev_b32_e32 v74, 16, v199
	v_and_b32_e32 v75, 0xffff0000, v199
	v_pk_fma_f32 v[72:73], v[16:17], v[74:75], v[72:73]
	v_lshlrev_b32_e32 v74, 16, v200
	v_and_b32_e32 v75, 0xffff0000, v200
	v_pk_fma_f32 v[66:67], v[10:11], v[74:75], v[66:67]
	v_lshlrev_b32_e32 v74, 16, v201
	v_and_b32_e32 v75, 0xffff0000, v201
	v_pk_fma_f32 v[68:69], v[12:13], v[74:75], v[68:69]
	v_pk_mul_f32 v[74:75], v[70:71], v[70:71]
	v_pk_mul_f32 v[78:79], v[66:67], v[66:67]
	v_pk_fma_f32 v[74:75], v[74:75], s[10:11], v[188:189] op_sel_hi:[1,0,0] neg_lo:[1,0,0] neg_hi:[1,0,0]
	v_pk_fma_f32 v[78:79], v[78:79], s[10:11], v[188:189] op_sel_hi:[1,0,0] neg_lo:[1,0,0] neg_hi:[1,0,0]
	v_pk_mul_f32 v[74:75], v[70:71], v[74:75]
	v_pk_mul_f32 v[76:77], v[72:73], v[72:73]
	v_pk_mul_f32 v[78:79], v[66:67], v[78:79]
	v_pk_mul_f32 v[80:81], v[68:69], v[68:69]
	v_exp_f32_e32 v74, v74
	v_exp_f32_e32 v75, v75
	v_pk_fma_f32 v[76:77], v[76:77], s[10:11], v[188:189] op_sel_hi:[1,0,0] neg_lo:[1,0,0] neg_hi:[1,0,0]
	v_exp_f32_e32 v78, v78
	v_exp_f32_e32 v79, v79
	v_pk_fma_f32 v[80:81], v[80:81], s[10:11], v[188:189] op_sel_hi:[1,0,0] neg_lo:[1,0,0] neg_hi:[1,0,0]
	v_pk_mul_f32 v[76:77], v[72:73], v[76:77]
	v_pk_mul_f32 v[80:81], v[68:69], v[80:81]
	v_exp_f32_e32 v76, v76
	v_exp_f32_e32 v77, v77
	v_exp_f32_e32 v80, v80
	v_exp_f32_e32 v81, v81
	v_pk_add_f32 v[74:75], v[74:75], 1.0 op_sel_hi:[1,0]
	v_pk_add_f32 v[78:79], v[78:79], 1.0 op_sel_hi:[1,0]
	v_rcp_f32_e32 v74, v74
	v_rcp_f32_e32 v75, v75
	v_rcp_f32_e32 v78, v78
	v_rcp_f32_e32 v79, v79
	v_pk_add_f32 v[76:77], v[76:77], 1.0 op_sel_hi:[1,0]
	v_pk_add_f32 v[80:81], v[80:81], 1.0 op_sel_hi:[1,0]
	v_rcp_f32_e32 v76, v76
	v_rcp_f32_e32 v77, v77
	v_rcp_f32_e32 v80, v80
	v_rcp_f32_e32 v81, v81
	v_add_u32_e32 v82, 0x900, v193
	v_pk_mul_f32 v[70:71], v[70:71], v[74:75]
	v_pk_mul_f32 v[74:75], v[66:67], v[78:79]
	v_add_u32_e32 v78, v82, v115
	v_ashrrev_i32_e32 v79, 31, v78
	v_pk_mul_f32 v[72:73], v[72:73], v[76:77]
	v_pk_mul_f32 v[76:77], v[68:69], v[80:81]
	v_lshlrev_b64 v[80:81], 11, v[78:79]
	v_lshlrev_b64 v[78:79], 12, v[78:79]
	v_lshl_add_u64 v[78:79], s[14:15], 0, v[78:79]
	v_lshl_add_u64 v[78:79], v[78:79], 0, s[36:37]
	v_cvt_pk_bf16_f32 v66, v70, v71
	v_cvt_pk_bf16_f32 v67, v72, v73
	v_cvt_pk_bf16_f32 v68, v74, v75
	v_cvt_pk_bf16_f32 v69, v76, v77
	v_lshl_add_u64 v[78:79], v[78:79], 0, v[190:191]
	global_store_dwordx4 v[78:79], v[66:69], off
	s_nop 1
	v_pk_mul_f32 v[66:67], v[70:71], s[12:13] op_sel_hi:[1,0]
	v_pk_mul_f32 v[68:69], v[74:75], s[12:13] op_sel_hi:[1,0]
	v_mov_b32_e32 v70, v1
	v_mov_b32_e32 v71, v1
	v_cvt_pk_fp8_f32 v70, v66, v67
	v_cvt_pk_fp8_f32 v71, v68, v69
	v_pk_mul_f32 v[66:67], v[72:73], s[12:13] op_sel_hi:[1,0]
	v_pk_mul_f32 v[68:69], v[76:77], s[12:13] op_sel_hi:[1,0]
	v_cvt_pk_fp8_f32 v70, v66, v67 op_sel:[0,0,1]
	v_cvt_pk_fp8_f32 v71, v68, v69 op_sel:[0,0,1]
	v_lshl_add_u64 v[66:67], s[60:61], 0, v[80:81]
	v_lshl_add_u64 v[66:67], v[66:67], 0, s[2:3]
	v_lshl_add_u64 v[66:67], v[66:67], 0, v[0:1]
	global_store_dwordx2 v[66:67], v[70:71], off
	s_waitcnt vmcnt(26)
	v_lshlrev_b32_e32 v66, 16, v194
	v_and_b32_e32 v67, 0xffff0000, v194
	v_pk_fma_f32 v[62:63], v[14:15], v[66:67], v[62:63]
	v_lshlrev_b32_e32 v66, 16, v195
	v_and_b32_e32 v67, 0xffff0000, v195
	v_pk_fma_f32 v[64:65], v[16:17], v[66:67], v[64:65]
	v_lshlrev_b32_e32 v66, 16, v196
	v_and_b32_e32 v67, 0xffff0000, v196
	v_pk_fma_f32 v[58:59], v[10:11], v[66:67], v[58:59]
	v_lshlrev_b32_e32 v66, 16, v197
	v_and_b32_e32 v67, 0xffff0000, v197
	v_pk_fma_f32 v[60:61], v[12:13], v[66:67], v[60:61]
	v_pk_mul_f32 v[66:67], v[62:63], v[62:63]
	v_pk_mul_f32 v[70:71], v[58:59], v[58:59]
	v_pk_fma_f32 v[66:67], v[66:67], s[10:11], v[188:189] op_sel_hi:[1,0,0] neg_lo:[1,0,0] neg_hi:[1,0,0]
	v_pk_fma_f32 v[70:71], v[70:71], s[10:11], v[188:189] op_sel_hi:[1,0,0] neg_lo:[1,0,0] neg_hi:[1,0,0]
	v_pk_mul_f32 v[66:67], v[62:63], v[66:67]
	v_pk_mul_f32 v[68:69], v[64:65], v[64:65]
	v_pk_mul_f32 v[70:71], v[58:59], v[70:71]
	v_pk_mul_f32 v[72:73], v[60:61], v[60:61]
	v_exp_f32_e32 v66, v66
	v_exp_f32_e32 v67, v67
	v_pk_fma_f32 v[68:69], v[68:69], s[10:11], v[188:189] op_sel_hi:[1,0,0] neg_lo:[1,0,0] neg_hi:[1,0,0]
	v_exp_f32_e32 v70, v70
	v_exp_f32_e32 v71, v71
	v_pk_fma_f32 v[72:73], v[72:73], s[10:11], v[188:189] op_sel_hi:[1,0,0] neg_lo:[1,0,0] neg_hi:[1,0,0]
	v_pk_mul_f32 v[68:69], v[64:65], v[68:69]
	v_pk_mul_f32 v[72:73], v[60:61], v[72:73]
	v_exp_f32_e32 v68, v68
	v_exp_f32_e32 v69, v69
	v_exp_f32_e32 v72, v72
	v_exp_f32_e32 v73, v73
	v_pk_add_f32 v[66:67], v[66:67], 1.0 op_sel_hi:[1,0]
	v_pk_add_f32 v[70:71], v[70:71], 1.0 op_sel_hi:[1,0]
	v_rcp_f32_e32 v66, v66
	v_rcp_f32_e32 v67, v67
	v_rcp_f32_e32 v70, v70
	v_rcp_f32_e32 v71, v71
	v_pk_add_f32 v[68:69], v[68:69], 1.0 op_sel_hi:[1,0]
	v_pk_add_f32 v[72:73], v[72:73], 1.0 op_sel_hi:[1,0]
	v_rcp_f32_e32 v68, v68
	v_rcp_f32_e32 v69, v69
	v_rcp_f32_e32 v72, v72
	v_rcp_f32_e32 v73, v73
	v_pk_mul_f32 v[62:63], v[62:63], v[66:67]
	v_pk_mul_f32 v[66:67], v[58:59], v[70:71]
	v_add_u32_e32 v70, v192, v82
	v_ashrrev_i32_e32 v71, 31, v70
	v_pk_mul_f32 v[64:65], v[64:65], v[68:69]
	v_pk_mul_f32 v[68:69], v[60:61], v[72:73]
	v_lshlrev_b64 v[72:73], 11, v[70:71]
	v_lshlrev_b64 v[70:71], 12, v[70:71]
	v_lshl_add_u64 v[70:71], s[14:15], 0, v[70:71]
	v_lshl_add_u64 v[70:71], v[70:71], 0, s[36:37]
	v_cvt_pk_bf16_f32 v58, v62, v63
	v_cvt_pk_bf16_f32 v59, v64, v65
	v_cvt_pk_bf16_f32 v60, v66, v67
	v_cvt_pk_bf16_f32 v61, v68, v69
	v_lshl_add_u64 v[70:71], v[70:71], 0, v[190:191]
	global_store_dwordx4 v[70:71], v[58:61], off
	s_nop 1
	v_pk_mul_f32 v[58:59], v[62:63], s[12:13] op_sel_hi:[1,0]
	v_pk_mul_f32 v[60:61], v[66:67], s[12:13] op_sel_hi:[1,0]
	v_mov_b32_e32 v62, v1
	v_mov_b32_e32 v63, v1
	v_cvt_pk_fp8_f32 v62, v58, v59
	v_cvt_pk_fp8_f32 v63, v60, v61
	v_pk_mul_f32 v[58:59], v[64:65], s[12:13] op_sel_hi:[1,0]
	v_pk_mul_f32 v[60:61], v[68:69], s[12:13] op_sel_hi:[1,0]
	v_cvt_pk_fp8_f32 v62, v58, v59 op_sel:[0,0,1]
	v_cvt_pk_fp8_f32 v63, v60, v61 op_sel:[0,0,1]
	v_lshl_add_u64 v[58:59], s[60:61], 0, v[72:73]
	v_lshl_add_u64 v[58:59], v[58:59], 0, s[2:3]
	v_lshl_add_u64 v[58:59], v[58:59], 0, v[0:1]
	global_store_dwordx2 v[58:59], v[62:63], off
	s_waitcnt vmcnt(27)
; __device__ __forceinline__ unsigned cvt_pk_bf16(float lo, float hi) { unsigned r; asm volatile("v_cvt_pk_bf16_f32 %0, %1, %2" : "=v"(r) : "v"(lo), "v"(hi)); return r; }
;     __device__ __forceinline__ void operator()(const Acc& acc, const Unit& u, int wr, int wc, int fr, int fq) const {
;     ...
;         for (int idx = 0; idx < 8; ++idx) { const int ai = idx >> 2, m = idx & 3, row = row0 + ai * 128 + m * 16;
; #pragma unroll
;             for (int bj = 0; bj < 2; ++bj) { const int col = bj * 32 + colb, tl = col >> 4;
;                 const u32x4 uu = urow[idx][bj];
;                 const f32x4 a = acc[ai][bj][m][0], b = acc[ai][bj][m][1];
;                 f32x2 y0 = (f32x2){a[0], a[1]} + (f32x2){d0[0], d0[1]} * (f32x2){bf2f(uu.x & 0xffffu), bf2f(uu.x >> 16)}, y1 = (f32x2){a[2], a[3]} + (f32x2){d0[2], d0[3]} * (f32x2){bf2f(uu.y & 0xffffu), bf2f(uu.y >> 16)};
;                 f32x2 y2 = (f32x2){b[0], b[1]} + (f32x2){d1[0], d1[1]} * (f32x2){bf2f(uu.z & 0xffffu), bf2f(uu.z >> 16)}, y3 = (f32x2){b[2], b[3]} + (f32x2){d1[2], d1[3]} * (f32x2){bf2f(uu.w & 0xffffu), bf2f(uu.w >> 16)};
;                 y0 = gelu_tanh2(y0); y1 = gelu_tanh2(y1); y2 = gelu_tanh2(y2); y3 = gelu_tanh2(y3);
;                 u32x4 w; w.x = cvt_pk_bf16(y0.x, y0.y); w.y = cvt_pk_bf16(y1.x, y1.y); w.z = cvt_pk_bf16(y2.x, y2.y); w.w = cvt_pk_bf16(y3.x, y3.y);
;                 *(u32x4*)(yg + (size_t)(row * 16 + tl) * DS + g * 16 + h0) = w;
;                 y0 = y0 * F8_SY; y1 = y1 * F8_SY; y2 = y2 * F8_SY; y3 = y3 * F8_SY;
;                 u32x2 w8; w8.x = pk4_fp8(y0.x, y0.y, y1.x, y1.y); w8.y = pk4_fp8(y2.x, y2.y, y3.x, y3.y);
;                 *(u32x2*)(yg8 + (size_t)(row * 16 + tl) * DS + g * 16 + h0) = w8; }
	v_lshlrev_b32_e32 v58, 16, v54
	v_and_b32_e32 v59, 0xffff0000, v54
	v_lshlrev_b32_e32 v54, 16, v55
	v_and_b32_e32 v55, 0xffff0000, v55
	v_pk_fma_f32 v[48:49], v[16:17], v[54:55], v[48:49]
	v_lshlrev_b32_e32 v54, 16, v56
	v_and_b32_e32 v55, 0xffff0000, v56
	v_pk_fma_f32 v[46:47], v[14:15], v[58:59], v[46:47]
	v_pk_fma_f32 v[42:43], v[10:11], v[54:55], v[42:43]
	v_lshlrev_b32_e32 v54, 16, v57
	v_and_b32_e32 v55, 0xffff0000, v57
	v_pk_fma_f32 v[44:45], v[12:13], v[54:55], v[44:45]
	v_pk_mul_f32 v[54:55], v[46:47], v[46:47]
	v_pk_mul_f32 v[58:59], v[42:43], v[42:43]
	v_pk_fma_f32 v[54:55], v[54:55], s[10:11], v[188:189] op_sel_hi:[1,0,0] neg_lo:[1,0,0] neg_hi:[1,0,0]
	v_pk_fma_f32 v[58:59], v[58:59], s[10:11], v[188:189] op_sel_hi:[1,0,0] neg_lo:[1,0,0] neg_hi:[1,0,0]
	v_pk_mul_f32 v[54:55], v[46:47], v[54:55]
	v_pk_mul_f32 v[56:57], v[48:49], v[48:49]
	v_pk_mul_f32 v[58:59], v[42:43], v[58:59]
	v_pk_mul_f32 v[60:61], v[44:45], v[44:45]
	v_exp_f32_e32 v54, v54
	v_exp_f32_e32 v55, v55
	v_pk_fma_f32 v[56:57], v[56:57], s[10:11], v[188:189] op_sel_hi:[1,0,0] neg_lo:[1,0,0] neg_hi:[1,0,0]
	v_exp_f32_e32 v58, v58
	v_exp_f32_e32 v59, v59
	v_pk_fma_f32 v[60:61], v[60:61], s[10:11], v[188:189] op_sel_hi:[1,0,0] neg_lo:[1,0,0] neg_hi:[1,0,0]
	v_pk_mul_f32 v[56:57], v[48:49], v[56:57]
	v_pk_mul_f32 v[60:61], v[44:45], v[60:61]
	v_exp_f32_e32 v56, v56
	v_exp_f32_e32 v57, v57
	v_exp_f32_e32 v60, v60
	v_exp_f32_e32 v61, v61
	v_pk_add_f32 v[54:55], v[54:55], 1.0 op_sel_hi:[1,0]
	v_pk_add_f32 v[58:59], v[58:59], 1.0 op_sel_hi:[1,0]
	v_rcp_f32_e32 v54, v54
	v_rcp_f32_e32 v55, v55
	v_rcp_f32_e32 v58, v58
	v_rcp_f32_e32 v59, v59
	v_pk_add_f32 v[56:57], v[56:57], 1.0 op_sel_hi:[1,0]
	v_pk_add_f32 v[60:61], v[60:61], 1.0 op_sel_hi:[1,0]
	v_rcp_f32_e32 v56, v56
	v_rcp_f32_e32 v57, v57
	v_rcp_f32_e32 v60, v60
	v_rcp_f32_e32 v61, v61
	v_add_u32_e32 v62, 0xa00, v193
	v_pk_mul_f32 v[46:47], v[46:47], v[54:55]
	v_pk_mul_f32 v[54:55], v[42:43], v[58:59]
	v_add_u32_e32 v58, v62, v115
	v_ashrrev_i32_e32 v59, 31, v58
	v_pk_mul_f32 v[48:49], v[48:49], v[56:57]
	v_pk_mul_f32 v[56:57], v[44:45], v[60:61]
	v_lshlrev_b64 v[60:61], 11, v[58:59]
	v_lshlrev_b64 v[58:59], 12, v[58:59]
	v_lshl_add_u64 v[58:59], s[14:15], 0, v[58:59]
	v_lshl_add_u64 v[58:59], v[58:59], 0, s[36:37]
	v_cvt_pk_bf16_f32 v42, v46, v47
	v_cvt_pk_bf16_f32 v43, v48, v49
	v_cvt_pk_bf16_f32 v44, v54, v55
	v_cvt_pk_bf16_f32 v45, v56, v57
	v_lshl_add_u64 v[58:59], v[58:59], 0, v[190:191]
	global_store_dwordx4 v[58:59], v[42:45], off
	s_nop 1
	v_pk_mul_f32 v[42:43], v[46:47], s[12:13] op_sel_hi:[1,0]
	v_pk_mul_f32 v[44:45], v[54:55], s[12:13] op_sel_hi:[1,0]
	v_mov_b32_e32 v46, v1
	v_mov_b32_e32 v47, v1
	v_cvt_pk_fp8_f32 v46, v42, v43
	v_cvt_pk_fp8_f32 v47, v44, v45
	v_pk_mul_f32 v[42:43], v[48:49], s[12:13] op_sel_hi:[1,0]
	v_pk_mul_f32 v[44:45], v[56:57], s[12:13] op_sel_hi:[1,0]
	v_cvt_pk_fp8_f32 v46, v42, v43 op_sel:[0,0,1]
	v_cvt_pk_fp8_f32 v47, v44, v45 op_sel:[0,0,1]
	v_lshl_add_u64 v[42:43], s[60:61], 0, v[60:61]
	v_lshl_add_u64 v[42:43], v[42:43], 0, s[2:3]
	v_lshl_add_u64 v[42:43], v[42:43], 0, v[0:1]
	global_store_dwordx2 v[42:43], v[46:47], off
	s_waitcnt vmcnt(28)
	v_lshlrev_b32_e32 v42, 16, v50
	v_and_b32_e32 v43, 0xffff0000, v50
	v_pk_fma_f32 v[38:39], v[14:15], v[42:43], v[38:39]
	v_lshlrev_b32_e32 v42, 16, v51
	v_and_b32_e32 v43, 0xffff0000, v51
	v_pk_fma_f32 v[40:41], v[16:17], v[42:43], v[40:41]
	v_lshlrev_b32_e32 v42, 16, v52
	v_and_b32_e32 v43, 0xffff0000, v52
	v_pk_fma_f32 v[34:35], v[10:11], v[42:43], v[34:35]
	v_lshlrev_b32_e32 v42, 16, v53
	v_and_b32_e32 v43, 0xffff0000, v53
	v_pk_fma_f32 v[36:37], v[12:13], v[42:43], v[36:37]
	v_pk_mul_f32 v[42:43], v[38:39], v[38:39]
	v_pk_mul_f32 v[46:47], v[34:35], v[34:35]
	v_pk_fma_f32 v[42:43], v[42:43], s[10:11], v[188:189] op_sel_hi:[1,0,0] neg_lo:[1,0,0] neg_hi:[1,0,0]
	v_pk_fma_f32 v[46:47], v[46:47], s[10:11], v[188:189] op_sel_hi:[1,0,0] neg_lo:[1,0,0] neg_hi:[1,0,0]
	v_pk_mul_f32 v[42:43], v[38:39], v[42:43]
	v_pk_mul_f32 v[44:45], v[40:41], v[40:41]
	v_pk_mul_f32 v[46:47], v[34:35], v[46:47]
	v_pk_mul_f32 v[48:49], v[36:37], v[36:37]
	v_exp_f32_e32 v42, v42
	v_exp_f32_e32 v43, v43
	v_pk_fma_f32 v[44:45], v[44:45], s[10:11], v[188:189] op_sel_hi:[1,0,0] neg_lo:[1,0,0] neg_hi:[1,0,0]
	v_exp_f32_e32 v46, v46
	v_exp_f32_e32 v47, v47
	v_pk_fma_f32 v[48:49], v[48:49], s[10:11], v[188:189] op_sel_hi:[1,0,0] neg_lo:[1,0,0] neg_hi:[1,0,0]
	v_pk_mul_f32 v[44:45], v[40:41], v[44:45]
	v_pk_mul_f32 v[48:49], v[36:37], v[48:49]
	v_exp_f32_e32 v44, v44
	v_exp_f32_e32 v45, v45
	v_exp_f32_e32 v48, v48
	v_exp_f32_e32 v49, v49
	v_pk_add_f32 v[42:43], v[42:43], 1.0 op_sel_hi:[1,0]
	v_pk_add_f32 v[46:47], v[46:47], 1.0 op_sel_hi:[1,0]
	v_rcp_f32_e32 v42, v42
	v_rcp_f32_e32 v43, v43
	v_rcp_f32_e32 v46, v46
	v_rcp_f32_e32 v47, v47
	v_pk_add_f32 v[44:45], v[44:45], 1.0 op_sel_hi:[1,0]
	v_pk_add_f32 v[48:49], v[48:49], 1.0 op_sel_hi:[1,0]
	v_rcp_f32_e32 v44, v44
	v_rcp_f32_e32 v45, v45
	v_rcp_f32_e32 v48, v48
	v_rcp_f32_e32 v49, v49
	v_pk_mul_f32 v[38:39], v[38:39], v[42:43]
	v_pk_mul_f32 v[42:43], v[34:35], v[46:47]
	v_add_u32_e32 v46, v192, v62
	v_ashrrev_i32_e32 v47, 31, v46
	v_pk_mul_f32 v[40:41], v[40:41], v[44:45]
	v_pk_mul_f32 v[44:45], v[36:37], v[48:49]
	v_lshlrev_b64 v[48:49], 11, v[46:47]
	v_lshlrev_b64 v[46:47], 12, v[46:47]
	v_lshl_add_u64 v[46:47], s[14:15], 0, v[46:47]
	v_lshl_add_u64 v[46:47], v[46:47], 0, s[36:37]
	v_cvt_pk_bf16_f32 v34, v38, v39
	v_cvt_pk_bf16_f32 v35, v40, v41
	v_cvt_pk_bf16_f32 v36, v42, v43
	v_cvt_pk_bf16_f32 v37, v44, v45
	v_lshl_add_u64 v[46:47], v[46:47], 0, v[190:191]
	global_store_dwordx4 v[46:47], v[34:37], off
	s_nop 1
	v_pk_mul_f32 v[34:35], v[38:39], s[12:13] op_sel_hi:[1,0]
	v_pk_mul_f32 v[36:37], v[42:43], s[12:13] op_sel_hi:[1,0]
	v_mov_b32_e32 v38, v1
	v_mov_b32_e32 v39, v1
	v_cvt_pk_fp8_f32 v38, v34, v35
	v_cvt_pk_fp8_f32 v39, v36, v37
	v_pk_mul_f32 v[34:35], v[40:41], s[12:13] op_sel_hi:[1,0]
	v_pk_mul_f32 v[36:37], v[44:45], s[12:13] op_sel_hi:[1,0]
	v_cvt_pk_fp8_f32 v38, v34, v35 op_sel:[0,0,1]
	v_cvt_pk_fp8_f32 v39, v36, v37 op_sel:[0,0,1]
	v_lshl_add_u64 v[34:35], s[60:61], 0, v[48:49]
	v_lshl_add_u64 v[34:35], v[34:35], 0, s[2:3]
	v_lshl_add_u64 v[34:35], v[34:35], 0, v[0:1]
	global_store_dwordx2 v[34:35], v[38:39], off
	s_waitcnt vmcnt(29)
; __device__ __forceinline__ unsigned cvt_pk_bf16(float lo, float hi) { unsigned r; asm volatile("v_cvt_pk_bf16_f32 %0, %1, %2" : "=v"(r) : "v"(lo), "v"(hi)); return r; }
;     __device__ __forceinline__ void operator()(const Acc& acc, const Unit& u, int wr, int wc, int fr, int fq) const {
;     ...
;         for (int idx = 0; idx < 8; ++idx) { const int ai = idx >> 2, m = idx & 3, row = row0 + ai * 128 + m * 16;
; #pragma unroll
;             for (int bj = 0; bj < 2; ++bj) { const int col = bj * 32 + colb, tl = col >> 4;
;                 const u32x4 uu = urow[idx][bj];
;                 const f32x4 a = acc[ai][bj][m][0], b = acc[ai][bj][m][1];
;                 f32x2 y0 = (f32x2){a[0], a[1]} + (f32x2){d0[0], d0[1]} * (f32x2){bf2f(uu.x & 0xffffu), bf2f(uu.x >> 16)}, y1 = (f32x2){a[2], a[3]} + (f32x2){d0[2], d0[3]} * (f32x2){bf2f(uu.y & 0xffffu), bf2f(uu.y >> 16)};
;                 f32x2 y2 = (f32x2){b[0], b[1]} + (f32x2){d1[0], d1[1]} * (f32x2){bf2f(uu.z & 0xffffu), bf2f(uu.z >> 16)}, y3 = (f32x2){b[2], b[3]} + (f32x2){d1[2], d1[3]} * (f32x2){bf2f(uu.w & 0xffffu), bf2f(uu.w >> 16)};
;                 y0 = gelu_tanh2(y0); y1 = gelu_tanh2(y1); y2 = gelu_tanh2(y2); y3 = gelu_tanh2(y3);
;                 u32x4 w; w.x = cvt_pk_bf16(y0.x, y0.y); w.y = cvt_pk_bf16(y1.x, y1.y); w.z = cvt_pk_bf16(y2.x, y2.y); w.w = cvt_pk_bf16(y3.x, y3.y);
;                 *(u32x4*)(yg + (size_t)(row * 16 + tl) * DS + g * 16 + h0) = w;
;                 y0 = y0 * F8_SY; y1 = y1 * F8_SY; y2 = y2 * F8_SY; y3 = y3 * F8_SY;
;                 u32x2 w8; w8.x = pk4_fp8(y0.x, y0.y, y1.x, y1.y); w8.y = pk4_fp8(y2.x, y2.y, y3.x, y3.y);
;                 *(u32x2*)(yg8 + (size_t)(row * 16 + tl) * DS + g * 16 + h0) = w8; }
	v_lshlrev_b32_e32 v34, 16, v30
	v_and_b32_e32 v35, 0xffff0000, v30
	v_lshlrev_b32_e32 v30, 16, v31
	v_and_b32_e32 v31, 0xffff0000, v31
	v_pk_fma_f32 v[24:25], v[16:17], v[30:31], v[24:25]
	v_lshlrev_b32_e32 v30, 16, v32
	v_and_b32_e32 v31, 0xffff0000, v32
	v_pk_fma_f32 v[22:23], v[14:15], v[34:35], v[22:23]
	v_pk_fma_f32 v[18:19], v[10:11], v[30:31], v[18:19]
	v_lshlrev_b32_e32 v30, 16, v33
	v_and_b32_e32 v31, 0xffff0000, v33
	v_pk_fma_f32 v[20:21], v[12:13], v[30:31], v[20:21]
	v_pk_mul_f32 v[30:31], v[22:23], v[22:23]
	v_pk_mul_f32 v[34:35], v[18:19], v[18:19]
	v_pk_fma_f32 v[30:31], v[30:31], s[10:11], v[188:189] op_sel_hi:[1,0,0] neg_lo:[1,0,0] neg_hi:[1,0,0]
	v_pk_fma_f32 v[34:35], v[34:35], s[10:11], v[188:189] op_sel_hi:[1,0,0] neg_lo:[1,0,0] neg_hi:[1,0,0]
	v_pk_mul_f32 v[30:31], v[22:23], v[30:31]
	v_pk_mul_f32 v[32:33], v[24:25], v[24:25]
	v_pk_mul_f32 v[34:35], v[18:19], v[34:35]
	v_pk_mul_f32 v[36:37], v[20:21], v[20:21]
	v_exp_f32_e32 v30, v30
	v_exp_f32_e32 v31, v31
	v_pk_fma_f32 v[32:33], v[32:33], s[10:11], v[188:189] op_sel_hi:[1,0,0] neg_lo:[1,0,0] neg_hi:[1,0,0]
	v_exp_f32_e32 v34, v34
	v_exp_f32_e32 v35, v35
	v_pk_fma_f32 v[36:37], v[36:37], s[10:11], v[188:189] op_sel_hi:[1,0,0] neg_lo:[1,0,0] neg_hi:[1,0,0]
	v_pk_mul_f32 v[32:33], v[24:25], v[32:33]
	v_pk_mul_f32 v[36:37], v[20:21], v[36:37]
	v_exp_f32_e32 v32, v32
	v_exp_f32_e32 v33, v33
	v_exp_f32_e32 v36, v36
	v_exp_f32_e32 v37, v37
	v_pk_add_f32 v[30:31], v[30:31], 1.0 op_sel_hi:[1,0]
	v_pk_add_f32 v[34:35], v[34:35], 1.0 op_sel_hi:[1,0]
	v_rcp_f32_e32 v30, v30
	v_rcp_f32_e32 v31, v31
	v_rcp_f32_e32 v34, v34
	v_rcp_f32_e32 v35, v35
	v_pk_add_f32 v[32:33], v[32:33], 1.0 op_sel_hi:[1,0]
	v_pk_add_f32 v[36:37], v[36:37], 1.0 op_sel_hi:[1,0]
	v_rcp_f32_e32 v32, v32
	v_rcp_f32_e32 v33, v33
	v_rcp_f32_e32 v36, v36
	v_rcp_f32_e32 v37, v37
	v_add_u32_e32 v38, 0xb00, v193
	v_pk_mul_f32 v[22:23], v[22:23], v[30:31]
	v_pk_mul_f32 v[30:31], v[18:19], v[34:35]
	v_add_u32_e32 v34, v38, v115
	v_ashrrev_i32_e32 v35, 31, v34
	v_pk_mul_f32 v[24:25], v[24:25], v[32:33]
	v_pk_mul_f32 v[32:33], v[20:21], v[36:37]
	v_lshlrev_b64 v[36:37], 11, v[34:35]
	v_lshlrev_b64 v[34:35], 12, v[34:35]
	v_lshl_add_u64 v[34:35], s[14:15], 0, v[34:35]
	v_lshl_add_u64 v[34:35], v[34:35], 0, s[36:37]
	v_cvt_pk_bf16_f32 v18, v22, v23
	v_cvt_pk_bf16_f32 v19, v24, v25
	v_cvt_pk_bf16_f32 v20, v30, v31
	v_cvt_pk_bf16_f32 v21, v32, v33
	v_lshl_add_u64 v[34:35], v[34:35], 0, v[190:191]
	global_store_dwordx4 v[34:35], v[18:21], off
	s_nop 1
	v_pk_mul_f32 v[18:19], v[22:23], s[12:13] op_sel_hi:[1,0]
	v_pk_mul_f32 v[20:21], v[30:31], s[12:13] op_sel_hi:[1,0]
	v_mov_b32_e32 v22, v1
	v_mov_b32_e32 v23, v1
	v_cvt_pk_fp8_f32 v22, v18, v19
	v_cvt_pk_fp8_f32 v23, v20, v21
	v_pk_mul_f32 v[18:19], v[24:25], s[12:13] op_sel_hi:[1,0]
	v_pk_mul_f32 v[20:21], v[32:33], s[12:13] op_sel_hi:[1,0]
	v_cvt_pk_fp8_f32 v22, v18, v19 op_sel:[0,0,1]
	v_cvt_pk_fp8_f32 v23, v20, v21 op_sel:[0,0,1]
	v_lshl_add_u64 v[18:19], s[60:61], 0, v[36:37]
	v_lshl_add_u64 v[18:19], v[18:19], 0, s[2:3]
	v_lshl_add_u64 v[18:19], v[18:19], 0, v[0:1]
	global_store_dwordx2 v[18:19], v[22:23], off
	s_waitcnt vmcnt(30)
	v_lshlrev_b32_e32 v18, 16, v26
	v_and_b32_e32 v19, 0xffff0000, v26
	v_pk_fma_f32 v[6:7], v[14:15], v[18:19], v[6:7]
	v_lshlrev_b32_e32 v14, 16, v27
	v_and_b32_e32 v15, 0xffff0000, v27
	v_pk_fma_f32 v[8:9], v[16:17], v[14:15], v[8:9]
	v_lshlrev_b32_e32 v14, 16, v28
	v_and_b32_e32 v15, 0xffff0000, v28
	v_pk_fma_f32 v[2:3], v[10:11], v[14:15], v[2:3]
	v_lshlrev_b32_e32 v10, 16, v29
	v_and_b32_e32 v11, 0xffff0000, v29
	v_pk_fma_f32 v[4:5], v[12:13], v[10:11], v[4:5]
	v_pk_mul_f32 v[10:11], v[6:7], v[6:7]
	v_pk_mul_f32 v[14:15], v[2:3], v[2:3]
	v_pk_fma_f32 v[10:11], v[10:11], s[10:11], v[188:189] op_sel_hi:[1,0,0] neg_lo:[1,0,0] neg_hi:[1,0,0]
	v_pk_fma_f32 v[14:15], v[14:15], s[10:11], v[188:189] op_sel_hi:[1,0,0] neg_lo:[1,0,0] neg_hi:[1,0,0]
	v_pk_mul_f32 v[10:11], v[6:7], v[10:11]
	v_pk_mul_f32 v[12:13], v[8:9], v[8:9]
	v_pk_mul_f32 v[14:15], v[2:3], v[14:15]
	v_pk_mul_f32 v[16:17], v[4:5], v[4:5]
	v_exp_f32_e32 v10, v10
	v_exp_f32_e32 v11, v11
	v_pk_fma_f32 v[12:13], v[12:13], s[10:11], v[188:189] op_sel_hi:[1,0,0] neg_lo:[1,0,0] neg_hi:[1,0,0]
	v_exp_f32_e32 v14, v14
	v_exp_f32_e32 v15, v15
	v_pk_fma_f32 v[16:17], v[16:17], s[10:11], v[188:189] op_sel_hi:[1,0,0] neg_lo:[1,0,0] neg_hi:[1,0,0]
	v_pk_mul_f32 v[12:13], v[8:9], v[12:13]
	v_pk_mul_f32 v[16:17], v[4:5], v[16:17]
	v_exp_f32_e32 v12, v12
	v_exp_f32_e32 v13, v13
	v_exp_f32_e32 v16, v16
	v_exp_f32_e32 v17, v17
	v_pk_add_f32 v[10:11], v[10:11], 1.0 op_sel_hi:[1,0]
	v_pk_add_f32 v[14:15], v[14:15], 1.0 op_sel_hi:[1,0]
	v_rcp_f32_e32 v10, v10
	v_rcp_f32_e32 v11, v11
	v_rcp_f32_e32 v14, v14
	v_rcp_f32_e32 v15, v15
	v_pk_add_f32 v[12:13], v[12:13], 1.0 op_sel_hi:[1,0]
	v_pk_add_f32 v[16:17], v[16:17], 1.0 op_sel_hi:[1,0]
	v_rcp_f32_e32 v12, v12
	v_rcp_f32_e32 v13, v13
	v_rcp_f32_e32 v16, v16
	v_rcp_f32_e32 v17, v17
	v_pk_mul_f32 v[6:7], v[6:7], v[10:11]
	v_pk_mul_f32 v[10:11], v[2:3], v[14:15]
	v_add_u32_e32 v14, v192, v38
	v_ashrrev_i32_e32 v15, 31, v14
	v_pk_mul_f32 v[8:9], v[8:9], v[12:13]
	v_pk_mul_f32 v[12:13], v[4:5], v[16:17]
	v_lshlrev_b64 v[16:17], 11, v[14:15]
	v_lshlrev_b64 v[14:15], 12, v[14:15]
	v_lshl_add_u64 v[14:15], s[14:15], 0, v[14:15]
	v_lshl_add_u64 v[14:15], v[14:15], 0, s[36:37]
	v_cvt_pk_bf16_f32 v2, v6, v7
	v_cvt_pk_bf16_f32 v3, v8, v9
	v_cvt_pk_bf16_f32 v4, v10, v11
	v_cvt_pk_bf16_f32 v5, v12, v13
	v_lshl_add_u64 v[14:15], v[14:15], 0, v[190:191]
	global_store_dwordx4 v[14:15], v[2:5], off
	s_nop 1
	v_pk_mul_f32 v[2:3], v[6:7], s[12:13] op_sel_hi:[1,0]
	v_pk_mul_f32 v[4:5], v[10:11], s[12:13] op_sel_hi:[1,0]
	v_mov_b32_e32 v6, v1
	v_mov_b32_e32 v7, v1
	v_cvt_pk_fp8_f32 v6, v2, v3
	v_cvt_pk_fp8_f32 v7, v4, v5
	v_pk_mul_f32 v[2:3], v[8:9], s[12:13] op_sel_hi:[1,0]
	v_pk_mul_f32 v[4:5], v[12:13], s[12:13] op_sel_hi:[1,0]
	v_cvt_pk_fp8_f32 v6, v2, v3 op_sel:[0,0,1]
	v_cvt_pk_fp8_f32 v7, v4, v5 op_sel:[0,0,1]
	v_lshl_add_u64 v[2:3], s[60:61], 0, v[16:17]
	v_lshl_add_u64 v[2:3], v[2:3], 0, s[2:3]
	v_lshl_add_u64 v[2:3], v[2:3], 0, v[0:1]
	global_store_dwordx2 v[2:3], v[6:7], off
	s_waitcnt vmcnt(0)
	s_cbranch_scc1 .LBB0_500
	s_barrier
	s_branch .LBB0_500
